# GEMM mainloops: LDS-DMA loads use SGPR base + 32-bit VGPR offset (saddr) form; 94 per-piece 64-bit VALU adds removed
# speedup vs baseline: 1.0643x; 1.0013x over previous
; #define PG8_STAGE(bufoff, gbase, voff) do { _Pragma("unroll") for (int _i = 0; _i < 2; ++_i) \
;         __builtin_amdgcn_global_load_lds((const unsigned*)((const char*)(gbase) + (voff)[_i]), (LAS unsigned*)(lds + (bufoff) + ldsw + _i * 8192), 16, 0, 0); } while (0)
; #define PG8_LDA(dst, b, h) do { _Pragma("unroll") for (int m = 0; m < 4; ++m) _Pragma("unroll") for (int k = 0; k < 2; ++k) dst[m][k] = *(const LAS bf16x8*)(lds + PG8_SA(b, h) + aoff + m * 2048 + k * 1024); } while (0)
; #define PG8_LDB(dst, b, h) do { _Pragma("unroll") for (int n = 0; n < 2; ++n) _Pragma("unroll") for (int k = 0; k < 2; ++k) dst[n][k] = *(const LAS bf16x8*)(lds + PG8_SB(b, h) + boff + n * 2048 + k * 1024); } while (0)
; #define PG8_MMA(ai, bj, At, Bt) do { __builtin_amdgcn_s_setprio(1); _Pragma("unroll") for (int m = 0; m < 4; ++m) _Pragma("unroll") for (int n = 0; n < 2; ++n) _Pragma("unroll") for (int k = 0; k < 2; ++k) \
;         acc[ai][bj][m][n] = __builtin_amdgcn_mfma_f32_16x16x32_bf16(Bt[n][k], At[m][k], acc[ai][bj][m][n], 0, 0, 0); __builtin_amdgcn_s_setprio(0); } while (0)
; #define PG8_WAIT_V(n) asm volatile("s_waitcnt vmcnt(" #n ")" ::: "memory")
; #define PG8_WAIT_L(n) asm volatile("s_waitcnt lgkmcnt(" #n ")" ::: "memory")
; #define PG8_BAR __builtin_amdgcn_s_barrier()
; #define PG8_SCHED __builtin_amdgcn_sched_barrier(0)
; template <class Epi>
; __device__ __forceinline__ void gemm_phase(LAS unsigned char* lds, const Gemm g, const StaticOrder& S, const Epi& E) {
;     ...
;             PG8_LDB(B0, 0, 0); PG8_LDB(B1, 0, 1); PG8_SCHED; PG8_LDA(At, 0, 0); PG8_STAGE(PG8_SA(1, 1), a1 + hstepA, voffA);
;             PG8_WAIT_V(8); PG8_WAIT_L(0); PG8_BAR; PG8_MMA(0, 0, At, B0); PG8_MMA(0, 1, At, B1); PG8_BAR; PG8_SCHED;
;             PG8_LDA(At, 0, 1); PG8_STAGE(PG8_SB(0, 0), b2, voffB); PG8_STAGE(PG8_SB(0, 1), b2 + hstepB, voffB); PG8_STAGE(PG8_SA(0, 0), a2, voffA);
;             PG8_WAIT_V(8); PG8_WAIT_L(0); PG8_BAR; PG8_MMA(1, 0, At, B0); PG8_MMA(1, 1, At, B1); PG8_BAR; PG8_SCHED;
.LBB0_414:
	s_add_u32 s14, s26, 0xfff80080
	s_addc_u32 s15, s27, -1
	s_add_i32 s33, 0, 0x10000
	s_cmp_eq_u32 s21, 28
	s_cselect_b32 s29, s0, s15
	s_cselect_b32 s28, s1, s14
	s_cselect_b32 s15, s3, s19
	s_cselect_b32 s14, s7, s9
	s_add_i32 s52, 0, 0x14000
	v_add_u32_e32 v150, s33, v1
	v_add_u32_e32 v159, s52, v1
	ds_read_b128 v[138:141], v150
	ds_read_b128 v[142:145], v150 offset:1024
	ds_read_b128 v[146:149], v150 offset:2048
	ds_read_b128 v[150:153], v150 offset:3072
	ds_read_b128 v[154:157], v159
	ds_read_b128 v[160:163], v159 offset:1024
	ds_read_b128 v[164:167], v159 offset:2048
	ds_read_b128 v[168:171], v159 offset:3072
	s_nop 0
	s_add_i32 m0, s35, 0xc000
	ds_read_b128 v[172:175], v158
	ds_read_b128 v[176:179], v158 offset:1024
	ds_read_b128 v[188:191], v158 offset:2048
	ds_read_b128 v[192:195], v158 offset:3072
	ds_read_b128 v[196:199], v158 offset:4096
	ds_read_b128 v[200:203], v158 offset:5120
	ds_read_b128 v[204:207], v158 offset:6144
	ds_read_b128 v[208:211], v158 offset:7168
	global_load_lds_dwordx4 v134, s[26:27]
	s_nop 0
	s_add_i32 m0, s35, 0xe000
	s_nop 0
	global_load_lds_dwordx4 v136, s[26:27]
	s_waitcnt vmcnt(8)
	s_waitcnt lgkmcnt(0)
	s_barrier
	s_setprio 1
	s_waitcnt lgkmcnt(0)
	v_mfma_f32_16x16x32_bf16 v[126:129], v[138:141], v[172:175], v[126:129]
	v_mfma_f32_16x16x32_bf16 v[122:125], v[146:149], v[172:175], v[122:125]
	v_mfma_f32_16x16x32_bf16 v[110:113], v[138:141], v[188:191], v[110:113]
	v_mfma_f32_16x16x32_bf16 v[106:109], v[146:149], v[188:191], v[106:109]
	v_mfma_f32_16x16x32_bf16 v[94:97], v[138:141], v[196:199], v[94:97]
	v_mfma_f32_16x16x32_bf16 v[90:93], v[146:149], v[196:199], v[90:93]
	v_mfma_f32_16x16x32_bf16 v[78:81], v[138:141], v[204:207], v[78:81]
	v_mfma_f32_16x16x32_bf16 v[74:77], v[146:149], v[204:207], v[74:77]
	v_mfma_f32_16x16x32_bf16 v[126:129], v[142:145], v[176:179], v[126:129]
	v_mfma_f32_16x16x32_bf16 v[122:125], v[150:153], v[176:179], v[122:125]
	v_mfma_f32_16x16x32_bf16 v[110:113], v[142:145], v[192:195], v[110:113]
	v_mfma_f32_16x16x32_bf16 v[106:109], v[150:153], v[192:195], v[106:109]
	v_mfma_f32_16x16x32_bf16 v[94:97], v[142:145], v[200:203], v[94:97]
	v_mfma_f32_16x16x32_bf16 v[90:93], v[150:153], v[200:203], v[90:93]
	v_mfma_f32_16x16x32_bf16 v[78:81], v[142:145], v[208:211], v[78:81]
	v_mfma_f32_16x16x32_bf16 v[74:77], v[150:153], v[208:211], v[74:77]
	s_setprio 0
	s_setprio 1
	v_mfma_f32_16x16x32_bf16 v[118:121], v[154:157], v[172:175], v[118:121]
	v_mfma_f32_16x16x32_bf16 v[114:117], v[164:167], v[172:175], v[114:117]
	v_mfma_f32_16x16x32_bf16 v[102:105], v[154:157], v[188:191], v[102:105]
	v_mfma_f32_16x16x32_bf16 v[98:101], v[164:167], v[188:191], v[98:101]
	v_mfma_f32_16x16x32_bf16 v[86:89], v[154:157], v[196:199], v[86:89]
	v_mfma_f32_16x16x32_bf16 v[82:85], v[164:167], v[196:199], v[82:85]
	v_mfma_f32_16x16x32_bf16 v[70:73], v[154:157], v[204:207], v[70:73]
	v_mfma_f32_16x16x32_bf16 v[66:69], v[164:167], v[204:207], v[66:69]
	v_mfma_f32_16x16x32_bf16 v[118:121], v[160:163], v[176:179], v[118:121]
	v_mfma_f32_16x16x32_bf16 v[114:117], v[168:171], v[176:179], v[114:117]
	v_mfma_f32_16x16x32_bf16 v[102:105], v[160:163], v[192:195], v[102:105]
	v_mfma_f32_16x16x32_bf16 v[98:101], v[168:171], v[192:195], v[98:101]
	v_mfma_f32_16x16x32_bf16 v[86:89], v[160:163], v[200:203], v[86:89]
	v_mfma_f32_16x16x32_bf16 v[82:85], v[168:171], v[200:203], v[82:85]
	v_mfma_f32_16x16x32_bf16 v[70:73], v[160:163], v[208:211], v[70:73]
	v_mfma_f32_16x16x32_bf16 v[66:69], v[168:171], v[208:211], v[66:69]
	s_setprio 0
	s_barrier
	s_add_i32 s33, s33, s34
	v_lshl_add_u64 v[184:185], s[14:15], 0, v[130:131]
	s_mov_b32 m0, s33
	ds_read_b128 v[172:175], v158 offset:16384
	ds_read_b128 v[176:179], v158 offset:17408
	ds_read_b128 v[188:191], v158 offset:18432
	ds_read_b128 v[192:195], v158 offset:19456
	ds_read_b128 v[196:199], v158 offset:20480
	ds_read_b128 v[200:203], v158 offset:21504
	ds_read_b128 v[204:207], v158 offset:22528
	ds_read_b128 v[208:211], v158 offset:23552
	global_load_lds_dwordx4 v130, s[14:15]
	s_add_i32 m0, s33, 0x2000
	s_add_u32 s40, s14, 0x80000
	v_lshl_add_u64 v[212:213], s[14:15], 0, v[132:133]
	s_addc_u32 s41, s15, 0
	s_add_i32 s33, s52, s34
	global_load_lds_dwordx4 v132, s[14:15]
	s_nop 0
	s_mov_b32 m0, s33
	v_lshl_add_u64 v[216:217], s[28:29], 0, v[132:133]
	global_load_lds_dwordx4 v130, s[40:41]
	s_nop 0
	s_add_i32 m0, s33, 0x2000
	s_nop 0
	global_load_lds_dwordx4 v132, s[40:41]
	v_lshl_add_u64 v[214:215], s[28:29], 0, v[130:131]
	s_mov_b32 m0, s35
	s_nop 0
	global_load_lds_dwordx4 v130, s[28:29]
	s_mov_b32 m0, s42
	s_nop 0
	global_load_lds_dwordx4 v132, s[28:29]
	s_waitcnt vmcnt(8)
	s_waitcnt lgkmcnt(0)
	s_barrier
; #define PG8_STAGE(bufoff, gbase, voff) do { _Pragma("unroll") for (int _i = 0; _i < 2; ++_i) \
;         __builtin_amdgcn_global_load_lds((const unsigned*)((const char*)(gbase) + (voff)[_i]), (LAS unsigned*)(lds + (bufoff) + ldsw + _i * 8192), 16, 0, 0); } while (0)
; #define PG8_LDA(dst, b, h) do { _Pragma("unroll") for (int m = 0; m < 4; ++m) _Pragma("unroll") for (int k = 0; k < 2; ++k) dst[m][k] = *(const LAS bf16x8*)(lds + PG8_SA(b, h) + aoff + m * 2048 + k * 1024); } while (0)
; #define PG8_LDB(dst, b, h) do { _Pragma("unroll") for (int n = 0; n < 2; ++n) _Pragma("unroll") for (int k = 0; k < 2; ++k) dst[n][k] = *(const LAS bf16x8*)(lds + PG8_SB(b, h) + boff + n * 2048 + k * 1024); } while (0)
; #define PG8_MMA(ai, bj, At, Bt) do { __builtin_amdgcn_s_setprio(1); _Pragma("unroll") for (int m = 0; m < 4; ++m) _Pragma("unroll") for (int n = 0; n < 2; ++n) _Pragma("unroll") for (int k = 0; k < 2; ++k) \
;         acc[ai][bj][m][n] = __builtin_amdgcn_mfma_f32_16x16x32_bf16(Bt[n][k], At[m][k], acc[ai][bj][m][n], 0, 0, 0); __builtin_amdgcn_s_setprio(0); } while (0)
; #define PG8_WAIT_V(n) asm volatile("s_waitcnt vmcnt(" #n ")" ::: "memory")
; #define PG8_WAIT_L(n) asm volatile("s_waitcnt lgkmcnt(" #n ")" ::: "memory")
; #define PG8_BAR __builtin_amdgcn_s_barrier()
; #define PG8_SCHED __builtin_amdgcn_sched_barrier(0)
; template <class Epi>
; __device__ __forceinline__ void gemm_phase(LAS unsigned char* lds, const Gemm g, const StaticOrder& S, const Epi& E) {
;     ...
;             PG8_WAIT_V(8); PG8_WAIT_L(0); PG8_BAR; PG8_MMA(1, 0, At, B0); PG8_MMA(1, 1, At, B1); PG8_BAR; PG8_SCHED;
;             PG8_LDB(B0, 1, 0); PG8_LDB(B1, 1, 1); PG8_SCHED; PG8_LDA(At, 1, 0); PG8_STAGE(PG8_SA(0, 1), a2 + hstepA, voffA);
;             PG8_WAIT_V(8); PG8_WAIT_L(0); PG8_BAR; PG8_MMA(0, 0, At, B0); PG8_MMA(0, 1, At, B1); PG8_BAR; PG8_SCHED;
	s_setprio 1
	s_waitcnt lgkmcnt(0)
	v_mfma_f32_16x16x32_bf16 v[62:65], v[138:141], v[172:175], v[62:65]
	v_mfma_f32_16x16x32_bf16 v[58:61], v[146:149], v[172:175], v[58:61]
	v_mfma_f32_16x16x32_bf16 v[46:49], v[138:141], v[188:191], v[46:49]
	v_mfma_f32_16x16x32_bf16 v[42:45], v[146:149], v[188:191], v[42:45]
	v_mfma_f32_16x16x32_bf16 v[30:33], v[138:141], v[196:199], v[30:33]
	v_mfma_f32_16x16x32_bf16 v[26:29], v[146:149], v[196:199], v[26:29]
	v_mfma_f32_16x16x32_bf16 v[14:17], v[138:141], v[204:207], v[14:17]
	v_mfma_f32_16x16x32_bf16 v[10:13], v[146:149], v[204:207], v[10:13]
	v_mfma_f32_16x16x32_bf16 v[62:65], v[142:145], v[176:179], v[62:65]
	v_mfma_f32_16x16x32_bf16 v[58:61], v[150:153], v[176:179], v[58:61]
	v_mfma_f32_16x16x32_bf16 v[46:49], v[142:145], v[192:195], v[46:49]
	v_mfma_f32_16x16x32_bf16 v[42:45], v[150:153], v[192:195], v[42:45]
	v_mfma_f32_16x16x32_bf16 v[30:33], v[142:145], v[200:203], v[30:33]
	v_mfma_f32_16x16x32_bf16 v[26:29], v[150:153], v[200:203], v[26:29]
	v_mfma_f32_16x16x32_bf16 v[14:17], v[142:145], v[208:211], v[14:17]
	v_mfma_f32_16x16x32_bf16 v[10:13], v[150:153], v[208:211], v[10:13]
	s_setprio 0
	s_setprio 1
	v_mfma_f32_16x16x32_bf16 v[54:57], v[154:157], v[172:175], v[54:57]
	v_mfma_f32_16x16x32_bf16 v[50:53], v[164:167], v[172:175], v[50:53]
	v_mfma_f32_16x16x32_bf16 v[38:41], v[154:157], v[188:191], v[38:41]
	v_mfma_f32_16x16x32_bf16 v[34:37], v[164:167], v[188:191], v[34:37]
	v_mfma_f32_16x16x32_bf16 v[22:25], v[154:157], v[196:199], v[22:25]
	v_mfma_f32_16x16x32_bf16 v[18:21], v[164:167], v[196:199], v[18:21]
	v_mfma_f32_16x16x32_bf16 v[6:9], v[154:157], v[204:207], v[6:9]
	v_mfma_f32_16x16x32_bf16 v[2:5], v[164:167], v[204:207], v[2:5]
	v_mfma_f32_16x16x32_bf16 v[54:57], v[160:163], v[176:179], v[54:57]
	v_mfma_f32_16x16x32_bf16 v[50:53], v[168:171], v[176:179], v[50:53]
	v_mfma_f32_16x16x32_bf16 v[38:41], v[160:163], v[192:195], v[38:41]
	v_mfma_f32_16x16x32_bf16 v[34:37], v[168:171], v[192:195], v[34:37]
	v_mfma_f32_16x16x32_bf16 v[22:25], v[160:163], v[200:203], v[22:25]
	v_mfma_f32_16x16x32_bf16 v[18:21], v[168:171], v[200:203], v[18:21]
	v_mfma_f32_16x16x32_bf16 v[6:9], v[160:163], v[208:211], v[6:9]
	v_mfma_f32_16x16x32_bf16 v[2:5], v[168:171], v[208:211], v[2:5]
	s_setprio 0
	s_barrier
	s_add_i32 s33, 0, 0x18000
	s_add_i32 s40, 0, 0x1c000
	v_add_u32_e32 v150, s33, v1
	v_add_u32_e32 v159, s40, v1
	ds_read_b128 v[138:141], v150
	ds_read_b128 v[142:145], v150 offset:1024
	ds_read_b128 v[146:149], v150 offset:2048
	ds_read_b128 v[150:153], v150 offset:3072
	ds_read_b128 v[154:157], v159
	ds_read_b128 v[160:163], v159 offset:1024
	ds_read_b128 v[164:167], v159 offset:2048
	ds_read_b128 v[168:171], v159 offset:3072
	s_add_u32 s28, s28, 0x80000
	s_addc_u32 s29, s29, 0
	s_mov_b32 m0, s45
	s_nop 0
	ds_read_b128 v[172:175], v158 offset:32768
	ds_read_b128 v[176:179], v158 offset:33792
	ds_read_b128 v[188:191], v158 offset:34816
	ds_read_b128 v[192:195], v158 offset:35840
	ds_read_b128 v[196:199], v158 offset:36864
	ds_read_b128 v[200:203], v158 offset:37888
	ds_read_b128 v[204:207], v158 offset:38912
	ds_read_b128 v[208:211], v158 offset:39936
	global_load_lds_dwordx4 v130, s[28:29]
	s_nop 0
	s_mov_b32 m0, s68
	s_nop 0
	global_load_lds_dwordx4 v132, s[28:29]
	s_waitcnt vmcnt(8)
	s_waitcnt lgkmcnt(0)
	s_barrier
	s_setprio 1
	s_waitcnt lgkmcnt(0)
	v_mfma_f32_16x16x32_bf16 v[126:129], v[138:141], v[172:175], v[126:129]
	v_mfma_f32_16x16x32_bf16 v[122:125], v[146:149], v[172:175], v[122:125]
	v_mfma_f32_16x16x32_bf16 v[110:113], v[138:141], v[188:191], v[110:113]
	v_mfma_f32_16x16x32_bf16 v[106:109], v[146:149], v[188:191], v[106:109]
	v_mfma_f32_16x16x32_bf16 v[94:97], v[138:141], v[196:199], v[94:97]
	v_mfma_f32_16x16x32_bf16 v[90:93], v[146:149], v[196:199], v[90:93]
	v_mfma_f32_16x16x32_bf16 v[78:81], v[138:141], v[204:207], v[78:81]
	v_mfma_f32_16x16x32_bf16 v[74:77], v[146:149], v[204:207], v[74:77]
	v_mfma_f32_16x16x32_bf16 v[126:129], v[142:145], v[176:179], v[126:129]
	v_mfma_f32_16x16x32_bf16 v[122:125], v[150:153], v[176:179], v[122:125]
	v_mfma_f32_16x16x32_bf16 v[110:113], v[142:145], v[192:195], v[110:113]
	v_mfma_f32_16x16x32_bf16 v[106:109], v[150:153], v[192:195], v[106:109]
	v_mfma_f32_16x16x32_bf16 v[94:97], v[142:145], v[200:203], v[94:97]
	v_mfma_f32_16x16x32_bf16 v[90:93], v[150:153], v[200:203], v[90:93]
	v_mfma_f32_16x16x32_bf16 v[78:81], v[142:145], v[208:211], v[78:81]
	v_mfma_f32_16x16x32_bf16 v[74:77], v[150:153], v[208:211], v[74:77]
	s_setprio 0
	s_setprio 1
	v_mfma_f32_16x16x32_bf16 v[118:121], v[154:157], v[172:175], v[118:121]
	v_mfma_f32_16x16x32_bf16 v[114:117], v[164:167], v[172:175], v[114:117]
	v_mfma_f32_16x16x32_bf16 v[102:105], v[154:157], v[188:191], v[102:105]
	v_mfma_f32_16x16x32_bf16 v[98:101], v[164:167], v[188:191], v[98:101]
	v_mfma_f32_16x16x32_bf16 v[86:89], v[154:157], v[196:199], v[86:89]
	v_mfma_f32_16x16x32_bf16 v[82:85], v[164:167], v[196:199], v[82:85]
	v_mfma_f32_16x16x32_bf16 v[70:73], v[154:157], v[204:207], v[70:73]
	v_mfma_f32_16x16x32_bf16 v[66:69], v[164:167], v[204:207], v[66:69]
	v_mfma_f32_16x16x32_bf16 v[118:121], v[160:163], v[176:179], v[118:121]
	v_mfma_f32_16x16x32_bf16 v[114:117], v[168:171], v[176:179], v[114:117]
	v_mfma_f32_16x16x32_bf16 v[102:105], v[160:163], v[192:195], v[102:105]
	v_mfma_f32_16x16x32_bf16 v[98:101], v[168:171], v[192:195], v[98:101]
	v_mfma_f32_16x16x32_bf16 v[86:89], v[160:163], v[200:203], v[86:89]
	v_mfma_f32_16x16x32_bf16 v[82:85], v[168:171], v[200:203], v[82:85]
	v_mfma_f32_16x16x32_bf16 v[70:73], v[160:163], v[208:211], v[70:73]
	v_mfma_f32_16x16x32_bf16 v[66:69], v[168:171], v[208:211], v[66:69]
	s_setprio 0
	s_barrier
; #define PG8_STAGE(bufoff, gbase, voff) do { _Pragma("unroll") for (int _i = 0; _i < 2; ++_i) \
;         __builtin_amdgcn_global_load_lds((const unsigned*)((const char*)(gbase) + (voff)[_i]), (LAS unsigned*)(lds + (bufoff) + ldsw + _i * 8192), 16, 0, 0); } while (0)
; #define PG8_LDA(dst, b, h) do { _Pragma("unroll") for (int m = 0; m < 4; ++m) _Pragma("unroll") for (int k = 0; k < 2; ++k) dst[m][k] = *(const LAS bf16x8*)(lds + PG8_SA(b, h) + aoff + m * 2048 + k * 1024); } while (0)
; #define PG8_MMA(ai, bj, At, Bt) do { __builtin_amdgcn_s_setprio(1); _Pragma("unroll") for (int m = 0; m < 4; ++m) _Pragma("unroll") for (int n = 0; n < 2; ++n) _Pragma("unroll") for (int k = 0; k < 2; ++k) \
;         acc[ai][bj][m][n] = __builtin_amdgcn_mfma_f32_16x16x32_bf16(Bt[n][k], At[m][k], acc[ai][bj][m][n], 0, 0, 0); __builtin_amdgcn_s_setprio(0); } while (0)
; #define PG8_WAIT_V(n) asm volatile("s_waitcnt vmcnt(" #n ")" ::: "memory")
; #define PG8_WAIT_L(n) asm volatile("s_waitcnt lgkmcnt(" #n ")" ::: "memory")
; #define PG8_BAR __builtin_amdgcn_s_barrier()
; #define PG8_SCHED __builtin_amdgcn_sched_barrier(0)
; template <class Epi>
; __device__ __forceinline__ void gemm_phase(LAS unsigned char* lds, const Gemm g, const StaticOrder& S, const Epi& E) {
;     ...
;             PG8_LDA(At, 1, 1); PG8_STAGE(PG8_SB(1, 0), b3, voffB); PG8_STAGE(PG8_SB(1, 1), b3 + hstepB, voffB); PG8_STAGE(PG8_SA(1, 0), a3, voffA);
;             PG8_WAIT_V(8); PG8_WAIT_L(0); PG8_BAR; PG8_MMA(1, 0, At, B0); PG8_MMA(1, 1, At, B1); PG8_BAR; PG8_SCHED;
;         }
	s_add_i32 s28, s33, s34
	v_lshl_add_u64 v[184:185], v[184:185], 0, s[84:85]
	s_mov_b32 m0, s28
	ds_read_b128 v[172:175], v158 offset:49152
	ds_read_b128 v[176:179], v158 offset:50176
	ds_read_b128 v[188:191], v158 offset:51200
	ds_read_b128 v[192:195], v158 offset:52224
	ds_read_b128 v[196:199], v158 offset:53248
	ds_read_b128 v[200:203], v158 offset:54272
	ds_read_b128 v[204:207], v158 offset:55296
	ds_read_b128 v[208:211], v158 offset:56320
	global_load_lds_dwordx4 v[184:185], off
	s_add_i32 m0, s28, 0x2000
	s_add_u32 s14, s14, 0x80080
	v_lshl_add_u64 v[184:185], v[212:213], 0, s[84:85]
	s_addc_u32 s15, s15, 0
	s_add_i32 s28, s40, s34
	global_load_lds_dwordx4 v[184:185], off
	s_nop 0
	s_mov_b32 m0, s28
	s_nop 0
	global_load_lds_dwordx4 v130, s[14:15]
	s_nop 0
	s_add_i32 m0, s28, 0x2000
	s_nop 0
	global_load_lds_dwordx4 v132, s[14:15]
	v_lshl_add_u64 v[184:185], v[214:215], 0, s[84:85]
	s_mov_b32 m0, s87
	s_nop 0
	global_load_lds_dwordx4 v[184:185], off
	v_lshl_add_u64 v[184:185], v[216:217], 0, s[84:85]
	s_mov_b32 m0, s91
	s_nop 0
	global_load_lds_dwordx4 v[184:185], off
	s_waitcnt vmcnt(8)
	s_waitcnt lgkmcnt(0)
	s_barrier
	s_setprio 1
	s_waitcnt lgkmcnt(0)
	v_mfma_f32_16x16x32_bf16 v[62:65], v[138:141], v[172:175], v[62:65]
	v_mfma_f32_16x16x32_bf16 v[58:61], v[146:149], v[172:175], v[58:61]
	v_mfma_f32_16x16x32_bf16 v[46:49], v[138:141], v[188:191], v[46:49]
	v_mfma_f32_16x16x32_bf16 v[42:45], v[146:149], v[188:191], v[42:45]
	v_mfma_f32_16x16x32_bf16 v[30:33], v[138:141], v[196:199], v[30:33]
	v_mfma_f32_16x16x32_bf16 v[26:29], v[146:149], v[196:199], v[26:29]
	v_mfma_f32_16x16x32_bf16 v[14:17], v[138:141], v[204:207], v[14:17]
	v_mfma_f32_16x16x32_bf16 v[10:13], v[146:149], v[204:207], v[10:13]
	v_mfma_f32_16x16x32_bf16 v[62:65], v[142:145], v[176:179], v[62:65]
	v_mfma_f32_16x16x32_bf16 v[58:61], v[150:153], v[176:179], v[58:61]
	v_mfma_f32_16x16x32_bf16 v[46:49], v[142:145], v[192:195], v[46:49]
	v_mfma_f32_16x16x32_bf16 v[42:45], v[150:153], v[192:195], v[42:45]
	v_mfma_f32_16x16x32_bf16 v[30:33], v[142:145], v[200:203], v[30:33]
	v_mfma_f32_16x16x32_bf16 v[26:29], v[150:153], v[200:203], v[26:29]
	v_mfma_f32_16x16x32_bf16 v[14:17], v[142:145], v[208:211], v[14:17]
	v_mfma_f32_16x16x32_bf16 v[10:13], v[150:153], v[208:211], v[10:13]
	s_setprio 0
	s_setprio 1
	v_mfma_f32_16x16x32_bf16 v[54:57], v[154:157], v[172:175], v[54:57]
	v_mfma_f32_16x16x32_bf16 v[50:53], v[164:167], v[172:175], v[50:53]
	v_mfma_f32_16x16x32_bf16 v[38:41], v[154:157], v[188:191], v[38:41]
	v_mfma_f32_16x16x32_bf16 v[34:37], v[164:167], v[188:191], v[34:37]
	v_mfma_f32_16x16x32_bf16 v[22:25], v[154:157], v[196:199], v[22:25]
	v_mfma_f32_16x16x32_bf16 v[18:21], v[164:167], v[196:199], v[18:21]
	v_mfma_f32_16x16x32_bf16 v[6:9], v[154:157], v[204:207], v[6:9]
	v_mfma_f32_16x16x32_bf16 v[2:5], v[164:167], v[204:207], v[2:5]
	v_mfma_f32_16x16x32_bf16 v[54:57], v[160:163], v[176:179], v[54:57]
	v_mfma_f32_16x16x32_bf16 v[50:53], v[168:171], v[176:179], v[50:53]
	v_mfma_f32_16x16x32_bf16 v[38:41], v[160:163], v[192:195], v[38:41]
	v_mfma_f32_16x16x32_bf16 v[34:37], v[168:171], v[192:195], v[34:37]
	v_mfma_f32_16x16x32_bf16 v[22:25], v[160:163], v[200:203], v[22:25]
	v_mfma_f32_16x16x32_bf16 v[18:21], v[168:171], v[200:203], v[18:21]
	v_mfma_f32_16x16x32_bf16 v[6:9], v[160:163], v[208:211], v[6:9]
	v_mfma_f32_16x16x32_bf16 v[2:5], v[168:171], v[208:211], v[2:5]
	s_setprio 0
	s_barrier
	s_add_i32 s21, s21, 2
	s_add_u32 s26, s26, 0x100
	s_addc_u32 s27, s27, 0
	s_add_u32 s9, s9, 0x100
	s_addc_u32 s19, s19, 0
	s_cmp_gt_u32 s21, 29
	s_cbranch_scc0 .LBB0_414
	s_and_b64 vcc, exec, s[16:17]
	s_cbranch_vccz .LBB0_417
	s_barrier

; #define PG8_STAGE(bufoff, gbase, voff) do { _Pragma("unroll") for (int _i = 0; _i < 2; ++_i) \
;         __builtin_amdgcn_global_load_lds((const unsigned*)((const char*)(gbase) + (voff)[_i]), (LAS unsigned*)(lds + (bufoff) + ldsw + _i * 8192), 16, 0, 0); } while (0)
; #define PG8_LDA(dst, b, h) do { _Pragma("unroll") for (int m = 0; m < 4; ++m) _Pragma("unroll") for (int k = 0; k < 2; ++k) dst[m][k] = *(const LAS bf16x8*)(lds + PG8_SA(b, h) + aoff + m * 2048 + k * 1024); } while (0)
; #define PG8_LDB(dst, b, h) do { _Pragma("unroll") for (int n = 0; n < 2; ++n) _Pragma("unroll") for (int k = 0; k < 2; ++k) dst[n][k] = *(const LAS bf16x8*)(lds + PG8_SB(b, h) + boff + n * 2048 + k * 1024); } while (0)
; #define PG8_MMA(ai, bj, At, Bt) do { __builtin_amdgcn_s_setprio(1); _Pragma("unroll") for (int m = 0; m < 4; ++m) _Pragma("unroll") for (int n = 0; n < 2; ++n) _Pragma("unroll") for (int k = 0; k < 2; ++k) \
;         acc[ai][bj][m][n] = __builtin_amdgcn_mfma_f32_16x16x32_bf16(Bt[n][k], At[m][k], acc[ai][bj][m][n], 0, 0, 0); __builtin_amdgcn_s_setprio(0); } while (0)
; #define PG8_WAIT_V(n) asm volatile("s_waitcnt vmcnt(" #n ")" ::: "memory")
; #define PG8_WAIT_L(n) asm volatile("s_waitcnt lgkmcnt(" #n ")" ::: "memory")
; #define PG8_BAR __builtin_amdgcn_s_barrier()
; #define PG8_SCHED __builtin_amdgcn_sched_barrier(0)
; template <class Epi>
; __device__ __forceinline__ void gemm_phase(LAS unsigned char* lds, const Gemm g, const StaticOrder& S, const Epi& E) {
;     ...
;             PG8_LDB(B0, 0, 0); PG8_LDB(B1, 0, 1); PG8_SCHED; PG8_LDA(At, 0, 0); PG8_STAGE(PG8_SA(1, 1), a1 + hstepA, voffA);
;             PG8_WAIT_V(8); PG8_WAIT_L(0); PG8_BAR; PG8_MMA(0, 0, At, B0); PG8_MMA(0, 1, At, B1); PG8_BAR; PG8_SCHED;
;             PG8_LDA(At, 0, 1); PG8_STAGE(PG8_SB(0, 0), b2, voffB); PG8_STAGE(PG8_SB(0, 1), b2 + hstepB, voffB); PG8_STAGE(PG8_SA(0, 0), a2, voffA);
;             PG8_WAIT_V(8); PG8_WAIT_L(0); PG8_BAR; PG8_MMA(1, 0, At, B0); PG8_MMA(1, 1, At, B1); PG8_BAR; PG8_SCHED;
.LBB0_1010:
	s_add_u32 s14, s26, 0xfff80080
	s_addc_u32 s15, s27, -1
	s_add_i32 s41, 0, 0x10000
	s_cmp_eq_u32 s52, 28
	s_cselect_b32 s29, s1, s15
	s_cselect_b32 s28, s3, s14
	s_cselect_b32 s15, s7, s40
	s_cselect_b32 s14, s17, s19
	s_add_i32 s53, 0, 0x14000
	v_add_u32_e32 v142, s41, v1
	v_add_u32_e32 v158, s53, v1
	ds_read_b128 v[130:133], v142
	ds_read_b128 v[134:137], v142 offset:1024
	ds_read_b128 v[138:141], v142 offset:2048
	ds_read_b128 v[142:145], v142 offset:3072
	ds_read_b128 v[146:149], v158
	ds_read_b128 v[150:153], v158 offset:1024
	ds_read_b128 v[154:157], v158 offset:2048
	ds_read_b128 v[158:161], v158 offset:3072
	s_nop 0
	s_add_i32 m0, s25, 0xc000
	ds_read_b128 v[162:165], v181
	ds_read_b128 v[166:169], v181 offset:1024
	ds_read_b128 v[170:173], v181 offset:2048
	ds_read_b128 v[174:177], v181 offset:3072
	ds_read_b128 v[200:203], v181 offset:4096
	ds_read_b128 v[204:207], v181 offset:5120
	ds_read_b128 v[208:211], v181 offset:6144
	ds_read_b128 v[212:215], v181 offset:7168
	global_load_lds_dwordx4 v196, s[26:27]
	s_nop 0
	s_add_i32 m0, s25, 0xe000
	s_nop 0
	global_load_lds_dwordx4 v198, s[26:27]
	s_waitcnt vmcnt(8)
	s_waitcnt lgkmcnt(0)
	s_barrier
	s_setprio 1
	s_waitcnt lgkmcnt(0)
	v_mfma_f32_16x16x32_bf16 v[126:129], v[130:133], v[162:165], v[126:129]
	v_mfma_f32_16x16x32_bf16 v[122:125], v[138:141], v[162:165], v[122:125]
	v_mfma_f32_16x16x32_bf16 v[110:113], v[130:133], v[170:173], v[110:113]
	v_mfma_f32_16x16x32_bf16 v[106:109], v[138:141], v[170:173], v[106:109]
	v_mfma_f32_16x16x32_bf16 v[94:97], v[130:133], v[200:203], v[94:97]
	v_mfma_f32_16x16x32_bf16 v[90:93], v[138:141], v[200:203], v[90:93]
	v_mfma_f32_16x16x32_bf16 v[82:85], v[130:133], v[208:211], v[82:85]
	v_mfma_f32_16x16x32_bf16 v[74:77], v[138:141], v[208:211], v[74:77]
	v_mfma_f32_16x16x32_bf16 v[126:129], v[134:137], v[166:169], v[126:129]
	v_mfma_f32_16x16x32_bf16 v[122:125], v[142:145], v[166:169], v[122:125]
	v_mfma_f32_16x16x32_bf16 v[110:113], v[134:137], v[174:177], v[110:113]
	v_mfma_f32_16x16x32_bf16 v[106:109], v[142:145], v[174:177], v[106:109]
	v_mfma_f32_16x16x32_bf16 v[94:97], v[134:137], v[204:207], v[94:97]
	v_mfma_f32_16x16x32_bf16 v[90:93], v[142:145], v[204:207], v[90:93]
	v_mfma_f32_16x16x32_bf16 v[82:85], v[134:137], v[212:215], v[82:85]
	v_mfma_f32_16x16x32_bf16 v[74:77], v[142:145], v[212:215], v[74:77]
	s_setprio 0
	s_setprio 1
	v_mfma_f32_16x16x32_bf16 v[118:121], v[146:149], v[162:165], v[118:121]
	v_mfma_f32_16x16x32_bf16 v[114:117], v[154:157], v[162:165], v[114:117]
	v_mfma_f32_16x16x32_bf16 v[102:105], v[146:149], v[170:173], v[102:105]
	v_mfma_f32_16x16x32_bf16 v[98:101], v[154:157], v[170:173], v[98:101]
	v_mfma_f32_16x16x32_bf16 v[86:89], v[146:149], v[200:203], v[86:89]
	v_mfma_f32_16x16x32_bf16 v[78:81], v[154:157], v[200:203], v[78:81]
	v_mfma_f32_16x16x32_bf16 v[70:73], v[146:149], v[208:211], v[70:73]
	v_mfma_f32_16x16x32_bf16 v[66:69], v[154:157], v[208:211], v[66:69]
	v_mfma_f32_16x16x32_bf16 v[118:121], v[150:153], v[166:169], v[118:121]
	v_mfma_f32_16x16x32_bf16 v[114:117], v[158:161], v[166:169], v[114:117]
	v_mfma_f32_16x16x32_bf16 v[102:105], v[150:153], v[174:177], v[102:105]
	v_mfma_f32_16x16x32_bf16 v[98:101], v[158:161], v[174:177], v[98:101]
	v_mfma_f32_16x16x32_bf16 v[86:89], v[150:153], v[204:207], v[86:89]
	v_mfma_f32_16x16x32_bf16 v[78:81], v[158:161], v[204:207], v[78:81]
	v_mfma_f32_16x16x32_bf16 v[70:73], v[150:153], v[212:215], v[70:73]
	v_mfma_f32_16x16x32_bf16 v[66:69], v[158:161], v[212:215], v[66:69]
	s_setprio 0
	s_barrier
	s_add_i32 s41, s41, s30
	v_lshl_add_u64 v[178:179], s[14:15], 0, v[190:191]
	s_mov_b32 m0, s41
	ds_read_b128 v[162:165], v181 offset:16384
	ds_read_b128 v[166:169], v181 offset:17408
	ds_read_b128 v[170:173], v181 offset:18432
	ds_read_b128 v[174:177], v181 offset:19456
	ds_read_b128 v[200:203], v181 offset:20480
	ds_read_b128 v[204:207], v181 offset:21504
	ds_read_b128 v[208:211], v181 offset:22528
	ds_read_b128 v[212:215], v181 offset:23552
	global_load_lds_dwordx4 v190, s[14:15]
	s_add_i32 m0, s41, 0x2000
	s_add_u32 s62, s14, 0x80000
	v_lshl_add_u64 v[184:185], s[14:15], 0, v[194:195]
	s_addc_u32 s63, s15, 0
	s_add_i32 s41, s53, s30
	global_load_lds_dwordx4 v194, s[14:15]
	s_nop 0
	s_mov_b32 m0, s41
	v_lshl_add_u64 v[218:219], s[28:29], 0, v[192:193]
	global_load_lds_dwordx4 v190, s[62:63]
	s_nop 0
	s_add_i32 m0, s41, 0x2000
	s_nop 0
	global_load_lds_dwordx4 v194, s[62:63]
	v_lshl_add_u64 v[216:217], s[28:29], 0, v[188:189]
	s_mov_b32 m0, s25
	s_nop 0
	global_load_lds_dwordx4 v188, s[28:29]
	s_mov_b32 m0, s31
	s_nop 0
	global_load_lds_dwordx4 v192, s[28:29]
	s_waitcnt vmcnt(8)
	s_waitcnt lgkmcnt(0)
	s_barrier
; #define PG8_STAGE(bufoff, gbase, voff) do { _Pragma("unroll") for (int _i = 0; _i < 2; ++_i) \
;         __builtin_amdgcn_global_load_lds((const unsigned*)((const char*)(gbase) + (voff)[_i]), (LAS unsigned*)(lds + (bufoff) + ldsw + _i * 8192), 16, 0, 0); } while (0)
; #define PG8_LDA(dst, b, h) do { _Pragma("unroll") for (int m = 0; m < 4; ++m) _Pragma("unroll") for (int k = 0; k < 2; ++k) dst[m][k] = *(const LAS bf16x8*)(lds + PG8_SA(b, h) + aoff + m * 2048 + k * 1024); } while (0)
; #define PG8_LDB(dst, b, h) do { _Pragma("unroll") for (int n = 0; n < 2; ++n) _Pragma("unroll") for (int k = 0; k < 2; ++k) dst[n][k] = *(const LAS bf16x8*)(lds + PG8_SB(b, h) + boff + n * 2048 + k * 1024); } while (0)
; #define PG8_MMA(ai, bj, At, Bt) do { __builtin_amdgcn_s_setprio(1); _Pragma("unroll") for (int m = 0; m < 4; ++m) _Pragma("unroll") for (int n = 0; n < 2; ++n) _Pragma("unroll") for (int k = 0; k < 2; ++k) \
;         acc[ai][bj][m][n] = __builtin_amdgcn_mfma_f32_16x16x32_bf16(Bt[n][k], At[m][k], acc[ai][bj][m][n], 0, 0, 0); __builtin_amdgcn_s_setprio(0); } while (0)
; #define PG8_WAIT_V(n) asm volatile("s_waitcnt vmcnt(" #n ")" ::: "memory")
; #define PG8_WAIT_L(n) asm volatile("s_waitcnt lgkmcnt(" #n ")" ::: "memory")
; #define PG8_BAR __builtin_amdgcn_s_barrier()
; #define PG8_SCHED __builtin_amdgcn_sched_barrier(0)
; template <class Epi>
; __device__ __forceinline__ void gemm_phase(LAS unsigned char* lds, const Gemm g, const StaticOrder& S, const Epi& E) {
;     ...
;             PG8_WAIT_V(8); PG8_WAIT_L(0); PG8_BAR; PG8_MMA(1, 0, At, B0); PG8_MMA(1, 1, At, B1); PG8_BAR; PG8_SCHED;
;             PG8_LDB(B0, 1, 0); PG8_LDB(B1, 1, 1); PG8_SCHED; PG8_LDA(At, 1, 0); PG8_STAGE(PG8_SA(0, 1), a2 + hstepA, voffA);
;             PG8_WAIT_V(8); PG8_WAIT_L(0); PG8_BAR; PG8_MMA(0, 0, At, B0); PG8_MMA(0, 1, At, B1); PG8_BAR; PG8_SCHED;
	s_setprio 1
	s_waitcnt lgkmcnt(0)
	v_mfma_f32_16x16x32_bf16 v[62:65], v[130:133], v[162:165], v[62:65]
	v_mfma_f32_16x16x32_bf16 v[58:61], v[138:141], v[162:165], v[58:61]
	v_mfma_f32_16x16x32_bf16 v[50:53], v[130:133], v[170:173], v[50:53]
	v_mfma_f32_16x16x32_bf16 v[42:45], v[138:141], v[170:173], v[42:45]
	v_mfma_f32_16x16x32_bf16 v[30:33], v[130:133], v[200:203], v[30:33]
	v_mfma_f32_16x16x32_bf16 v[26:29], v[138:141], v[200:203], v[26:29]
	v_mfma_f32_16x16x32_bf16 v[18:21], v[130:133], v[208:211], v[18:21]
	v_mfma_f32_16x16x32_bf16 v[10:13], v[138:141], v[208:211], v[10:13]
	v_mfma_f32_16x16x32_bf16 v[62:65], v[134:137], v[166:169], v[62:65]
	v_mfma_f32_16x16x32_bf16 v[58:61], v[142:145], v[166:169], v[58:61]
	v_mfma_f32_16x16x32_bf16 v[50:53], v[134:137], v[174:177], v[50:53]
	v_mfma_f32_16x16x32_bf16 v[42:45], v[142:145], v[174:177], v[42:45]
	v_mfma_f32_16x16x32_bf16 v[30:33], v[134:137], v[204:207], v[30:33]
	v_mfma_f32_16x16x32_bf16 v[26:29], v[142:145], v[204:207], v[26:29]
	v_mfma_f32_16x16x32_bf16 v[18:21], v[134:137], v[212:215], v[18:21]
	v_mfma_f32_16x16x32_bf16 v[10:13], v[142:145], v[212:215], v[10:13]
	s_setprio 0
	s_setprio 1
	v_mfma_f32_16x16x32_bf16 v[54:57], v[146:149], v[162:165], v[54:57]
	v_mfma_f32_16x16x32_bf16 v[46:49], v[154:157], v[162:165], v[46:49]
	v_mfma_f32_16x16x32_bf16 v[38:41], v[146:149], v[170:173], v[38:41]
	v_mfma_f32_16x16x32_bf16 v[34:37], v[154:157], v[170:173], v[34:37]
	v_mfma_f32_16x16x32_bf16 v[22:25], v[146:149], v[200:203], v[22:25]
	v_mfma_f32_16x16x32_bf16 v[14:17], v[154:157], v[200:203], v[14:17]
	v_mfma_f32_16x16x32_bf16 v[6:9], v[146:149], v[208:211], v[6:9]
	v_mfma_f32_16x16x32_bf16 v[2:5], v[154:157], v[208:211], v[2:5]
	v_mfma_f32_16x16x32_bf16 v[54:57], v[150:153], v[166:169], v[54:57]
	v_mfma_f32_16x16x32_bf16 v[46:49], v[158:161], v[166:169], v[46:49]
	v_mfma_f32_16x16x32_bf16 v[38:41], v[150:153], v[174:177], v[38:41]
	v_mfma_f32_16x16x32_bf16 v[34:37], v[158:161], v[174:177], v[34:37]
	v_mfma_f32_16x16x32_bf16 v[22:25], v[150:153], v[204:207], v[22:25]
	v_mfma_f32_16x16x32_bf16 v[14:17], v[158:161], v[204:207], v[14:17]
	v_mfma_f32_16x16x32_bf16 v[6:9], v[150:153], v[212:215], v[6:9]
	v_mfma_f32_16x16x32_bf16 v[2:5], v[158:161], v[212:215], v[2:5]
	s_setprio 0
	s_barrier
	s_add_i32 s41, 0, 0x18000
	s_add_i32 s53, 0, 0x1c000
	v_add_u32_e32 v142, s41, v1
	v_add_u32_e32 v158, s53, v1
	ds_read_b128 v[130:133], v142
	ds_read_b128 v[134:137], v142 offset:1024
	ds_read_b128 v[138:141], v142 offset:2048
	ds_read_b128 v[142:145], v142 offset:3072
	ds_read_b128 v[146:149], v158
	ds_read_b128 v[150:153], v158 offset:1024
	ds_read_b128 v[154:157], v158 offset:2048
	ds_read_b128 v[158:161], v158 offset:3072
	s_add_u32 s28, s28, 0x80000
	s_addc_u32 s29, s29, 0
	s_mov_b32 m0, s33
	s_nop 0
	ds_read_b128 v[162:165], v181 offset:32768
	ds_read_b128 v[166:169], v181 offset:33792
	ds_read_b128 v[170:173], v181 offset:34816
	ds_read_b128 v[174:177], v181 offset:35840
	ds_read_b128 v[200:203], v181 offset:36864
	ds_read_b128 v[204:207], v181 offset:37888
	ds_read_b128 v[208:211], v181 offset:38912
	ds_read_b128 v[212:215], v181 offset:39936
	global_load_lds_dwordx4 v188, s[28:29]
	s_nop 0
	s_mov_b32 m0, s34
	s_nop 0
	global_load_lds_dwordx4 v192, s[28:29]
	s_waitcnt vmcnt(8)
	s_waitcnt lgkmcnt(0)
	s_barrier
	s_setprio 1
	s_waitcnt lgkmcnt(0)
	v_mfma_f32_16x16x32_bf16 v[126:129], v[130:133], v[162:165], v[126:129]
	v_mfma_f32_16x16x32_bf16 v[122:125], v[138:141], v[162:165], v[122:125]
	v_mfma_f32_16x16x32_bf16 v[110:113], v[130:133], v[170:173], v[110:113]
	v_mfma_f32_16x16x32_bf16 v[106:109], v[138:141], v[170:173], v[106:109]
	v_mfma_f32_16x16x32_bf16 v[94:97], v[130:133], v[200:203], v[94:97]
	v_mfma_f32_16x16x32_bf16 v[90:93], v[138:141], v[200:203], v[90:93]
	v_mfma_f32_16x16x32_bf16 v[82:85], v[130:133], v[208:211], v[82:85]
	v_mfma_f32_16x16x32_bf16 v[74:77], v[138:141], v[208:211], v[74:77]
	v_mfma_f32_16x16x32_bf16 v[126:129], v[134:137], v[166:169], v[126:129]
	v_mfma_f32_16x16x32_bf16 v[122:125], v[142:145], v[166:169], v[122:125]
	v_mfma_f32_16x16x32_bf16 v[110:113], v[134:137], v[174:177], v[110:113]
	v_mfma_f32_16x16x32_bf16 v[106:109], v[142:145], v[174:177], v[106:109]
	v_mfma_f32_16x16x32_bf16 v[94:97], v[134:137], v[204:207], v[94:97]
	v_mfma_f32_16x16x32_bf16 v[90:93], v[142:145], v[204:207], v[90:93]
	v_mfma_f32_16x16x32_bf16 v[82:85], v[134:137], v[212:215], v[82:85]
	v_mfma_f32_16x16x32_bf16 v[74:77], v[142:145], v[212:215], v[74:77]
	s_setprio 0
	s_setprio 1
	v_mfma_f32_16x16x32_bf16 v[118:121], v[146:149], v[162:165], v[118:121]
	v_mfma_f32_16x16x32_bf16 v[114:117], v[154:157], v[162:165], v[114:117]
	v_mfma_f32_16x16x32_bf16 v[102:105], v[146:149], v[170:173], v[102:105]
	v_mfma_f32_16x16x32_bf16 v[98:101], v[154:157], v[170:173], v[98:101]
	v_mfma_f32_16x16x32_bf16 v[86:89], v[146:149], v[200:203], v[86:89]
	v_mfma_f32_16x16x32_bf16 v[78:81], v[154:157], v[200:203], v[78:81]
	v_mfma_f32_16x16x32_bf16 v[70:73], v[146:149], v[208:211], v[70:73]
	v_mfma_f32_16x16x32_bf16 v[66:69], v[154:157], v[208:211], v[66:69]
	v_mfma_f32_16x16x32_bf16 v[118:121], v[150:153], v[166:169], v[118:121]
	v_mfma_f32_16x16x32_bf16 v[114:117], v[158:161], v[166:169], v[114:117]
	v_mfma_f32_16x16x32_bf16 v[102:105], v[150:153], v[174:177], v[102:105]
	v_mfma_f32_16x16x32_bf16 v[98:101], v[158:161], v[174:177], v[98:101]
	v_mfma_f32_16x16x32_bf16 v[86:89], v[150:153], v[204:207], v[86:89]
	v_mfma_f32_16x16x32_bf16 v[78:81], v[158:161], v[204:207], v[78:81]
	v_mfma_f32_16x16x32_bf16 v[70:73], v[150:153], v[212:215], v[70:73]
	v_mfma_f32_16x16x32_bf16 v[66:69], v[158:161], v[212:215], v[66:69]
	s_setprio 0
	s_barrier
; #define PG8_STAGE(bufoff, gbase, voff) do { _Pragma("unroll") for (int _i = 0; _i < 2; ++_i) \
;         __builtin_amdgcn_global_load_lds((const unsigned*)((const char*)(gbase) + (voff)[_i]), (LAS unsigned*)(lds + (bufoff) + ldsw + _i * 8192), 16, 0, 0); } while (0)
; #define PG8_LDA(dst, b, h) do { _Pragma("unroll") for (int m = 0; m < 4; ++m) _Pragma("unroll") for (int k = 0; k < 2; ++k) dst[m][k] = *(const LAS bf16x8*)(lds + PG8_SA(b, h) + aoff + m * 2048 + k * 1024); } while (0)
; #define PG8_MMA(ai, bj, At, Bt) do { __builtin_amdgcn_s_setprio(1); _Pragma("unroll") for (int m = 0; m < 4; ++m) _Pragma("unroll") for (int n = 0; n < 2; ++n) _Pragma("unroll") for (int k = 0; k < 2; ++k) \
;         acc[ai][bj][m][n] = __builtin_amdgcn_mfma_f32_16x16x32_bf16(Bt[n][k], At[m][k], acc[ai][bj][m][n], 0, 0, 0); __builtin_amdgcn_s_setprio(0); } while (0)
; #define PG8_WAIT_V(n) asm volatile("s_waitcnt vmcnt(" #n ")" ::: "memory")
; #define PG8_WAIT_L(n) asm volatile("s_waitcnt lgkmcnt(" #n ")" ::: "memory")
; #define PG8_BAR __builtin_amdgcn_s_barrier()
; #define PG8_SCHED __builtin_amdgcn_sched_barrier(0)
; template <class Epi>
; __device__ __forceinline__ void gemm_phase(LAS unsigned char* lds, const Gemm g, const StaticOrder& S, const Epi& E) {
;     ...
;             PG8_LDA(At, 1, 1); PG8_STAGE(PG8_SB(1, 0), b3, voffB); PG8_STAGE(PG8_SB(1, 1), b3 + hstepB, voffB); PG8_STAGE(PG8_SA(1, 0), a3, voffA);
;             PG8_WAIT_V(8); PG8_WAIT_L(0); PG8_BAR; PG8_MMA(1, 0, At, B0); PG8_MMA(1, 1, At, B1); PG8_BAR; PG8_SCHED;
;         }
	s_add_i32 s28, s41, s30
	v_lshl_add_u64 v[178:179], v[178:179], 0, s[84:85]
	s_mov_b32 m0, s28
	ds_read_b128 v[162:165], v181 offset:49152
	ds_read_b128 v[166:169], v181 offset:50176
	ds_read_b128 v[170:173], v181 offset:51200
	ds_read_b128 v[174:177], v181 offset:52224
	ds_read_b128 v[200:203], v181 offset:53248
	ds_read_b128 v[204:207], v181 offset:54272
	ds_read_b128 v[208:211], v181 offset:55296
	ds_read_b128 v[212:215], v181 offset:56320
	global_load_lds_dwordx4 v[178:179], off
	s_add_i32 m0, s28, 0x2000
	s_add_u32 s14, s14, 0x80080
	v_lshl_add_u64 v[178:179], v[184:185], 0, s[84:85]
	s_addc_u32 s15, s15, 0
	s_add_i32 s28, s53, s30
	global_load_lds_dwordx4 v[178:179], off
	s_nop 0
	s_mov_b32 m0, s28
	s_nop 0
	global_load_lds_dwordx4 v190, s[14:15]
	s_nop 0
	s_add_i32 m0, s28, 0x2000
	s_nop 0
	global_load_lds_dwordx4 v194, s[14:15]
	v_lshl_add_u64 v[178:179], v[216:217], 0, s[84:85]
	s_mov_b32 m0, s44
	s_nop 0
	global_load_lds_dwordx4 v[178:179], off
	v_lshl_add_u64 v[178:179], v[218:219], 0, s[84:85]
	s_mov_b32 m0, s45
	s_nop 0
	global_load_lds_dwordx4 v[178:179], off
	s_waitcnt vmcnt(8)
	s_waitcnt lgkmcnt(0)
	s_barrier
	s_setprio 1
	s_waitcnt lgkmcnt(0)
	v_mfma_f32_16x16x32_bf16 v[62:65], v[130:133], v[162:165], v[62:65]
	v_mfma_f32_16x16x32_bf16 v[58:61], v[138:141], v[162:165], v[58:61]
	v_mfma_f32_16x16x32_bf16 v[50:53], v[130:133], v[170:173], v[50:53]
	v_mfma_f32_16x16x32_bf16 v[42:45], v[138:141], v[170:173], v[42:45]
	v_mfma_f32_16x16x32_bf16 v[30:33], v[130:133], v[200:203], v[30:33]
	v_mfma_f32_16x16x32_bf16 v[26:29], v[138:141], v[200:203], v[26:29]
	v_mfma_f32_16x16x32_bf16 v[18:21], v[130:133], v[208:211], v[18:21]
	v_mfma_f32_16x16x32_bf16 v[10:13], v[138:141], v[208:211], v[10:13]
	v_mfma_f32_16x16x32_bf16 v[62:65], v[134:137], v[166:169], v[62:65]
	v_mfma_f32_16x16x32_bf16 v[58:61], v[142:145], v[166:169], v[58:61]
	v_mfma_f32_16x16x32_bf16 v[50:53], v[134:137], v[174:177], v[50:53]
	v_mfma_f32_16x16x32_bf16 v[42:45], v[142:145], v[174:177], v[42:45]
	v_mfma_f32_16x16x32_bf16 v[30:33], v[134:137], v[204:207], v[30:33]
	v_mfma_f32_16x16x32_bf16 v[26:29], v[142:145], v[204:207], v[26:29]
	v_mfma_f32_16x16x32_bf16 v[18:21], v[134:137], v[212:215], v[18:21]
	v_mfma_f32_16x16x32_bf16 v[10:13], v[142:145], v[212:215], v[10:13]
	s_setprio 0
	s_setprio 1
	v_mfma_f32_16x16x32_bf16 v[54:57], v[146:149], v[162:165], v[54:57]
	v_mfma_f32_16x16x32_bf16 v[46:49], v[154:157], v[162:165], v[46:49]
	v_mfma_f32_16x16x32_bf16 v[38:41], v[146:149], v[170:173], v[38:41]
	v_mfma_f32_16x16x32_bf16 v[34:37], v[154:157], v[170:173], v[34:37]
	v_mfma_f32_16x16x32_bf16 v[22:25], v[146:149], v[200:203], v[22:25]
	v_mfma_f32_16x16x32_bf16 v[14:17], v[154:157], v[200:203], v[14:17]
	v_mfma_f32_16x16x32_bf16 v[6:9], v[146:149], v[208:211], v[6:9]
	v_mfma_f32_16x16x32_bf16 v[2:5], v[154:157], v[208:211], v[2:5]
	v_mfma_f32_16x16x32_bf16 v[54:57], v[150:153], v[166:169], v[54:57]
	v_mfma_f32_16x16x32_bf16 v[46:49], v[158:161], v[166:169], v[46:49]
	v_mfma_f32_16x16x32_bf16 v[38:41], v[150:153], v[174:177], v[38:41]
	v_mfma_f32_16x16x32_bf16 v[34:37], v[158:161], v[174:177], v[34:37]
	v_mfma_f32_16x16x32_bf16 v[22:25], v[150:153], v[204:207], v[22:25]
	v_mfma_f32_16x16x32_bf16 v[14:17], v[158:161], v[204:207], v[14:17]
	v_mfma_f32_16x16x32_bf16 v[6:9], v[150:153], v[212:215], v[6:9]
	v_mfma_f32_16x16x32_bf16 v[2:5], v[158:161], v[212:215], v[2:5]
	s_setprio 0
	s_barrier
	s_add_i32 s52, s52, 2
	s_add_u32 s26, s26, 0x100
	s_addc_u32 s27, s27, 0
	s_add_u32 s19, s19, 0x100
	s_addc_u32 s40, s40, 0
	s_cmp_gt_u32 s52, 29
	s_cbranch_scc0 .LBB0_1010
	s_and_b64 vcc, exec, s[12:13]
	s_cbranch_vccz .LBB0_1013
	s_barrier

; #define PG8_STAGE(bufoff, gbase, voff) do { _Pragma("unroll") for (int _i = 0; _i < 2; ++_i) \
;         __builtin_amdgcn_global_load_lds((const unsigned*)((const char*)(gbase) + (voff)[_i]), (LAS unsigned*)(lds + (bufoff) + ldsw + _i * 8192), 16, 0, 0); } while (0)
; #define PG8_LDA(dst, b, h) do { _Pragma("unroll") for (int m = 0; m < 4; ++m) _Pragma("unroll") for (int k = 0; k < 2; ++k) dst[m][k] = *(const LAS bf16x8*)(lds + PG8_SA(b, h) + aoff + m * 2048 + k * 1024); } while (0)
; #define PG8_LDB(dst, b, h) do { _Pragma("unroll") for (int n = 0; n < 2; ++n) _Pragma("unroll") for (int k = 0; k < 2; ++k) dst[n][k] = *(const LAS bf16x8*)(lds + PG8_SB(b, h) + boff + n * 2048 + k * 1024); } while (0)
; #define PG8_MMA(ai, bj, At, Bt) do { __builtin_amdgcn_s_setprio(1); _Pragma("unroll") for (int m = 0; m < 4; ++m) _Pragma("unroll") for (int n = 0; n < 2; ++n) _Pragma("unroll") for (int k = 0; k < 2; ++k) \
;         acc[ai][bj][m][n] = __builtin_amdgcn_mfma_f32_16x16x32_bf16(Bt[n][k], At[m][k], acc[ai][bj][m][n], 0, 0, 0); __builtin_amdgcn_s_setprio(0); } while (0)
; #define PG8_WAIT_V(n) asm volatile("s_waitcnt vmcnt(" #n ")" ::: "memory")
; #define PG8_WAIT_L(n) asm volatile("s_waitcnt lgkmcnt(" #n ")" ::: "memory")
; #define PG8_BAR __builtin_amdgcn_s_barrier()
; #define PG8_SCHED __builtin_amdgcn_sched_barrier(0)
; template <class Epi>
; __device__ __forceinline__ void gemm_phase(LAS unsigned char* lds, const Gemm g, const StaticOrder& S, const Epi& E) {
;     ...
;             PG8_LDB(B0, 0, 0); PG8_LDB(B1, 0, 1); PG8_SCHED; PG8_LDA(At, 0, 0); PG8_STAGE(PG8_SA(1, 1), a1 + hstepA, voffA);
;             PG8_WAIT_V(8); PG8_WAIT_L(0); PG8_BAR; PG8_MMA(0, 0, At, B0); PG8_MMA(0, 1, At, B1); PG8_BAR; PG8_SCHED;
;             PG8_LDA(At, 0, 1); PG8_STAGE(PG8_SB(0, 0), b2, voffB); PG8_STAGE(PG8_SB(0, 1), b2 + hstepB, voffB); PG8_STAGE(PG8_SA(0, 0), a2, voffA);
;             PG8_WAIT_V(8); PG8_WAIT_L(0); PG8_BAR; PG8_MMA(1, 0, At, B0); PG8_MMA(1, 1, At, B1); PG8_BAR; PG8_SCHED;
.LBB0_1107:
	s_add_u32 s34, vcc_lo, 0xfff80080
	s_addc_u32 s35, vcc_hi, -1
	s_add_i32 s76, 0, 0x10000
	s_cmp_eq_u32 s41, 28
	s_cselect_b32 s69, s3, s35
	s_cselect_b32 s68, s7, s34
	s_cselect_b32 s35, s13, s87
	s_cselect_b32 s34, s40, s65
	s_add_i32 s78, 0, 0x14000
	v_add_u32_e32 v142, s76, v1
	v_add_u32_e32 v163, s78, v1
	ds_read_b128 v[130:133], v142
	ds_read_b128 v[134:137], v142 offset:1024
	ds_read_b128 v[138:141], v142 offset:2048
	ds_read_b128 v[142:145], v142 offset:3072
	ds_read_b128 v[158:161], v163
	ds_read_b128 v[164:167], v163 offset:1024
	ds_read_b128 v[168:171], v163 offset:2048
	ds_read_b128 v[172:175], v163 offset:3072
	v_lshl_add_u64 v[184:185], vcc, 0, v[154:155]
	s_add_i32 m0, s70, 0xc000
	ds_read_b128 v[176:179], v162
	ds_read_b128 v[188:191], v162 offset:1024
	ds_read_b128 v[192:195], v162 offset:2048
	ds_read_b128 v[196:199], v162 offset:3072
	ds_read_b128 v[200:203], v162 offset:4096
	ds_read_b128 v[204:207], v162 offset:5120
	ds_read_b128 v[208:211], v162 offset:6144
	ds_read_b128 v[212:215], v162 offset:7168
	global_load_lds_dwordx4 v[184:185], off
	v_lshl_add_u64 v[184:185], vcc, 0, v[156:157]
	s_add_i32 m0, s70, 0xe000
	s_nop 0
	global_load_lds_dwordx4 v[184:185], off
	s_waitcnt vmcnt(8)
	s_waitcnt lgkmcnt(0)
	s_barrier
	s_setprio 1
	s_waitcnt lgkmcnt(0)
	v_mfma_f32_16x16x32_bf16 v[126:129], v[130:133], v[176:179], v[126:129]
	v_mfma_f32_16x16x32_bf16 v[122:125], v[138:141], v[176:179], v[122:125]
	v_mfma_f32_16x16x32_bf16 v[114:117], v[130:133], v[192:195], v[114:117]
	v_mfma_f32_16x16x32_bf16 v[106:109], v[138:141], v[192:195], v[106:109]
	v_mfma_f32_16x16x32_bf16 v[98:101], v[130:133], v[200:203], v[98:101]
	v_mfma_f32_16x16x32_bf16 v[90:93], v[138:141], v[200:203], v[90:93]
	v_mfma_f32_16x16x32_bf16 v[82:85], v[130:133], v[208:211], v[82:85]
	v_mfma_f32_16x16x32_bf16 v[74:77], v[138:141], v[208:211], v[74:77]
	v_mfma_f32_16x16x32_bf16 v[126:129], v[134:137], v[188:191], v[126:129]
	v_mfma_f32_16x16x32_bf16 v[122:125], v[142:145], v[188:191], v[122:125]
	v_mfma_f32_16x16x32_bf16 v[114:117], v[134:137], v[196:199], v[114:117]
	v_mfma_f32_16x16x32_bf16 v[106:109], v[142:145], v[196:199], v[106:109]
	v_mfma_f32_16x16x32_bf16 v[98:101], v[134:137], v[204:207], v[98:101]
	v_mfma_f32_16x16x32_bf16 v[90:93], v[142:145], v[204:207], v[90:93]
	v_mfma_f32_16x16x32_bf16 v[82:85], v[134:137], v[212:215], v[82:85]
	v_mfma_f32_16x16x32_bf16 v[74:77], v[142:145], v[212:215], v[74:77]
	s_setprio 0
	s_setprio 1
	v_mfma_f32_16x16x32_bf16 v[118:121], v[158:161], v[176:179], v[118:121]
	v_mfma_f32_16x16x32_bf16 v[110:113], v[168:171], v[176:179], v[110:113]
	v_mfma_f32_16x16x32_bf16 v[102:105], v[158:161], v[192:195], v[102:105]
	v_mfma_f32_16x16x32_bf16 v[94:97], v[168:171], v[192:195], v[94:97]
	v_mfma_f32_16x16x32_bf16 v[86:89], v[158:161], v[200:203], v[86:89]
	v_mfma_f32_16x16x32_bf16 v[78:81], v[168:171], v[200:203], v[78:81]
	v_mfma_f32_16x16x32_bf16 v[70:73], v[158:161], v[208:211], v[70:73]
	v_mfma_f32_16x16x32_bf16 v[66:69], v[168:171], v[208:211], v[66:69]
	v_mfma_f32_16x16x32_bf16 v[118:121], v[164:167], v[188:191], v[118:121]
	v_mfma_f32_16x16x32_bf16 v[110:113], v[172:175], v[188:191], v[110:113]
	v_mfma_f32_16x16x32_bf16 v[102:105], v[164:167], v[196:199], v[102:105]
	v_mfma_f32_16x16x32_bf16 v[94:97], v[172:175], v[196:199], v[94:97]
	v_mfma_f32_16x16x32_bf16 v[86:89], v[164:167], v[204:207], v[86:89]
	v_mfma_f32_16x16x32_bf16 v[78:81], v[172:175], v[204:207], v[78:81]
	v_mfma_f32_16x16x32_bf16 v[70:73], v[164:167], v[212:215], v[70:73]
	v_mfma_f32_16x16x32_bf16 v[66:69], v[172:175], v[212:215], v[66:69]
	s_setprio 0
	s_barrier
	s_add_i32 s76, s76, s42
	v_lshl_add_u64 v[184:185], s[34:35], 0, v[148:149]
	s_mov_b32 m0, s76
	ds_read_b128 v[176:179], v162 offset:16384
	ds_read_b128 v[188:191], v162 offset:17408
	ds_read_b128 v[192:195], v162 offset:18432
	ds_read_b128 v[196:199], v162 offset:19456
	ds_read_b128 v[200:203], v162 offset:20480
	ds_read_b128 v[204:207], v162 offset:21504
	ds_read_b128 v[208:211], v162 offset:22528
	ds_read_b128 v[212:215], v162 offset:23552
	global_load_lds_dwordx4 v148, s[34:35]
	s_add_i32 m0, s76, 0x2000
	s_add_u32 s76, s34, 0x80000
	v_lshl_add_u64 v[216:217], s[34:35], 0, v[152:153]
	s_addc_u32 s77, s35, 0
	s_add_i32 s78, s78, s42
	global_load_lds_dwordx4 v152, s[34:35]
	s_nop 0
	s_mov_b32 m0, s78
	v_lshl_add_u64 v[220:221], s[68:69], 0, v[150:151]
	global_load_lds_dwordx4 v148, s[76:77]
	s_nop 0
	s_add_i32 m0, s78, 0x2000
	s_nop 0
	global_load_lds_dwordx4 v152, s[76:77]
	v_lshl_add_u64 v[218:219], s[68:69], 0, v[146:147]
	s_mov_b32 m0, s70
	s_nop 0
	global_load_lds_dwordx4 v146, s[68:69]
	s_mov_b32 m0, s91
	s_nop 0
	global_load_lds_dwordx4 v150, s[68:69]
	s_waitcnt vmcnt(8)
	s_waitcnt lgkmcnt(0)
	s_barrier
; #define PG8_STAGE(bufoff, gbase, voff) do { _Pragma("unroll") for (int _i = 0; _i < 2; ++_i) \
;         __builtin_amdgcn_global_load_lds((const unsigned*)((const char*)(gbase) + (voff)[_i]), (LAS unsigned*)(lds + (bufoff) + ldsw + _i * 8192), 16, 0, 0); } while (0)
; #define PG8_LDA(dst, b, h) do { _Pragma("unroll") for (int m = 0; m < 4; ++m) _Pragma("unroll") for (int k = 0; k < 2; ++k) dst[m][k] = *(const LAS bf16x8*)(lds + PG8_SA(b, h) + aoff + m * 2048 + k * 1024); } while (0)
; #define PG8_LDB(dst, b, h) do { _Pragma("unroll") for (int n = 0; n < 2; ++n) _Pragma("unroll") for (int k = 0; k < 2; ++k) dst[n][k] = *(const LAS bf16x8*)(lds + PG8_SB(b, h) + boff + n * 2048 + k * 1024); } while (0)
; #define PG8_MMA(ai, bj, At, Bt) do { __builtin_amdgcn_s_setprio(1); _Pragma("unroll") for (int m = 0; m < 4; ++m) _Pragma("unroll") for (int n = 0; n < 2; ++n) _Pragma("unroll") for (int k = 0; k < 2; ++k) \
;         acc[ai][bj][m][n] = __builtin_amdgcn_mfma_f32_16x16x32_bf16(Bt[n][k], At[m][k], acc[ai][bj][m][n], 0, 0, 0); __builtin_amdgcn_s_setprio(0); } while (0)
; #define PG8_WAIT_V(n) asm volatile("s_waitcnt vmcnt(" #n ")" ::: "memory")
; #define PG8_WAIT_L(n) asm volatile("s_waitcnt lgkmcnt(" #n ")" ::: "memory")
; #define PG8_BAR __builtin_amdgcn_s_barrier()
; #define PG8_SCHED __builtin_amdgcn_sched_barrier(0)
; template <class Epi>
; __device__ __forceinline__ void gemm_phase(LAS unsigned char* lds, const Gemm g, const StaticOrder& S, const Epi& E) {
;     ...
;             PG8_WAIT_V(8); PG8_WAIT_L(0); PG8_BAR; PG8_MMA(1, 0, At, B0); PG8_MMA(1, 1, At, B1); PG8_BAR; PG8_SCHED;
;             PG8_LDB(B0, 1, 0); PG8_LDB(B1, 1, 1); PG8_SCHED; PG8_LDA(At, 1, 0); PG8_STAGE(PG8_SA(0, 1), a2 + hstepA, voffA);
;             PG8_WAIT_V(8); PG8_WAIT_L(0); PG8_BAR; PG8_MMA(0, 0, At, B0); PG8_MMA(0, 1, At, B1); PG8_BAR; PG8_SCHED;
	s_setprio 1
	s_waitcnt lgkmcnt(0)
	v_mfma_f32_16x16x32_bf16 v[62:65], v[130:133], v[176:179], v[62:65]
	v_mfma_f32_16x16x32_bf16 v[58:61], v[138:141], v[176:179], v[58:61]
	v_mfma_f32_16x16x32_bf16 v[54:57], v[130:133], v[192:195], v[54:57]
	v_mfma_f32_16x16x32_bf16 v[46:49], v[138:141], v[192:195], v[46:49]
	v_mfma_f32_16x16x32_bf16 v[38:41], v[130:133], v[200:203], v[38:41]
	v_mfma_f32_16x16x32_bf16 v[30:33], v[138:141], v[200:203], v[30:33]
	v_mfma_f32_16x16x32_bf16 v[22:25], v[130:133], v[208:211], v[22:25]
	v_mfma_f32_16x16x32_bf16 v[14:17], v[138:141], v[208:211], v[14:17]
	v_mfma_f32_16x16x32_bf16 v[62:65], v[134:137], v[188:191], v[62:65]
	v_mfma_f32_16x16x32_bf16 v[58:61], v[142:145], v[188:191], v[58:61]
	v_mfma_f32_16x16x32_bf16 v[54:57], v[134:137], v[196:199], v[54:57]
	v_mfma_f32_16x16x32_bf16 v[46:49], v[142:145], v[196:199], v[46:49]
	v_mfma_f32_16x16x32_bf16 v[38:41], v[134:137], v[204:207], v[38:41]
	v_mfma_f32_16x16x32_bf16 v[30:33], v[142:145], v[204:207], v[30:33]
	v_mfma_f32_16x16x32_bf16 v[22:25], v[134:137], v[212:215], v[22:25]
	v_mfma_f32_16x16x32_bf16 v[14:17], v[142:145], v[212:215], v[14:17]
	s_setprio 0
	s_setprio 1
	v_mfma_f32_16x16x32_bf16 v[50:53], v[158:161], v[176:179], v[50:53]
	v_mfma_f32_16x16x32_bf16 v[42:45], v[168:171], v[176:179], v[42:45]
	v_mfma_f32_16x16x32_bf16 v[34:37], v[158:161], v[192:195], v[34:37]
	v_mfma_f32_16x16x32_bf16 v[26:29], v[168:171], v[192:195], v[26:29]
	v_mfma_f32_16x16x32_bf16 v[18:21], v[158:161], v[200:203], v[18:21]
	v_mfma_f32_16x16x32_bf16 v[10:13], v[168:171], v[200:203], v[10:13]
	v_mfma_f32_16x16x32_bf16 v[6:9], v[158:161], v[208:211], v[6:9]
	v_mfma_f32_16x16x32_bf16 v[2:5], v[168:171], v[208:211], v[2:5]
	v_mfma_f32_16x16x32_bf16 v[50:53], v[164:167], v[188:191], v[50:53]
	v_mfma_f32_16x16x32_bf16 v[42:45], v[172:175], v[188:191], v[42:45]
	v_mfma_f32_16x16x32_bf16 v[34:37], v[164:167], v[196:199], v[34:37]
	v_mfma_f32_16x16x32_bf16 v[26:29], v[172:175], v[196:199], v[26:29]
	v_mfma_f32_16x16x32_bf16 v[18:21], v[164:167], v[204:207], v[18:21]
	v_mfma_f32_16x16x32_bf16 v[10:13], v[172:175], v[204:207], v[10:13]
	v_mfma_f32_16x16x32_bf16 v[6:9], v[164:167], v[212:215], v[6:9]
	v_mfma_f32_16x16x32_bf16 v[2:5], v[172:175], v[212:215], v[2:5]
	s_setprio 0
	s_barrier
	s_add_i32 s76, 0, 0x18000
	s_add_i32 s77, 0, 0x1c000
	v_add_u32_e32 v142, s76, v1
	v_add_u32_e32 v163, s77, v1
	ds_read_b128 v[130:133], v142
	ds_read_b128 v[134:137], v142 offset:1024
	ds_read_b128 v[138:141], v142 offset:2048
	ds_read_b128 v[142:145], v142 offset:3072
	ds_read_b128 v[158:161], v163
	ds_read_b128 v[164:167], v163 offset:1024
	ds_read_b128 v[168:171], v163 offset:2048
	ds_read_b128 v[172:175], v163 offset:3072
	s_add_u32 s68, s68, 0x80000
	s_addc_u32 s69, s69, 0
	s_mov_b32 m0, s62
	s_nop 0
	ds_read_b128 v[176:179], v162 offset:32768
	ds_read_b128 v[188:191], v162 offset:33792
	ds_read_b128 v[192:195], v162 offset:34816
	ds_read_b128 v[196:199], v162 offset:35840
	ds_read_b128 v[200:203], v162 offset:36864
	ds_read_b128 v[204:207], v162 offset:37888
	ds_read_b128 v[208:211], v162 offset:38912
	ds_read_b128 v[212:215], v162 offset:39936
	global_load_lds_dwordx4 v146, s[68:69]
	s_nop 0
	s_mov_b32 m0, s63
	s_nop 0
	global_load_lds_dwordx4 v150, s[68:69]
	s_waitcnt vmcnt(8)
	s_waitcnt lgkmcnt(0)
	s_barrier
	s_setprio 1
	s_waitcnt lgkmcnt(0)
	v_mfma_f32_16x16x32_bf16 v[126:129], v[130:133], v[176:179], v[126:129]
	v_mfma_f32_16x16x32_bf16 v[122:125], v[138:141], v[176:179], v[122:125]
	v_mfma_f32_16x16x32_bf16 v[114:117], v[130:133], v[192:195], v[114:117]
	v_mfma_f32_16x16x32_bf16 v[106:109], v[138:141], v[192:195], v[106:109]
	v_mfma_f32_16x16x32_bf16 v[98:101], v[130:133], v[200:203], v[98:101]
	v_mfma_f32_16x16x32_bf16 v[90:93], v[138:141], v[200:203], v[90:93]
	v_mfma_f32_16x16x32_bf16 v[82:85], v[130:133], v[208:211], v[82:85]
	v_mfma_f32_16x16x32_bf16 v[74:77], v[138:141], v[208:211], v[74:77]
	v_mfma_f32_16x16x32_bf16 v[126:129], v[134:137], v[188:191], v[126:129]
	v_mfma_f32_16x16x32_bf16 v[122:125], v[142:145], v[188:191], v[122:125]
	v_mfma_f32_16x16x32_bf16 v[114:117], v[134:137], v[196:199], v[114:117]
	v_mfma_f32_16x16x32_bf16 v[106:109], v[142:145], v[196:199], v[106:109]
	v_mfma_f32_16x16x32_bf16 v[98:101], v[134:137], v[204:207], v[98:101]
	v_mfma_f32_16x16x32_bf16 v[90:93], v[142:145], v[204:207], v[90:93]
	v_mfma_f32_16x16x32_bf16 v[82:85], v[134:137], v[212:215], v[82:85]
	v_mfma_f32_16x16x32_bf16 v[74:77], v[142:145], v[212:215], v[74:77]
	s_setprio 0
	s_setprio 1
	v_mfma_f32_16x16x32_bf16 v[118:121], v[158:161], v[176:179], v[118:121]
	v_mfma_f32_16x16x32_bf16 v[110:113], v[168:171], v[176:179], v[110:113]
	v_mfma_f32_16x16x32_bf16 v[102:105], v[158:161], v[192:195], v[102:105]
	v_mfma_f32_16x16x32_bf16 v[94:97], v[168:171], v[192:195], v[94:97]
	v_mfma_f32_16x16x32_bf16 v[86:89], v[158:161], v[200:203], v[86:89]
	v_mfma_f32_16x16x32_bf16 v[78:81], v[168:171], v[200:203], v[78:81]
	v_mfma_f32_16x16x32_bf16 v[70:73], v[158:161], v[208:211], v[70:73]
	v_mfma_f32_16x16x32_bf16 v[66:69], v[168:171], v[208:211], v[66:69]
	v_mfma_f32_16x16x32_bf16 v[118:121], v[164:167], v[188:191], v[118:121]
	v_mfma_f32_16x16x32_bf16 v[110:113], v[172:175], v[188:191], v[110:113]
	v_mfma_f32_16x16x32_bf16 v[102:105], v[164:167], v[196:199], v[102:105]
	v_mfma_f32_16x16x32_bf16 v[94:97], v[172:175], v[196:199], v[94:97]
	v_mfma_f32_16x16x32_bf16 v[86:89], v[164:167], v[204:207], v[86:89]
	v_mfma_f32_16x16x32_bf16 v[78:81], v[172:175], v[204:207], v[78:81]
	v_mfma_f32_16x16x32_bf16 v[70:73], v[164:167], v[212:215], v[70:73]
	v_mfma_f32_16x16x32_bf16 v[66:69], v[172:175], v[212:215], v[66:69]
	s_setprio 0
	s_barrier
; #define PG8_STAGE(bufoff, gbase, voff) do { _Pragma("unroll") for (int _i = 0; _i < 2; ++_i) \
;         __builtin_amdgcn_global_load_lds((const unsigned*)((const char*)(gbase) + (voff)[_i]), (LAS unsigned*)(lds + (bufoff) + ldsw + _i * 8192), 16, 0, 0); } while (0)
; #define PG8_LDA(dst, b, h) do { _Pragma("unroll") for (int m = 0; m < 4; ++m) _Pragma("unroll") for (int k = 0; k < 2; ++k) dst[m][k] = *(const LAS bf16x8*)(lds + PG8_SA(b, h) + aoff + m * 2048 + k * 1024); } while (0)
; #define PG8_MMA(ai, bj, At, Bt) do { __builtin_amdgcn_s_setprio(1); _Pragma("unroll") for (int m = 0; m < 4; ++m) _Pragma("unroll") for (int n = 0; n < 2; ++n) _Pragma("unroll") for (int k = 0; k < 2; ++k) \
;         acc[ai][bj][m][n] = __builtin_amdgcn_mfma_f32_16x16x32_bf16(Bt[n][k], At[m][k], acc[ai][bj][m][n], 0, 0, 0); __builtin_amdgcn_s_setprio(0); } while (0)
; #define PG8_WAIT_V(n) asm volatile("s_waitcnt vmcnt(" #n ")" ::: "memory")
; #define PG8_WAIT_L(n) asm volatile("s_waitcnt lgkmcnt(" #n ")" ::: "memory")
; #define PG8_BAR __builtin_amdgcn_s_barrier()
; #define PG8_SCHED __builtin_amdgcn_sched_barrier(0)
; template <class Epi>
; __device__ __forceinline__ void gemm_phase(LAS unsigned char* lds, const Gemm g, const StaticOrder& S, const Epi& E) {
;     ...
;             PG8_LDA(At, 1, 1); PG8_STAGE(PG8_SB(1, 0), b3, voffB); PG8_STAGE(PG8_SB(1, 1), b3 + hstepB, voffB); PG8_STAGE(PG8_SA(1, 0), a3, voffA);
;             PG8_WAIT_V(8); PG8_WAIT_L(0); PG8_BAR; PG8_MMA(1, 0, At, B0); PG8_MMA(1, 1, At, B1); PG8_BAR; PG8_SCHED;
;         }
	s_add_i32 s68, s76, s42
	v_lshl_add_u64 v[184:185], v[184:185], 0, s[84:85]
	s_mov_b32 m0, s68
	ds_read_b128 v[176:179], v162 offset:49152
	ds_read_b128 v[188:191], v162 offset:50176
	ds_read_b128 v[192:195], v162 offset:51200
	ds_read_b128 v[196:199], v162 offset:52224
	ds_read_b128 v[200:203], v162 offset:53248
	ds_read_b128 v[204:207], v162 offset:54272
	ds_read_b128 v[208:211], v162 offset:55296
	ds_read_b128 v[212:215], v162 offset:56320
	global_load_lds_dwordx4 v[184:185], off
	s_add_i32 m0, s68, 0x2000
	s_add_u32 s34, s34, 0x80080
	v_lshl_add_u64 v[184:185], v[216:217], 0, s[84:85]
	s_addc_u32 s35, s35, 0
	s_add_i32 s68, s77, s42
	global_load_lds_dwordx4 v[184:185], off
	s_nop 0
	s_mov_b32 m0, s68
	s_nop 0
	global_load_lds_dwordx4 v148, s[34:35]
	s_nop 0
	s_add_i32 m0, s68, 0x2000
	s_nop 0
	global_load_lds_dwordx4 v152, s[34:35]
	v_lshl_add_u64 v[184:185], v[218:219], 0, s[84:85]
	s_mov_b32 m0, s94
	s_nop 0
	global_load_lds_dwordx4 v[184:185], off
	v_lshl_add_u64 v[184:185], v[220:221], 0, s[84:85]
	s_mov_b32 m0, s95
	s_nop 0
	global_load_lds_dwordx4 v[184:185], off
	s_waitcnt vmcnt(8)
	s_waitcnt lgkmcnt(0)
	s_barrier
	s_setprio 1
	s_waitcnt lgkmcnt(0)
	v_mfma_f32_16x16x32_bf16 v[62:65], v[130:133], v[176:179], v[62:65]
	v_mfma_f32_16x16x32_bf16 v[58:61], v[138:141], v[176:179], v[58:61]
	v_mfma_f32_16x16x32_bf16 v[54:57], v[130:133], v[192:195], v[54:57]
	v_mfma_f32_16x16x32_bf16 v[46:49], v[138:141], v[192:195], v[46:49]
	v_mfma_f32_16x16x32_bf16 v[38:41], v[130:133], v[200:203], v[38:41]
	v_mfma_f32_16x16x32_bf16 v[30:33], v[138:141], v[200:203], v[30:33]
	v_mfma_f32_16x16x32_bf16 v[22:25], v[130:133], v[208:211], v[22:25]
	v_mfma_f32_16x16x32_bf16 v[14:17], v[138:141], v[208:211], v[14:17]
	v_mfma_f32_16x16x32_bf16 v[62:65], v[134:137], v[188:191], v[62:65]
	v_mfma_f32_16x16x32_bf16 v[58:61], v[142:145], v[188:191], v[58:61]
	v_mfma_f32_16x16x32_bf16 v[54:57], v[134:137], v[196:199], v[54:57]
	v_mfma_f32_16x16x32_bf16 v[46:49], v[142:145], v[196:199], v[46:49]
	v_mfma_f32_16x16x32_bf16 v[38:41], v[134:137], v[204:207], v[38:41]
	v_mfma_f32_16x16x32_bf16 v[30:33], v[142:145], v[204:207], v[30:33]
	v_mfma_f32_16x16x32_bf16 v[22:25], v[134:137], v[212:215], v[22:25]
	v_mfma_f32_16x16x32_bf16 v[14:17], v[142:145], v[212:215], v[14:17]
	s_setprio 0
	s_setprio 1
	v_mfma_f32_16x16x32_bf16 v[50:53], v[158:161], v[176:179], v[50:53]
	v_mfma_f32_16x16x32_bf16 v[42:45], v[168:171], v[176:179], v[42:45]
	v_mfma_f32_16x16x32_bf16 v[34:37], v[158:161], v[192:195], v[34:37]
	v_mfma_f32_16x16x32_bf16 v[26:29], v[168:171], v[192:195], v[26:29]
	v_mfma_f32_16x16x32_bf16 v[18:21], v[158:161], v[200:203], v[18:21]
	v_mfma_f32_16x16x32_bf16 v[10:13], v[168:171], v[200:203], v[10:13]
	v_mfma_f32_16x16x32_bf16 v[6:9], v[158:161], v[208:211], v[6:9]
	v_mfma_f32_16x16x32_bf16 v[2:5], v[168:171], v[208:211], v[2:5]
	v_mfma_f32_16x16x32_bf16 v[50:53], v[164:167], v[188:191], v[50:53]
	v_mfma_f32_16x16x32_bf16 v[42:45], v[172:175], v[188:191], v[42:45]
	v_mfma_f32_16x16x32_bf16 v[34:37], v[164:167], v[196:199], v[34:37]
	v_mfma_f32_16x16x32_bf16 v[26:29], v[172:175], v[196:199], v[26:29]
	v_mfma_f32_16x16x32_bf16 v[18:21], v[164:167], v[204:207], v[18:21]
	v_mfma_f32_16x16x32_bf16 v[10:13], v[172:175], v[204:207], v[10:13]
	v_mfma_f32_16x16x32_bf16 v[6:9], v[164:167], v[212:215], v[6:9]
	v_mfma_f32_16x16x32_bf16 v[2:5], v[172:175], v[212:215], v[2:5]
	s_setprio 0
	s_barrier
	s_add_i32 s41, s41, 2
	s_add_u32 vcc_lo, vcc_lo, 0x100
	s_addc_u32 vcc_hi, vcc_hi, 0
	s_add_u32 s65, s65, 0x100
	s_addc_u32 s87, s87, 0
	s_cmp_gt_u32 s41, 29
	s_cbranch_scc0 .LBB0_1107
	s_and_b64 vcc, exec, s[10:11]
	s_cbranch_vccz .LBB0_1110
	s_barrier

; #define PG8_STAGE(bufoff, gbase, voff) do { _Pragma("unroll") for (int _i = 0; _i < 2; ++_i) \
;         __builtin_amdgcn_global_load_lds((const unsigned*)((const char*)(gbase) + (voff)[_i]), (LAS unsigned*)(lds + (bufoff) + ldsw + _i * 8192), 16, 0, 0); } while (0)
; #define PG8_LDA(dst, b, h) do { _Pragma("unroll") for (int m = 0; m < 4; ++m) _Pragma("unroll") for (int k = 0; k < 2; ++k) dst[m][k] = *(const LAS bf16x8*)(lds + PG8_SA(b, h) + aoff + m * 2048 + k * 1024); } while (0)
; #define PG8_LDB(dst, b, h) do { _Pragma("unroll") for (int n = 0; n < 2; ++n) _Pragma("unroll") for (int k = 0; k < 2; ++k) dst[n][k] = *(const LAS bf16x8*)(lds + PG8_SB(b, h) + boff + n * 2048 + k * 1024); } while (0)
; #define PG8_MMA(ai, bj, At, Bt) do { __builtin_amdgcn_s_setprio(1); _Pragma("unroll") for (int m = 0; m < 4; ++m) _Pragma("unroll") for (int n = 0; n < 2; ++n) _Pragma("unroll") for (int k = 0; k < 2; ++k) \
;         acc[ai][bj][m][n] = __builtin_amdgcn_mfma_f32_16x16x32_bf16(Bt[n][k], At[m][k], acc[ai][bj][m][n], 0, 0, 0); __builtin_amdgcn_s_setprio(0); } while (0)
; #define PG8_WAIT_V(n) asm volatile("s_waitcnt vmcnt(" #n ")" ::: "memory")
; #define PG8_WAIT_L(n) asm volatile("s_waitcnt lgkmcnt(" #n ")" ::: "memory")
; #define PG8_BAR __builtin_amdgcn_s_barrier()
; #define PG8_SCHED __builtin_amdgcn_sched_barrier(0)
; template <class Epi>
; __device__ __forceinline__ void gemm_phase(LAS unsigned char* lds, const Gemm g, const StaticOrder& S, const Epi& E) {
;     ...
;             PG8_LDB(B0, 0, 0); PG8_LDB(B1, 0, 1); PG8_SCHED; PG8_LDA(At, 0, 0); PG8_STAGE(PG8_SA(1, 1), a1 + hstepA, voffA);
;             PG8_WAIT_V(8); PG8_WAIT_L(0); PG8_BAR; PG8_MMA(0, 0, At, B0); PG8_MMA(0, 1, At, B1); PG8_BAR; PG8_SCHED;
;             PG8_LDA(At, 0, 1); PG8_STAGE(PG8_SB(0, 0), b2, voffB); PG8_STAGE(PG8_SB(0, 1), b2 + hstepB, voffB); PG8_STAGE(PG8_SA(0, 0), a2, voffA);
;             PG8_WAIT_V(8); PG8_WAIT_L(0); PG8_BAR; PG8_MMA(1, 0, At, B0); PG8_MMA(1, 1, At, B1); PG8_BAR; PG8_SCHED;
.LBB0_1324:
	s_add_u32 s14, s24, 0xfff80080
	s_addc_u32 s15, s25, -1
	s_add_i32 s53, 0, 0x10000
	s_cmp_eq_u32 s41, 28
	s_cselect_b32 s27, s3, s15
	s_cselect_b32 s26, s7, s14
	s_cselect_b32 s15, s13, s52
	s_cselect_b32 s14, s17, s40
	s_add_i32 s69, 0, 0x14000
	v_add_u32_e32 v142, s53, v1
	v_add_u32_e32 v158, s69, v1
	ds_read_b128 v[130:133], v142
	ds_read_b128 v[134:137], v142 offset:1024
	ds_read_b128 v[138:141], v142 offset:2048
	ds_read_b128 v[142:145], v142 offset:3072
	ds_read_b128 v[146:149], v158
	ds_read_b128 v[150:153], v158 offset:1024
	ds_read_b128 v[154:157], v158 offset:2048
	ds_read_b128 v[158:161], v158 offset:3072
	s_nop 0
	s_add_i32 m0, s23, 0xc000
	ds_read_b128 v[162:165], v181
	ds_read_b128 v[174:177], v181 offset:1024
	ds_read_b128 v[188:191], v181 offset:2048
	ds_read_b128 v[192:195], v181 offset:3072
	ds_read_b128 v[196:199], v181 offset:4096
	ds_read_b128 v[200:203], v181 offset:5120
	ds_read_b128 v[204:207], v181 offset:6144
	ds_read_b128 v[208:211], v181 offset:7168
	global_load_lds_dwordx4 v170, s[24:25]
	s_nop 0
	s_add_i32 m0, s23, 0xe000
	s_nop 0
	global_load_lds_dwordx4 v172, s[24:25]
	s_waitcnt vmcnt(8)
	s_waitcnt lgkmcnt(0)
	s_barrier
	s_setprio 1
	s_waitcnt lgkmcnt(0)
	v_mfma_f32_16x16x32_bf16 v[122:125], v[130:133], v[162:165], v[122:125]
	v_mfma_f32_16x16x32_bf16 v[118:121], v[138:141], v[162:165], v[118:121]
	v_mfma_f32_16x16x32_bf16 v[110:113], v[130:133], v[188:191], v[110:113]
	v_mfma_f32_16x16x32_bf16 v[102:105], v[138:141], v[188:191], v[102:105]
	v_mfma_f32_16x16x32_bf16 v[94:97], v[130:133], v[196:199], v[94:97]
	v_mfma_f32_16x16x32_bf16 v[86:89], v[138:141], v[196:199], v[86:89]
	v_mfma_f32_16x16x32_bf16 v[78:81], v[130:133], v[204:207], v[78:81]
	v_mfma_f32_16x16x32_bf16 v[70:73], v[138:141], v[204:207], v[70:73]
	v_mfma_f32_16x16x32_bf16 v[122:125], v[134:137], v[174:177], v[122:125]
	v_mfma_f32_16x16x32_bf16 v[118:121], v[142:145], v[174:177], v[118:121]
	v_mfma_f32_16x16x32_bf16 v[110:113], v[134:137], v[192:195], v[110:113]
	v_mfma_f32_16x16x32_bf16 v[102:105], v[142:145], v[192:195], v[102:105]
	v_mfma_f32_16x16x32_bf16 v[94:97], v[134:137], v[200:203], v[94:97]
	v_mfma_f32_16x16x32_bf16 v[86:89], v[142:145], v[200:203], v[86:89]
	v_mfma_f32_16x16x32_bf16 v[78:81], v[134:137], v[208:211], v[78:81]
	v_mfma_f32_16x16x32_bf16 v[70:73], v[142:145], v[208:211], v[70:73]
	s_setprio 0
	s_setprio 1
	v_mfma_f32_16x16x32_bf16 v[126:129], v[146:149], v[162:165], v[126:129]
	v_mfma_f32_16x16x32_bf16 v[114:117], v[154:157], v[162:165], v[114:117]
	v_mfma_f32_16x16x32_bf16 v[106:109], v[146:149], v[188:191], v[106:109]
	v_mfma_f32_16x16x32_bf16 v[98:101], v[154:157], v[188:191], v[98:101]
	v_mfma_f32_16x16x32_bf16 v[90:93], v[146:149], v[196:199], v[90:93]
	v_mfma_f32_16x16x32_bf16 v[82:85], v[154:157], v[196:199], v[82:85]
	v_mfma_f32_16x16x32_bf16 v[74:77], v[146:149], v[204:207], v[74:77]
	v_mfma_f32_16x16x32_bf16 v[66:69], v[154:157], v[204:207], v[66:69]
	v_mfma_f32_16x16x32_bf16 v[126:129], v[150:153], v[174:177], v[126:129]
	v_mfma_f32_16x16x32_bf16 v[114:117], v[158:161], v[174:177], v[114:117]
	v_mfma_f32_16x16x32_bf16 v[106:109], v[150:153], v[192:195], v[106:109]
	v_mfma_f32_16x16x32_bf16 v[98:101], v[158:161], v[192:195], v[98:101]
	v_mfma_f32_16x16x32_bf16 v[90:93], v[150:153], v[200:203], v[90:93]
	v_mfma_f32_16x16x32_bf16 v[82:85], v[158:161], v[200:203], v[82:85]
	v_mfma_f32_16x16x32_bf16 v[74:77], v[150:153], v[208:211], v[74:77]
	v_mfma_f32_16x16x32_bf16 v[66:69], v[158:161], v[208:211], v[66:69]
	s_setprio 0
	s_barrier
	s_add_i32 s53, s53, s28
	v_lshl_add_u64 v[178:179], s[14:15], 0, v[166:167]
	s_mov_b32 m0, s53
	ds_read_b128 v[162:165], v181 offset:16384
	ds_read_b128 v[174:177], v181 offset:17408
	ds_read_b128 v[188:191], v181 offset:18432
	ds_read_b128 v[192:195], v181 offset:19456
	ds_read_b128 v[196:199], v181 offset:20480
	ds_read_b128 v[200:203], v181 offset:21504
	ds_read_b128 v[204:207], v181 offset:22528
	ds_read_b128 v[208:211], v181 offset:23552
	global_load_lds_dwordx4 v166, s[14:15]
	s_add_i32 m0, s53, 0x2000
	s_add_u32 s64, s14, 0x80000
	v_lshl_add_u64 v[184:185], s[14:15], 0, v[168:169]
	s_addc_u32 s65, s15, 0
	s_add_i32 s53, s69, s28
	global_load_lds_dwordx4 v168, s[14:15]
	s_nop 0
	s_mov_b32 m0, s53
	v_lshl_add_u64 v[214:215], s[26:27], 0, v[168:169]
	global_load_lds_dwordx4 v166, s[64:65]
	s_nop 0
	s_add_i32 m0, s53, 0x2000
	s_nop 0
	global_load_lds_dwordx4 v168, s[64:65]
	v_lshl_add_u64 v[212:213], s[26:27], 0, v[166:167]
	s_mov_b32 m0, s23
	s_nop 0
	global_load_lds_dwordx4 v166, s[26:27]
	s_mov_b32 m0, s29
	s_nop 0
	global_load_lds_dwordx4 v168, s[26:27]
	s_waitcnt vmcnt(8)
	s_waitcnt lgkmcnt(0)
	s_barrier
; #define PG8_STAGE(bufoff, gbase, voff) do { _Pragma("unroll") for (int _i = 0; _i < 2; ++_i) \
;         __builtin_amdgcn_global_load_lds((const unsigned*)((const char*)(gbase) + (voff)[_i]), (LAS unsigned*)(lds + (bufoff) + ldsw + _i * 8192), 16, 0, 0); } while (0)
; #define PG8_LDA(dst, b, h) do { _Pragma("unroll") for (int m = 0; m < 4; ++m) _Pragma("unroll") for (int k = 0; k < 2; ++k) dst[m][k] = *(const LAS bf16x8*)(lds + PG8_SA(b, h) + aoff + m * 2048 + k * 1024); } while (0)
; #define PG8_LDB(dst, b, h) do { _Pragma("unroll") for (int n = 0; n < 2; ++n) _Pragma("unroll") for (int k = 0; k < 2; ++k) dst[n][k] = *(const LAS bf16x8*)(lds + PG8_SB(b, h) + boff + n * 2048 + k * 1024); } while (0)
; #define PG8_MMA(ai, bj, At, Bt) do { __builtin_amdgcn_s_setprio(1); _Pragma("unroll") for (int m = 0; m < 4; ++m) _Pragma("unroll") for (int n = 0; n < 2; ++n) _Pragma("unroll") for (int k = 0; k < 2; ++k) \
;         acc[ai][bj][m][n] = __builtin_amdgcn_mfma_f32_16x16x32_bf16(Bt[n][k], At[m][k], acc[ai][bj][m][n], 0, 0, 0); __builtin_amdgcn_s_setprio(0); } while (0)
; #define PG8_WAIT_V(n) asm volatile("s_waitcnt vmcnt(" #n ")" ::: "memory")
; #define PG8_WAIT_L(n) asm volatile("s_waitcnt lgkmcnt(" #n ")" ::: "memory")
; #define PG8_BAR __builtin_amdgcn_s_barrier()
; #define PG8_SCHED __builtin_amdgcn_sched_barrier(0)
; template <class Epi>
; __device__ __forceinline__ void gemm_phase(LAS unsigned char* lds, const Gemm g, const StaticOrder& S, const Epi& E) {
;     ...
;             PG8_WAIT_V(8); PG8_WAIT_L(0); PG8_BAR; PG8_MMA(1, 0, At, B0); PG8_MMA(1, 1, At, B1); PG8_BAR; PG8_SCHED;
;             PG8_LDB(B0, 1, 0); PG8_LDB(B1, 1, 1); PG8_SCHED; PG8_LDA(At, 1, 0); PG8_STAGE(PG8_SA(0, 1), a2 + hstepA, voffA);
;             PG8_WAIT_V(8); PG8_WAIT_L(0); PG8_BAR; PG8_MMA(0, 0, At, B0); PG8_MMA(0, 1, At, B1); PG8_BAR; PG8_SCHED;
	s_setprio 1
	s_waitcnt lgkmcnt(0)
	v_mfma_f32_16x16x32_bf16 v[62:65], v[130:133], v[162:165], v[62:65]
	v_mfma_f32_16x16x32_bf16 v[54:57], v[138:141], v[162:165], v[54:57]
	v_mfma_f32_16x16x32_bf16 v[46:49], v[130:133], v[188:191], v[46:49]
	v_mfma_f32_16x16x32_bf16 v[38:41], v[138:141], v[188:191], v[38:41]
	v_mfma_f32_16x16x32_bf16 v[30:33], v[130:133], v[196:199], v[30:33]
	v_mfma_f32_16x16x32_bf16 v[22:25], v[138:141], v[196:199], v[22:25]
	v_mfma_f32_16x16x32_bf16 v[14:17], v[130:133], v[204:207], v[14:17]
	v_mfma_f32_16x16x32_bf16 v[6:9], v[138:141], v[204:207], v[6:9]
	v_mfma_f32_16x16x32_bf16 v[62:65], v[134:137], v[174:177], v[62:65]
	v_mfma_f32_16x16x32_bf16 v[54:57], v[142:145], v[174:177], v[54:57]
	v_mfma_f32_16x16x32_bf16 v[46:49], v[134:137], v[192:195], v[46:49]
	v_mfma_f32_16x16x32_bf16 v[38:41], v[142:145], v[192:195], v[38:41]
	v_mfma_f32_16x16x32_bf16 v[30:33], v[134:137], v[200:203], v[30:33]
	v_mfma_f32_16x16x32_bf16 v[22:25], v[142:145], v[200:203], v[22:25]
	v_mfma_f32_16x16x32_bf16 v[14:17], v[134:137], v[208:211], v[14:17]
	v_mfma_f32_16x16x32_bf16 v[6:9], v[142:145], v[208:211], v[6:9]
	s_setprio 0
	s_setprio 1
	v_mfma_f32_16x16x32_bf16 v[58:61], v[146:149], v[162:165], v[58:61]
	v_mfma_f32_16x16x32_bf16 v[50:53], v[154:157], v[162:165], v[50:53]
	v_mfma_f32_16x16x32_bf16 v[42:45], v[146:149], v[188:191], v[42:45]
	v_mfma_f32_16x16x32_bf16 v[34:37], v[154:157], v[188:191], v[34:37]
	v_mfma_f32_16x16x32_bf16 v[26:29], v[146:149], v[196:199], v[26:29]
	v_mfma_f32_16x16x32_bf16 v[18:21], v[154:157], v[196:199], v[18:21]
	v_mfma_f32_16x16x32_bf16 v[10:13], v[146:149], v[204:207], v[10:13]
	v_mfma_f32_16x16x32_bf16 v[2:5], v[154:157], v[204:207], v[2:5]
	v_mfma_f32_16x16x32_bf16 v[58:61], v[150:153], v[174:177], v[58:61]
	v_mfma_f32_16x16x32_bf16 v[50:53], v[158:161], v[174:177], v[50:53]
	v_mfma_f32_16x16x32_bf16 v[42:45], v[150:153], v[192:195], v[42:45]
	v_mfma_f32_16x16x32_bf16 v[34:37], v[158:161], v[192:195], v[34:37]
	v_mfma_f32_16x16x32_bf16 v[26:29], v[150:153], v[200:203], v[26:29]
	v_mfma_f32_16x16x32_bf16 v[18:21], v[158:161], v[200:203], v[18:21]
	v_mfma_f32_16x16x32_bf16 v[10:13], v[150:153], v[208:211], v[10:13]
	v_mfma_f32_16x16x32_bf16 v[2:5], v[158:161], v[208:211], v[2:5]
	s_setprio 0
	s_barrier
	s_add_i32 s53, 0, 0x18000
	s_add_i32 s64, 0, 0x1c000
	v_add_u32_e32 v142, s53, v1
	v_add_u32_e32 v158, s64, v1
	ds_read_b128 v[130:133], v142
	ds_read_b128 v[134:137], v142 offset:1024
	ds_read_b128 v[138:141], v142 offset:2048
	ds_read_b128 v[142:145], v142 offset:3072
	ds_read_b128 v[146:149], v158
	ds_read_b128 v[150:153], v158 offset:1024
	ds_read_b128 v[154:157], v158 offset:2048
	ds_read_b128 v[158:161], v158 offset:3072
	s_add_u32 s26, s26, 0x80000
	s_addc_u32 s27, s27, 0
	s_mov_b32 m0, s30
	s_nop 0
	ds_read_b128 v[162:165], v181 offset:32768
	ds_read_b128 v[174:177], v181 offset:33792
	ds_read_b128 v[188:191], v181 offset:34816
	ds_read_b128 v[192:195], v181 offset:35840
	ds_read_b128 v[196:199], v181 offset:36864
	ds_read_b128 v[200:203], v181 offset:37888
	ds_read_b128 v[204:207], v181 offset:38912
	ds_read_b128 v[208:211], v181 offset:39936
	global_load_lds_dwordx4 v166, s[26:27]
	s_nop 0
	s_mov_b32 m0, s31
	s_nop 0
	global_load_lds_dwordx4 v168, s[26:27]
	s_waitcnt vmcnt(8)
	s_waitcnt lgkmcnt(0)
	s_barrier
	s_setprio 1
	s_waitcnt lgkmcnt(0)
	v_mfma_f32_16x16x32_bf16 v[122:125], v[130:133], v[162:165], v[122:125]
	v_mfma_f32_16x16x32_bf16 v[118:121], v[138:141], v[162:165], v[118:121]
	v_mfma_f32_16x16x32_bf16 v[110:113], v[130:133], v[188:191], v[110:113]
	v_mfma_f32_16x16x32_bf16 v[102:105], v[138:141], v[188:191], v[102:105]
	v_mfma_f32_16x16x32_bf16 v[94:97], v[130:133], v[196:199], v[94:97]
	v_mfma_f32_16x16x32_bf16 v[86:89], v[138:141], v[196:199], v[86:89]
	v_mfma_f32_16x16x32_bf16 v[78:81], v[130:133], v[204:207], v[78:81]
	v_mfma_f32_16x16x32_bf16 v[70:73], v[138:141], v[204:207], v[70:73]
	v_mfma_f32_16x16x32_bf16 v[122:125], v[134:137], v[174:177], v[122:125]
	v_mfma_f32_16x16x32_bf16 v[118:121], v[142:145], v[174:177], v[118:121]
	v_mfma_f32_16x16x32_bf16 v[110:113], v[134:137], v[192:195], v[110:113]
	v_mfma_f32_16x16x32_bf16 v[102:105], v[142:145], v[192:195], v[102:105]
	v_mfma_f32_16x16x32_bf16 v[94:97], v[134:137], v[200:203], v[94:97]
	v_mfma_f32_16x16x32_bf16 v[86:89], v[142:145], v[200:203], v[86:89]
	v_mfma_f32_16x16x32_bf16 v[78:81], v[134:137], v[208:211], v[78:81]
	v_mfma_f32_16x16x32_bf16 v[70:73], v[142:145], v[208:211], v[70:73]
	s_setprio 0
	s_setprio 1
	v_mfma_f32_16x16x32_bf16 v[126:129], v[146:149], v[162:165], v[126:129]
	v_mfma_f32_16x16x32_bf16 v[114:117], v[154:157], v[162:165], v[114:117]
	v_mfma_f32_16x16x32_bf16 v[106:109], v[146:149], v[188:191], v[106:109]
	v_mfma_f32_16x16x32_bf16 v[98:101], v[154:157], v[188:191], v[98:101]
	v_mfma_f32_16x16x32_bf16 v[90:93], v[146:149], v[196:199], v[90:93]
	v_mfma_f32_16x16x32_bf16 v[82:85], v[154:157], v[196:199], v[82:85]
	v_mfma_f32_16x16x32_bf16 v[74:77], v[146:149], v[204:207], v[74:77]
	v_mfma_f32_16x16x32_bf16 v[66:69], v[154:157], v[204:207], v[66:69]
	v_mfma_f32_16x16x32_bf16 v[126:129], v[150:153], v[174:177], v[126:129]
	v_mfma_f32_16x16x32_bf16 v[114:117], v[158:161], v[174:177], v[114:117]
	v_mfma_f32_16x16x32_bf16 v[106:109], v[150:153], v[192:195], v[106:109]
	v_mfma_f32_16x16x32_bf16 v[98:101], v[158:161], v[192:195], v[98:101]
	v_mfma_f32_16x16x32_bf16 v[90:93], v[150:153], v[200:203], v[90:93]
	v_mfma_f32_16x16x32_bf16 v[82:85], v[158:161], v[200:203], v[82:85]
	v_mfma_f32_16x16x32_bf16 v[74:77], v[150:153], v[208:211], v[74:77]
	v_mfma_f32_16x16x32_bf16 v[66:69], v[158:161], v[208:211], v[66:69]
	s_setprio 0
	s_barrier
; #define PG8_STAGE(bufoff, gbase, voff) do { _Pragma("unroll") for (int _i = 0; _i < 2; ++_i) \
;         __builtin_amdgcn_global_load_lds((const unsigned*)((const char*)(gbase) + (voff)[_i]), (LAS unsigned*)(lds + (bufoff) + ldsw + _i * 8192), 16, 0, 0); } while (0)
; #define PG8_LDA(dst, b, h) do { _Pragma("unroll") for (int m = 0; m < 4; ++m) _Pragma("unroll") for (int k = 0; k < 2; ++k) dst[m][k] = *(const LAS bf16x8*)(lds + PG8_SA(b, h) + aoff + m * 2048 + k * 1024); } while (0)
; #define PG8_MMA(ai, bj, At, Bt) do { __builtin_amdgcn_s_setprio(1); _Pragma("unroll") for (int m = 0; m < 4; ++m) _Pragma("unroll") for (int n = 0; n < 2; ++n) _Pragma("unroll") for (int k = 0; k < 2; ++k) \
;         acc[ai][bj][m][n] = __builtin_amdgcn_mfma_f32_16x16x32_bf16(Bt[n][k], At[m][k], acc[ai][bj][m][n], 0, 0, 0); __builtin_amdgcn_s_setprio(0); } while (0)
; #define PG8_WAIT_V(n) asm volatile("s_waitcnt vmcnt(" #n ")" ::: "memory")
; #define PG8_WAIT_L(n) asm volatile("s_waitcnt lgkmcnt(" #n ")" ::: "memory")
; #define PG8_BAR __builtin_amdgcn_s_barrier()
; #define PG8_SCHED __builtin_amdgcn_sched_barrier(0)
; template <class Epi>
; __device__ __forceinline__ void gemm_phase(LAS unsigned char* lds, const Gemm g, const StaticOrder& S, const Epi& E) {
;     ...
;             PG8_LDA(At, 1, 1); PG8_STAGE(PG8_SB(1, 0), b3, voffB); PG8_STAGE(PG8_SB(1, 1), b3 + hstepB, voffB); PG8_STAGE(PG8_SA(1, 0), a3, voffA);
;             PG8_WAIT_V(8); PG8_WAIT_L(0); PG8_BAR; PG8_MMA(1, 0, At, B0); PG8_MMA(1, 1, At, B1); PG8_BAR; PG8_SCHED;
;         }
;         if (wr == 0) PG8_BAR;
	s_add_i32 s26, s53, s28
	v_lshl_add_u64 v[178:179], v[178:179], 0, s[84:85]
	s_mov_b32 m0, s26
	ds_read_b128 v[162:165], v181 offset:49152
	ds_read_b128 v[174:177], v181 offset:50176
	ds_read_b128 v[188:191], v181 offset:51200
	ds_read_b128 v[192:195], v181 offset:52224
	ds_read_b128 v[196:199], v181 offset:53248
	ds_read_b128 v[200:203], v181 offset:54272
	ds_read_b128 v[204:207], v181 offset:55296
	ds_read_b128 v[208:211], v181 offset:56320
	global_load_lds_dwordx4 v[178:179], off
	s_add_i32 m0, s26, 0x2000
	s_add_u32 s14, s14, 0x80080
	v_lshl_add_u64 v[178:179], v[184:185], 0, s[84:85]
	s_addc_u32 s15, s15, 0
	s_add_i32 s26, s64, s28
	global_load_lds_dwordx4 v[178:179], off
	s_nop 0
	s_mov_b32 m0, s26
	s_nop 0
	global_load_lds_dwordx4 v166, s[14:15]
	s_nop 0
	s_add_i32 m0, s26, 0x2000
	s_nop 0
	global_load_lds_dwordx4 v168, s[14:15]
	v_lshl_add_u64 v[178:179], v[212:213], 0, s[84:85]
	s_mov_b32 m0, s35
	s_nop 0
	global_load_lds_dwordx4 v[178:179], off
	v_lshl_add_u64 v[178:179], v[214:215], 0, s[84:85]
	s_mov_b32 m0, s42
	s_nop 0
	global_load_lds_dwordx4 v[178:179], off
	s_waitcnt vmcnt(8)
	s_waitcnt lgkmcnt(0)
	s_barrier
	s_setprio 1
	s_waitcnt lgkmcnt(0)
	v_mfma_f32_16x16x32_bf16 v[62:65], v[130:133], v[162:165], v[62:65]
	v_mfma_f32_16x16x32_bf16 v[54:57], v[138:141], v[162:165], v[54:57]
	v_mfma_f32_16x16x32_bf16 v[46:49], v[130:133], v[188:191], v[46:49]
	v_mfma_f32_16x16x32_bf16 v[38:41], v[138:141], v[188:191], v[38:41]
	v_mfma_f32_16x16x32_bf16 v[30:33], v[130:133], v[196:199], v[30:33]
	v_mfma_f32_16x16x32_bf16 v[22:25], v[138:141], v[196:199], v[22:25]
	v_mfma_f32_16x16x32_bf16 v[14:17], v[130:133], v[204:207], v[14:17]
	v_mfma_f32_16x16x32_bf16 v[6:9], v[138:141], v[204:207], v[6:9]
	v_mfma_f32_16x16x32_bf16 v[62:65], v[134:137], v[174:177], v[62:65]
	v_mfma_f32_16x16x32_bf16 v[54:57], v[142:145], v[174:177], v[54:57]
	v_mfma_f32_16x16x32_bf16 v[46:49], v[134:137], v[192:195], v[46:49]
	v_mfma_f32_16x16x32_bf16 v[38:41], v[142:145], v[192:195], v[38:41]
	v_mfma_f32_16x16x32_bf16 v[30:33], v[134:137], v[200:203], v[30:33]
	v_mfma_f32_16x16x32_bf16 v[22:25], v[142:145], v[200:203], v[22:25]
	v_mfma_f32_16x16x32_bf16 v[14:17], v[134:137], v[208:211], v[14:17]
	v_mfma_f32_16x16x32_bf16 v[6:9], v[142:145], v[208:211], v[6:9]
	s_setprio 0
	s_setprio 1
	v_mfma_f32_16x16x32_bf16 v[58:61], v[146:149], v[162:165], v[58:61]
	v_mfma_f32_16x16x32_bf16 v[50:53], v[154:157], v[162:165], v[50:53]
	v_mfma_f32_16x16x32_bf16 v[42:45], v[146:149], v[188:191], v[42:45]
	v_mfma_f32_16x16x32_bf16 v[34:37], v[154:157], v[188:191], v[34:37]
	v_mfma_f32_16x16x32_bf16 v[26:29], v[146:149], v[196:199], v[26:29]
	v_mfma_f32_16x16x32_bf16 v[18:21], v[154:157], v[196:199], v[18:21]
	v_mfma_f32_16x16x32_bf16 v[10:13], v[146:149], v[204:207], v[10:13]
	v_mfma_f32_16x16x32_bf16 v[2:5], v[154:157], v[204:207], v[2:5]
	v_mfma_f32_16x16x32_bf16 v[58:61], v[150:153], v[174:177], v[58:61]
	v_mfma_f32_16x16x32_bf16 v[50:53], v[158:161], v[174:177], v[50:53]
	v_mfma_f32_16x16x32_bf16 v[42:45], v[150:153], v[192:195], v[42:45]
	v_mfma_f32_16x16x32_bf16 v[34:37], v[158:161], v[192:195], v[34:37]
	v_mfma_f32_16x16x32_bf16 v[26:29], v[150:153], v[200:203], v[26:29]
	v_mfma_f32_16x16x32_bf16 v[18:21], v[158:161], v[200:203], v[18:21]
	v_mfma_f32_16x16x32_bf16 v[10:13], v[150:153], v[208:211], v[10:13]
	v_mfma_f32_16x16x32_bf16 v[2:5], v[158:161], v[208:211], v[2:5]
	s_setprio 0
	s_barrier
	s_add_i32 s41, s41, 2
	s_add_u32 s24, s24, 0x100
	s_addc_u32 s25, s25, 0
	s_add_u32 s40, s40, 0x100
	s_addc_u32 s52, s52, 0
	s_cmp_gt_u32 s41, 29
	s_cbranch_scc0 .LBB0_1324
	s_and_b64 vcc, exec, s[10:11]
	s_cbranch_vccz .LBB0_1327
	s_barrier

; #define PG8_STAGE(bufoff, gbase, voff) do { _Pragma("unroll") for (int _i = 0; _i < 2; ++_i) \
;         __builtin_amdgcn_global_load_lds((const unsigned*)((const char*)(gbase) + (voff)[_i]), (LAS unsigned*)(lds + (bufoff) + ldsw + _i * 8192), 16, 0, 0); } while (0)
; #define PG8_LDA(dst, b, h) do { _Pragma("unroll") for (int m = 0; m < 4; ++m) _Pragma("unroll") for (int k = 0; k < 2; ++k) dst[m][k] = *(const LAS bf16x8*)(lds + PG8_SA(b, h) + aoff + m * 2048 + k * 1024); } while (0)
; #define PG8_LDB(dst, b, h) do { _Pragma("unroll") for (int n = 0; n < 2; ++n) _Pragma("unroll") for (int k = 0; k < 2; ++k) dst[n][k] = *(const LAS bf16x8*)(lds + PG8_SB(b, h) + boff + n * 2048 + k * 1024); } while (0)
; #define PG8_MMA(ai, bj, At, Bt) do { __builtin_amdgcn_s_setprio(1); _Pragma("unroll") for (int m = 0; m < 4; ++m) _Pragma("unroll") for (int n = 0; n < 2; ++n) _Pragma("unroll") for (int k = 0; k < 2; ++k) \
;         acc[ai][bj][m][n] = __builtin_amdgcn_mfma_f32_16x16x32_bf16(Bt[n][k], At[m][k], acc[ai][bj][m][n], 0, 0, 0); __builtin_amdgcn_s_setprio(0); } while (0)
; #define PG8_WAIT_V(n) asm volatile("s_waitcnt vmcnt(" #n ")" ::: "memory")
; #define PG8_WAIT_L(n) asm volatile("s_waitcnt lgkmcnt(" #n ")" ::: "memory")
; #define PG8_BAR __builtin_amdgcn_s_barrier()
; #define PG8_SCHED __builtin_amdgcn_sched_barrier(0)
; template <class Epi>
; __device__ __forceinline__ void gemm_phase(LAS unsigned char* lds, const Gemm g, const StaticOrder& S, const Epi& E) {
;     ...
;             const bool last = (t == nt - 2);
;             const char* a1 = cA + (size_t)(t + 1) * kstep;
;             const char* a2 = last ? nA : cA + (size_t)(t + 2) * kstep; const char* b2 = last ? nB : cB + (size_t)(t + 2) * kstep;
;             const char* a3 = a2 + kstep; const char* b3 = b2 + kstep;
;             PG8_LDB(B0, 0, 0); PG8_LDB(B1, 0, 1); PG8_SCHED; PG8_LDA(At, 0, 0); PG8_STAGE(PG8_SA(1, 1), a1 + hstepA, voffA);
;             PG8_WAIT_V(8); PG8_WAIT_L(0); PG8_BAR; PG8_MMA(0, 0, At, B0); PG8_MMA(0, 1, At, B1); PG8_BAR; PG8_SCHED;
;             PG8_LDA(At, 0, 1); PG8_STAGE(PG8_SB(0, 0), b2, voffB); PG8_STAGE(PG8_SB(0, 1), b2 + hstepB, voffB); PG8_STAGE(PG8_SA(0, 0), a2, voffA);
;             PG8_WAIT_V(8); PG8_WAIT_L(0); PG8_BAR; PG8_MMA(1, 0, At, B0); PG8_MMA(1, 1, At, B1); PG8_BAR; PG8_SCHED;
.LBB0_1412:
	s_add_u32 s14, s22, 0xfff80080
	s_addc_u32 s15, s23, -1
	s_add_i32 s41, 0, 0x10000
	s_cmp_eq_u32 s64, 28
	s_cselect_b32 s25, s3, s15
	s_cselect_b32 s24, s7, s14
	s_cselect_b32 s15, s13, s63
	s_cselect_b32 s14, s17, s40
	s_add_i32 s65, 0, 0x14000
	v_add_u32_e32 v142, s41, v1
	v_add_u32_e32 v163, s65, v1
	ds_read_b128 v[130:133], v142
	ds_read_b128 v[134:137], v142 offset:1024
	ds_read_b128 v[138:141], v142 offset:2048
	ds_read_b128 v[142:145], v142 offset:3072
	ds_read_b128 v[158:161], v163
	ds_read_b128 v[164:167], v163 offset:1024
	ds_read_b128 v[168:171], v163 offset:2048
	ds_read_b128 v[172:175], v163 offset:3072
	s_nop 0
	s_add_i32 m0, s30, 0xc000
	ds_read_b128 v[176:179], v162
	ds_read_b128 v[188:191], v162 offset:1024
	ds_read_b128 v[192:195], v162 offset:2048
	ds_read_b128 v[196:199], v162 offset:3072
	ds_read_b128 v[200:203], v162 offset:4096
	ds_read_b128 v[204:207], v162 offset:5120
	ds_read_b128 v[208:211], v162 offset:6144
	ds_read_b128 v[212:215], v162 offset:7168
	global_load_lds_dwordx4 v154, s[22:23]
	s_nop 0
	s_add_i32 m0, s30, 0xe000
	s_nop 0
	global_load_lds_dwordx4 v156, s[22:23]
	s_waitcnt vmcnt(8)
	s_waitcnt lgkmcnt(0)
	s_barrier
	s_setprio 1
	s_waitcnt lgkmcnt(0)
	v_mfma_f32_16x16x32_bf16 v[126:129], v[130:133], v[176:179], v[126:129]
	v_mfma_f32_16x16x32_bf16 v[122:125], v[138:141], v[176:179], v[122:125]
	v_mfma_f32_16x16x32_bf16 v[118:121], v[130:133], v[192:195], v[118:121]
	v_mfma_f32_16x16x32_bf16 v[110:113], v[138:141], v[192:195], v[110:113]
	v_mfma_f32_16x16x32_bf16 v[102:105], v[130:133], v[200:203], v[102:105]
	v_mfma_f32_16x16x32_bf16 v[94:97], v[138:141], v[200:203], v[94:97]
	v_mfma_f32_16x16x32_bf16 v[86:89], v[130:133], v[208:211], v[86:89]
	v_mfma_f32_16x16x32_bf16 v[78:81], v[138:141], v[208:211], v[78:81]
	v_mfma_f32_16x16x32_bf16 v[126:129], v[134:137], v[188:191], v[126:129]
	v_mfma_f32_16x16x32_bf16 v[122:125], v[142:145], v[188:191], v[122:125]
	v_mfma_f32_16x16x32_bf16 v[118:121], v[134:137], v[196:199], v[118:121]
	v_mfma_f32_16x16x32_bf16 v[110:113], v[142:145], v[196:199], v[110:113]
	v_mfma_f32_16x16x32_bf16 v[102:105], v[134:137], v[204:207], v[102:105]
	v_mfma_f32_16x16x32_bf16 v[94:97], v[142:145], v[204:207], v[94:97]
	v_mfma_f32_16x16x32_bf16 v[86:89], v[134:137], v[212:215], v[86:89]
	v_mfma_f32_16x16x32_bf16 v[78:81], v[142:145], v[212:215], v[78:81]
	s_setprio 0
	s_setprio 1
	v_mfma_f32_16x16x32_bf16 v[114:117], v[158:161], v[176:179], v[114:117]
	v_mfma_f32_16x16x32_bf16 v[106:109], v[168:171], v[176:179], v[106:109]
	v_mfma_f32_16x16x32_bf16 v[98:101], v[158:161], v[192:195], v[98:101]
	v_mfma_f32_16x16x32_bf16 v[90:93], v[168:171], v[192:195], v[90:93]
	v_mfma_f32_16x16x32_bf16 v[82:85], v[158:161], v[200:203], v[82:85]
	v_mfma_f32_16x16x32_bf16 v[74:77], v[168:171], v[200:203], v[74:77]
	v_mfma_f32_16x16x32_bf16 v[70:73], v[158:161], v[208:211], v[70:73]
	v_mfma_f32_16x16x32_bf16 v[66:69], v[168:171], v[208:211], v[66:69]
	v_mfma_f32_16x16x32_bf16 v[114:117], v[164:167], v[188:191], v[114:117]
	v_mfma_f32_16x16x32_bf16 v[106:109], v[172:175], v[188:191], v[106:109]
	v_mfma_f32_16x16x32_bf16 v[98:101], v[164:167], v[196:199], v[98:101]
	v_mfma_f32_16x16x32_bf16 v[90:93], v[172:175], v[196:199], v[90:93]
	v_mfma_f32_16x16x32_bf16 v[82:85], v[164:167], v[204:207], v[82:85]
	v_mfma_f32_16x16x32_bf16 v[74:77], v[172:175], v[204:207], v[74:77]
	v_mfma_f32_16x16x32_bf16 v[70:73], v[164:167], v[212:215], v[70:73]
	v_mfma_f32_16x16x32_bf16 v[66:69], v[172:175], v[212:215], v[66:69]
	s_setprio 0
	s_barrier
	s_add_i32 s41, s41, s28
	v_lshl_add_u64 v[184:185], s[14:15], 0, v[150:151]
	s_mov_b32 m0, s41
	ds_read_b128 v[176:179], v162 offset:16384
	ds_read_b128 v[188:191], v162 offset:17408
	ds_read_b128 v[192:195], v162 offset:18432
	ds_read_b128 v[196:199], v162 offset:19456
	ds_read_b128 v[200:203], v162 offset:20480
	ds_read_b128 v[204:207], v162 offset:21504
	ds_read_b128 v[208:211], v162 offset:22528
	ds_read_b128 v[212:215], v162 offset:23552
	global_load_lds_dwordx4 v150, s[14:15]
	s_add_i32 m0, s41, 0x2000
	s_add_u32 s68, s14, 0x80000
	v_lshl_add_u64 v[216:217], s[14:15], 0, v[146:147]
	s_addc_u32 s69, s15, 0
	s_add_i32 s41, s65, s28
	global_load_lds_dwordx4 v146, s[14:15]
	s_nop 0
	s_mov_b32 m0, s41
	v_lshl_add_u64 v[220:221], s[24:25], 0, v[148:149]
	global_load_lds_dwordx4 v150, s[68:69]
	s_nop 0
	s_add_i32 m0, s41, 0x2000
	s_nop 0
	global_load_lds_dwordx4 v146, s[68:69]
	v_lshl_add_u64 v[218:219], s[24:25], 0, v[152:153]
	s_mov_b32 m0, s30
	s_nop 0
	global_load_lds_dwordx4 v152, s[24:25]
	s_mov_b32 m0, s31
	s_nop 0
	global_load_lds_dwordx4 v148, s[24:25]
	s_waitcnt vmcnt(8)
	s_waitcnt lgkmcnt(0)
	s_barrier
; #define PG8_STAGE(bufoff, gbase, voff) do { _Pragma("unroll") for (int _i = 0; _i < 2; ++_i) \
;         __builtin_amdgcn_global_load_lds((const unsigned*)((const char*)(gbase) + (voff)[_i]), (LAS unsigned*)(lds + (bufoff) + ldsw + _i * 8192), 16, 0, 0); } while (0)
; #define PG8_LDA(dst, b, h) do { _Pragma("unroll") for (int m = 0; m < 4; ++m) _Pragma("unroll") for (int k = 0; k < 2; ++k) dst[m][k] = *(const LAS bf16x8*)(lds + PG8_SA(b, h) + aoff + m * 2048 + k * 1024); } while (0)
; #define PG8_LDB(dst, b, h) do { _Pragma("unroll") for (int n = 0; n < 2; ++n) _Pragma("unroll") for (int k = 0; k < 2; ++k) dst[n][k] = *(const LAS bf16x8*)(lds + PG8_SB(b, h) + boff + n * 2048 + k * 1024); } while (0)
; #define PG8_MMA(ai, bj, At, Bt) do { __builtin_amdgcn_s_setprio(1); _Pragma("unroll") for (int m = 0; m < 4; ++m) _Pragma("unroll") for (int n = 0; n < 2; ++n) _Pragma("unroll") for (int k = 0; k < 2; ++k) \
;         acc[ai][bj][m][n] = __builtin_amdgcn_mfma_f32_16x16x32_bf16(Bt[n][k], At[m][k], acc[ai][bj][m][n], 0, 0, 0); __builtin_amdgcn_s_setprio(0); } while (0)
; #define PG8_WAIT_V(n) asm volatile("s_waitcnt vmcnt(" #n ")" ::: "memory")
; #define PG8_WAIT_L(n) asm volatile("s_waitcnt lgkmcnt(" #n ")" ::: "memory")
; #define PG8_BAR __builtin_amdgcn_s_barrier()
; #define PG8_SCHED __builtin_amdgcn_sched_barrier(0)
; template <class Epi>
; __device__ __forceinline__ void gemm_phase(LAS unsigned char* lds, const Gemm g, const StaticOrder& S, const Epi& E) {
;     ...
;             PG8_WAIT_V(8); PG8_WAIT_L(0); PG8_BAR; PG8_MMA(1, 0, At, B0); PG8_MMA(1, 1, At, B1); PG8_BAR; PG8_SCHED;
;             PG8_LDB(B0, 1, 0); PG8_LDB(B1, 1, 1); PG8_SCHED; PG8_LDA(At, 1, 0); PG8_STAGE(PG8_SA(0, 1), a2 + hstepA, voffA);
;             PG8_WAIT_V(8); PG8_WAIT_L(0); PG8_BAR; PG8_MMA(0, 0, At, B0); PG8_MMA(0, 1, At, B1); PG8_BAR; PG8_SCHED;
	s_setprio 1
	s_waitcnt lgkmcnt(0)
	v_mfma_f32_16x16x32_bf16 v[62:65], v[130:133], v[176:179], v[62:65]
	v_mfma_f32_16x16x32_bf16 v[58:61], v[138:141], v[176:179], v[58:61]
	v_mfma_f32_16x16x32_bf16 v[54:57], v[130:133], v[192:195], v[54:57]
	v_mfma_f32_16x16x32_bf16 v[46:49], v[138:141], v[192:195], v[46:49]
	v_mfma_f32_16x16x32_bf16 v[38:41], v[130:133], v[200:203], v[38:41]
	v_mfma_f32_16x16x32_bf16 v[30:33], v[138:141], v[200:203], v[30:33]
	v_mfma_f32_16x16x32_bf16 v[22:25], v[130:133], v[208:211], v[22:25]
	v_mfma_f32_16x16x32_bf16 v[14:17], v[138:141], v[208:211], v[14:17]
	v_mfma_f32_16x16x32_bf16 v[62:65], v[134:137], v[188:191], v[62:65]
	v_mfma_f32_16x16x32_bf16 v[58:61], v[142:145], v[188:191], v[58:61]
	v_mfma_f32_16x16x32_bf16 v[54:57], v[134:137], v[196:199], v[54:57]
	v_mfma_f32_16x16x32_bf16 v[46:49], v[142:145], v[196:199], v[46:49]
	v_mfma_f32_16x16x32_bf16 v[38:41], v[134:137], v[204:207], v[38:41]
	v_mfma_f32_16x16x32_bf16 v[30:33], v[142:145], v[204:207], v[30:33]
	v_mfma_f32_16x16x32_bf16 v[22:25], v[134:137], v[212:215], v[22:25]
	v_mfma_f32_16x16x32_bf16 v[14:17], v[142:145], v[212:215], v[14:17]
	s_setprio 0
	s_setprio 1
	v_mfma_f32_16x16x32_bf16 v[50:53], v[158:161], v[176:179], v[50:53]
	v_mfma_f32_16x16x32_bf16 v[42:45], v[168:171], v[176:179], v[42:45]
	v_mfma_f32_16x16x32_bf16 v[34:37], v[158:161], v[192:195], v[34:37]
	v_mfma_f32_16x16x32_bf16 v[26:29], v[168:171], v[192:195], v[26:29]
	v_mfma_f32_16x16x32_bf16 v[18:21], v[158:161], v[200:203], v[18:21]
	v_mfma_f32_16x16x32_bf16 v[10:13], v[168:171], v[200:203], v[10:13]
	v_mfma_f32_16x16x32_bf16 v[6:9], v[158:161], v[208:211], v[6:9]
	v_mfma_f32_16x16x32_bf16 v[2:5], v[168:171], v[208:211], v[2:5]
	v_mfma_f32_16x16x32_bf16 v[50:53], v[164:167], v[188:191], v[50:53]
	v_mfma_f32_16x16x32_bf16 v[42:45], v[172:175], v[188:191], v[42:45]
	v_mfma_f32_16x16x32_bf16 v[34:37], v[164:167], v[196:199], v[34:37]
	v_mfma_f32_16x16x32_bf16 v[26:29], v[172:175], v[196:199], v[26:29]
	v_mfma_f32_16x16x32_bf16 v[18:21], v[164:167], v[204:207], v[18:21]
	v_mfma_f32_16x16x32_bf16 v[10:13], v[172:175], v[204:207], v[10:13]
	v_mfma_f32_16x16x32_bf16 v[6:9], v[164:167], v[212:215], v[6:9]
	v_mfma_f32_16x16x32_bf16 v[2:5], v[172:175], v[212:215], v[2:5]
	s_setprio 0
	s_barrier
	s_add_i32 s41, 0, 0x18000
	s_add_i32 s65, 0, 0x1c000
	v_add_u32_e32 v142, s41, v1
	v_add_u32_e32 v163, s65, v1
	ds_read_b128 v[130:133], v142
	ds_read_b128 v[134:137], v142 offset:1024
	ds_read_b128 v[138:141], v142 offset:2048
	ds_read_b128 v[142:145], v142 offset:3072
	ds_read_b128 v[158:161], v163
	ds_read_b128 v[164:167], v163 offset:1024
	ds_read_b128 v[168:171], v163 offset:2048
	ds_read_b128 v[172:175], v163 offset:3072
	s_add_u32 s24, s24, 0x80000
	s_addc_u32 s25, s25, 0
	s_mov_b32 m0, s33
	s_nop 0
	ds_read_b128 v[176:179], v162 offset:32768
	ds_read_b128 v[188:191], v162 offset:33792
	ds_read_b128 v[192:195], v162 offset:34816
	ds_read_b128 v[196:199], v162 offset:35840
	ds_read_b128 v[200:203], v162 offset:36864
	ds_read_b128 v[204:207], v162 offset:37888
	ds_read_b128 v[208:211], v162 offset:38912
	ds_read_b128 v[212:215], v162 offset:39936
	global_load_lds_dwordx4 v152, s[24:25]
	s_nop 0
	s_mov_b32 m0, s34
	s_nop 0
	global_load_lds_dwordx4 v148, s[24:25]
	s_waitcnt vmcnt(8)
	s_waitcnt lgkmcnt(0)
	s_barrier
	s_setprio 1
	s_waitcnt lgkmcnt(0)
	v_mfma_f32_16x16x32_bf16 v[126:129], v[130:133], v[176:179], v[126:129]
	v_mfma_f32_16x16x32_bf16 v[122:125], v[138:141], v[176:179], v[122:125]
	v_mfma_f32_16x16x32_bf16 v[118:121], v[130:133], v[192:195], v[118:121]
	v_mfma_f32_16x16x32_bf16 v[110:113], v[138:141], v[192:195], v[110:113]
	v_mfma_f32_16x16x32_bf16 v[102:105], v[130:133], v[200:203], v[102:105]
	v_mfma_f32_16x16x32_bf16 v[94:97], v[138:141], v[200:203], v[94:97]
	v_mfma_f32_16x16x32_bf16 v[86:89], v[130:133], v[208:211], v[86:89]
	v_mfma_f32_16x16x32_bf16 v[78:81], v[138:141], v[208:211], v[78:81]
	v_mfma_f32_16x16x32_bf16 v[126:129], v[134:137], v[188:191], v[126:129]
	v_mfma_f32_16x16x32_bf16 v[122:125], v[142:145], v[188:191], v[122:125]
	v_mfma_f32_16x16x32_bf16 v[118:121], v[134:137], v[196:199], v[118:121]
	v_mfma_f32_16x16x32_bf16 v[110:113], v[142:145], v[196:199], v[110:113]
	v_mfma_f32_16x16x32_bf16 v[102:105], v[134:137], v[204:207], v[102:105]
	v_mfma_f32_16x16x32_bf16 v[94:97], v[142:145], v[204:207], v[94:97]
	v_mfma_f32_16x16x32_bf16 v[86:89], v[134:137], v[212:215], v[86:89]
	v_mfma_f32_16x16x32_bf16 v[78:81], v[142:145], v[212:215], v[78:81]
	s_setprio 0
	s_setprio 1
	v_mfma_f32_16x16x32_bf16 v[114:117], v[158:161], v[176:179], v[114:117]
	v_mfma_f32_16x16x32_bf16 v[106:109], v[168:171], v[176:179], v[106:109]
	v_mfma_f32_16x16x32_bf16 v[98:101], v[158:161], v[192:195], v[98:101]
	v_mfma_f32_16x16x32_bf16 v[90:93], v[168:171], v[192:195], v[90:93]
	v_mfma_f32_16x16x32_bf16 v[82:85], v[158:161], v[200:203], v[82:85]
	v_mfma_f32_16x16x32_bf16 v[74:77], v[168:171], v[200:203], v[74:77]
	v_mfma_f32_16x16x32_bf16 v[70:73], v[158:161], v[208:211], v[70:73]
	v_mfma_f32_16x16x32_bf16 v[66:69], v[168:171], v[208:211], v[66:69]
	v_mfma_f32_16x16x32_bf16 v[114:117], v[164:167], v[188:191], v[114:117]
	v_mfma_f32_16x16x32_bf16 v[106:109], v[172:175], v[188:191], v[106:109]
	v_mfma_f32_16x16x32_bf16 v[98:101], v[164:167], v[196:199], v[98:101]
	v_mfma_f32_16x16x32_bf16 v[90:93], v[172:175], v[196:199], v[90:93]
	v_mfma_f32_16x16x32_bf16 v[82:85], v[164:167], v[204:207], v[82:85]
	v_mfma_f32_16x16x32_bf16 v[74:77], v[172:175], v[204:207], v[74:77]
	v_mfma_f32_16x16x32_bf16 v[70:73], v[164:167], v[212:215], v[70:73]
	v_mfma_f32_16x16x32_bf16 v[66:69], v[172:175], v[212:215], v[66:69]
	s_setprio 0
	s_barrier
; #define PG8_STAGE(bufoff, gbase, voff) do { _Pragma("unroll") for (int _i = 0; _i < 2; ++_i) \
;         __builtin_amdgcn_global_load_lds((const unsigned*)((const char*)(gbase) + (voff)[_i]), (LAS unsigned*)(lds + (bufoff) + ldsw + _i * 8192), 16, 0, 0); } while (0)
; #define PG8_LDA(dst, b, h) do { _Pragma("unroll") for (int m = 0; m < 4; ++m) _Pragma("unroll") for (int k = 0; k < 2; ++k) dst[m][k] = *(const LAS bf16x8*)(lds + PG8_SA(b, h) + aoff + m * 2048 + k * 1024); } while (0)
; #define PG8_MMA(ai, bj, At, Bt) do { __builtin_amdgcn_s_setprio(1); _Pragma("unroll") for (int m = 0; m < 4; ++m) _Pragma("unroll") for (int n = 0; n < 2; ++n) _Pragma("unroll") for (int k = 0; k < 2; ++k) \
;         acc[ai][bj][m][n] = __builtin_amdgcn_mfma_f32_16x16x32_bf16(Bt[n][k], At[m][k], acc[ai][bj][m][n], 0, 0, 0); __builtin_amdgcn_s_setprio(0); } while (0)
; #define PG8_WAIT_V(n) asm volatile("s_waitcnt vmcnt(" #n ")" ::: "memory")
; #define PG8_WAIT_L(n) asm volatile("s_waitcnt lgkmcnt(" #n ")" ::: "memory")
; #define PG8_BAR __builtin_amdgcn_s_barrier()
; #define PG8_SCHED __builtin_amdgcn_sched_barrier(0)
; template <class Epi>
; __device__ __forceinline__ void gemm_phase(LAS unsigned char* lds, const Gemm g, const StaticOrder& S, const Epi& E) {
;     ...
;             PG8_LDA(At, 1, 1); PG8_STAGE(PG8_SB(1, 0), b3, voffB); PG8_STAGE(PG8_SB(1, 1), b3 + hstepB, voffB); PG8_STAGE(PG8_SA(1, 0), a3, voffA);
;             PG8_WAIT_V(8); PG8_WAIT_L(0); PG8_BAR; PG8_MMA(1, 0, At, B0); PG8_MMA(1, 1, At, B1); PG8_BAR; PG8_SCHED;
;         }
;         if (wr == 0) PG8_BAR;
	s_add_i32 s24, s41, s28
	v_lshl_add_u64 v[184:185], v[184:185], 0, s[84:85]
	s_mov_b32 m0, s24
	ds_read_b128 v[176:179], v162 offset:49152
	ds_read_b128 v[188:191], v162 offset:50176
	ds_read_b128 v[192:195], v162 offset:51200
	ds_read_b128 v[196:199], v162 offset:52224
	ds_read_b128 v[200:203], v162 offset:53248
	ds_read_b128 v[204:207], v162 offset:54272
	ds_read_b128 v[208:211], v162 offset:55296
	ds_read_b128 v[212:215], v162 offset:56320
	global_load_lds_dwordx4 v[184:185], off
	s_add_i32 m0, s24, 0x2000
	s_add_u32 s14, s14, 0x80080
	v_lshl_add_u64 v[184:185], v[216:217], 0, s[84:85]
	s_addc_u32 s15, s15, 0
	s_add_i32 s24, s65, s28
	global_load_lds_dwordx4 v[184:185], off
	s_nop 0
	s_mov_b32 m0, s24
	s_nop 0
	global_load_lds_dwordx4 v150, s[14:15]
	s_nop 0
	s_add_i32 m0, s24, 0x2000
	s_nop 0
	global_load_lds_dwordx4 v146, s[14:15]
	v_lshl_add_u64 v[184:185], v[218:219], 0, s[84:85]
	s_mov_b32 m0, s44
	s_nop 0
	global_load_lds_dwordx4 v[184:185], off
	v_lshl_add_u64 v[184:185], v[220:221], 0, s[84:85]
	s_mov_b32 m0, s45
	s_nop 0
	global_load_lds_dwordx4 v[184:185], off
	s_waitcnt vmcnt(8)
	s_waitcnt lgkmcnt(0)
	s_barrier
	s_setprio 1
	s_waitcnt lgkmcnt(0)
	v_mfma_f32_16x16x32_bf16 v[62:65], v[130:133], v[176:179], v[62:65]
	v_mfma_f32_16x16x32_bf16 v[58:61], v[138:141], v[176:179], v[58:61]
	v_mfma_f32_16x16x32_bf16 v[54:57], v[130:133], v[192:195], v[54:57]
	v_mfma_f32_16x16x32_bf16 v[46:49], v[138:141], v[192:195], v[46:49]
	v_mfma_f32_16x16x32_bf16 v[38:41], v[130:133], v[200:203], v[38:41]
	v_mfma_f32_16x16x32_bf16 v[30:33], v[138:141], v[200:203], v[30:33]
	v_mfma_f32_16x16x32_bf16 v[22:25], v[130:133], v[208:211], v[22:25]
	v_mfma_f32_16x16x32_bf16 v[14:17], v[138:141], v[208:211], v[14:17]
	v_mfma_f32_16x16x32_bf16 v[62:65], v[134:137], v[188:191], v[62:65]
	v_mfma_f32_16x16x32_bf16 v[58:61], v[142:145], v[188:191], v[58:61]
	v_mfma_f32_16x16x32_bf16 v[54:57], v[134:137], v[196:199], v[54:57]
	v_mfma_f32_16x16x32_bf16 v[46:49], v[142:145], v[196:199], v[46:49]
	v_mfma_f32_16x16x32_bf16 v[38:41], v[134:137], v[204:207], v[38:41]
	v_mfma_f32_16x16x32_bf16 v[30:33], v[142:145], v[204:207], v[30:33]
	v_mfma_f32_16x16x32_bf16 v[22:25], v[134:137], v[212:215], v[22:25]
	v_mfma_f32_16x16x32_bf16 v[14:17], v[142:145], v[212:215], v[14:17]
	s_setprio 0
	s_setprio 1
	v_mfma_f32_16x16x32_bf16 v[50:53], v[158:161], v[176:179], v[50:53]
	v_mfma_f32_16x16x32_bf16 v[42:45], v[168:171], v[176:179], v[42:45]
	v_mfma_f32_16x16x32_bf16 v[34:37], v[158:161], v[192:195], v[34:37]
	v_mfma_f32_16x16x32_bf16 v[26:29], v[168:171], v[192:195], v[26:29]
	v_mfma_f32_16x16x32_bf16 v[18:21], v[158:161], v[200:203], v[18:21]
	v_mfma_f32_16x16x32_bf16 v[10:13], v[168:171], v[200:203], v[10:13]
	v_mfma_f32_16x16x32_bf16 v[6:9], v[158:161], v[208:211], v[6:9]
	v_mfma_f32_16x16x32_bf16 v[2:5], v[168:171], v[208:211], v[2:5]
	v_mfma_f32_16x16x32_bf16 v[50:53], v[164:167], v[188:191], v[50:53]
	v_mfma_f32_16x16x32_bf16 v[42:45], v[172:175], v[188:191], v[42:45]
	v_mfma_f32_16x16x32_bf16 v[34:37], v[164:167], v[196:199], v[34:37]
	v_mfma_f32_16x16x32_bf16 v[26:29], v[172:175], v[196:199], v[26:29]
	v_mfma_f32_16x16x32_bf16 v[18:21], v[164:167], v[204:207], v[18:21]
	v_mfma_f32_16x16x32_bf16 v[10:13], v[172:175], v[204:207], v[10:13]
	v_mfma_f32_16x16x32_bf16 v[6:9], v[164:167], v[212:215], v[6:9]
	v_mfma_f32_16x16x32_bf16 v[2:5], v[172:175], v[212:215], v[2:5]
	s_setprio 0
	s_barrier
	s_add_i32 s64, s64, 2
	s_add_u32 s22, s22, 0x100
	s_addc_u32 s23, s23, 0
	s_add_u32 s40, s40, 0x100
	s_addc_u32 s63, s63, 0
	s_cmp_gt_u32 s64, 29
	s_cbranch_scc0 .LBB0_1412
	s_and_b64 vcc, exec, s[10:11]
	s_cbranch_vccz .LBB0_1415
	s_barrier

; #define PG8_STAGE(bufoff, gbase, voff) do { _Pragma("unroll") for (int _i = 0; _i < 2; ++_i) \
;         __builtin_amdgcn_global_load_lds((const unsigned*)((const char*)(gbase) + (voff)[_i]), (LAS unsigned*)(lds + (bufoff) + ldsw + _i * 8192), 16, 0, 0); } while (0)
; #define PG8_LDA(dst, b, h) do { _Pragma("unroll") for (int m = 0; m < 4; ++m) _Pragma("unroll") for (int k = 0; k < 2; ++k) dst[m][k] = *(const LAS bf16x8*)(lds + PG8_SA(b, h) + aoff + m * 2048 + k * 1024); } while (0)
; #define PG8_LDB(dst, b, h) do { _Pragma("unroll") for (int n = 0; n < 2; ++n) _Pragma("unroll") for (int k = 0; k < 2; ++k) dst[n][k] = *(const LAS bf16x8*)(lds + PG8_SB(b, h) + boff + n * 2048 + k * 1024); } while (0)
; #define PG8_MMA(ai, bj, At, Bt) do { __builtin_amdgcn_s_setprio(1); _Pragma("unroll") for (int m = 0; m < 4; ++m) _Pragma("unroll") for (int n = 0; n < 2; ++n) _Pragma("unroll") for (int k = 0; k < 2; ++k) \
;         acc[ai][bj][m][n] = __builtin_amdgcn_mfma_f32_16x16x32_bf16(Bt[n][k], At[m][k], acc[ai][bj][m][n], 0, 0, 0); __builtin_amdgcn_s_setprio(0); } while (0)
; #define PG8_WAIT_V(n) asm volatile("s_waitcnt vmcnt(" #n ")" ::: "memory")
; #define PG8_BAR __builtin_amdgcn_s_barrier()
; template <class Epi>
; __device__ __forceinline__ void gemm_phase(LAS unsigned char* lds, const Gemm g, const StaticOrder& S, const Epi& E) {
;     ...
;         const bool has_next = S.next(ui + 1, nxt);
;         const char* nA = has_next ? PG8_UA(nxt) : cA; const char* nB = has_next ? PG8_UB(nxt) : cB;
;         for (int t = 0; t < nt; t += 2) {
;             const bool last = (t == nt - 2);
;             const char* a1 = cA + (size_t)(t + 1) * kstep;
;             const char* a2 = last ? nA : cA + (size_t)(t + 2) * kstep; const char* b2 = last ? nB : cB + (size_t)(t + 2) * kstep;
;             const char* a3 = a2 + kstep; const char* b3 = b2 + kstep;
;             PG8_LDB(B0, 0, 0); PG8_LDB(B1, 0, 1); PG8_SCHED; PG8_LDA(At, 0, 0); PG8_STAGE(PG8_SA(1, 1), a1 + hstepA, voffA);
;             PG8_WAIT_V(8); PG8_WAIT_L(0); PG8_BAR; PG8_MMA(0, 0, At, B0); PG8_MMA(0, 1, At, B1); PG8_BAR; PG8_SCHED;
;             PG8_LDA(At, 0, 1); PG8_STAGE(PG8_SB(0, 0), b2, voffB); PG8_STAGE(PG8_SB(0, 1), b2 + hstepB, voffB); PG8_STAGE(PG8_SA(0, 0), a2, voffA);
;             PG8_WAIT_V(8); PG8_WAIT_L(0); PG8_BAR; PG8_MMA(1, 0, At, B0); PG8_MMA(1, 1, At, B1); PG8_BAR; PG8_SCHED;
.LBB0_1440:
	s_add_u32 s41, s20, s14
	s_addc_u32 s44, s21, 0
	s_add_u32 s15, s41, 0x100
	s_addc_u32 s34, s44, 0
	s_and_b64 s[30:31], s[28:29], exec
	s_cselect_b32 s31, s19, s34
	s_cselect_b32 s30, s3, s15
	s_add_u32 s14, s12, s14
	s_addc_u32 s15, s13, 0
	s_add_u32 s34, s14, 0x100
	s_addc_u32 s35, s15, 0
	s_add_i32 s81, 0, 0x10000
	s_and_b64 s[14:15], s[28:29], exec
	s_cselect_b32 s35, s17, s35
	s_cselect_b32 s34, s40, s34
	s_add_i32 s29, 0, 0x14000
	s_add_u32 s68, s41, 0x10080
	s_addc_u32 s69, s44, 0
	s_add_i32 s77, s81, s63
	s_add_i32 m0, s11, 0xc000
	s_add_i32 s83, s11, 0xe000
	s_add_i32 s80, s77, 0x2000
	v_add_u32_e32 v139, s81, v1
	s_add_u32 s44, s34, 0x10000
	ds_read_b128 v[140:143], v139
	ds_read_b128 v[144:147], v139 offset:1024
	ds_read_b128 v[148:151], v139 offset:2048
	ds_read_b128 v[152:155], v139 offset:3072
	v_add_u32_e32 v139, s29, v1
	s_addc_u32 s45, s35, 0
	s_add_i32 s79, s29, s63
	ds_read_b128 v[156:159], v139
	ds_read_b128 v[160:163], v139 offset:1024
	ds_read_b128 v[164:167], v139 offset:2048
	ds_read_b128 v[168:171], v139 offset:3072
	s_add_i32 s78, s79, 0x2000
	s_add_i32 vcc_lo, 0, 0x18000
	s_add_i32 vcc_hi, 0, 0x1c000
	s_add_u32 s14, s30, 0x10000
	s_addc_u32 s15, s31, 0
	s_add_i32 s41, vcc_lo, s63
	s_add_i32 s76, s41, 0x2000
	s_add_u32 s28, s34, 0x10080
	s_addc_u32 s29, s35, 0
	s_add_i32 s81, vcc_hi, s63
	s_add_i32 s82, s81, 0x2000
	s_nop 0
	ds_read_b128 v[172:175], v138
	ds_read_b128 v[176:179], v138 offset:1024
	ds_read_b128 v[188:191], v138 offset:2048
	ds_read_b128 v[192:195], v138 offset:3072
	ds_read_b128 v[196:199], v138 offset:4096
	ds_read_b128 v[200:203], v138 offset:5120
	ds_read_b128 v[204:207], v138 offset:6144
	ds_read_b128 v[208:211], v138 offset:7168
	global_load_lds_dwordx4 v130, s[68:69]
	s_nop 0
	s_mov_b32 m0, s83
	s_nop 0
	global_load_lds_dwordx4 v134, s[68:69]
	s_waitcnt vmcnt(8)
	s_waitcnt lgkmcnt(0)
	s_barrier
	s_setprio 1
	s_waitcnt lgkmcnt(0)
	v_mfma_f32_16x16x32_bf16 v[126:129], v[140:143], v[172:175], v[126:129]
	v_mfma_f32_16x16x32_bf16 v[122:125], v[148:151], v[172:175], v[122:125]
	v_mfma_f32_16x16x32_bf16 v[118:121], v[140:143], v[188:191], v[118:121]
	v_mfma_f32_16x16x32_bf16 v[114:117], v[148:151], v[188:191], v[114:117]
	v_mfma_f32_16x16x32_bf16 v[102:105], v[140:143], v[196:199], v[102:105]
	v_mfma_f32_16x16x32_bf16 v[98:101], v[148:151], v[196:199], v[98:101]
	v_mfma_f32_16x16x32_bf16 v[86:89], v[140:143], v[204:207], v[86:89]
	v_mfma_f32_16x16x32_bf16 v[82:85], v[148:151], v[204:207], v[82:85]
	v_mfma_f32_16x16x32_bf16 v[126:129], v[144:147], v[176:179], v[126:129]
	v_mfma_f32_16x16x32_bf16 v[122:125], v[152:155], v[176:179], v[122:125]
	v_mfma_f32_16x16x32_bf16 v[118:121], v[144:147], v[192:195], v[118:121]
	v_mfma_f32_16x16x32_bf16 v[114:117], v[152:155], v[192:195], v[114:117]
	v_mfma_f32_16x16x32_bf16 v[102:105], v[144:147], v[200:203], v[102:105]
	v_mfma_f32_16x16x32_bf16 v[98:101], v[152:155], v[200:203], v[98:101]
	v_mfma_f32_16x16x32_bf16 v[86:89], v[144:147], v[208:211], v[86:89]
	v_mfma_f32_16x16x32_bf16 v[82:85], v[152:155], v[208:211], v[82:85]
	s_setprio 0
	s_setprio 1
	v_mfma_f32_16x16x32_bf16 v[110:113], v[156:159], v[172:175], v[110:113]
	v_mfma_f32_16x16x32_bf16 v[106:109], v[164:167], v[172:175], v[106:109]
	v_mfma_f32_16x16x32_bf16 v[94:97], v[156:159], v[188:191], v[94:97]
	v_mfma_f32_16x16x32_bf16 v[90:93], v[164:167], v[188:191], v[90:93]
	v_mfma_f32_16x16x32_bf16 v[78:81], v[156:159], v[196:199], v[78:81]
	v_mfma_f32_16x16x32_bf16 v[74:77], v[164:167], v[196:199], v[74:77]
	v_mfma_f32_16x16x32_bf16 v[70:73], v[156:159], v[204:207], v[70:73]
	v_mfma_f32_16x16x32_bf16 v[66:69], v[164:167], v[204:207], v[66:69]
	v_mfma_f32_16x16x32_bf16 v[110:113], v[160:163], v[176:179], v[110:113]
	v_mfma_f32_16x16x32_bf16 v[106:109], v[168:171], v[176:179], v[106:109]
	v_mfma_f32_16x16x32_bf16 v[94:97], v[160:163], v[192:195], v[94:97]
	v_mfma_f32_16x16x32_bf16 v[90:93], v[168:171], v[192:195], v[90:93]
	v_mfma_f32_16x16x32_bf16 v[78:81], v[160:163], v[200:203], v[78:81]
	v_mfma_f32_16x16x32_bf16 v[74:77], v[168:171], v[200:203], v[74:77]
	v_mfma_f32_16x16x32_bf16 v[70:73], v[160:163], v[208:211], v[70:73]
	v_mfma_f32_16x16x32_bf16 v[66:69], v[168:171], v[208:211], v[66:69]
	s_setprio 0
	s_barrier
	s_mov_b32 m0, s77
	v_lshl_add_u64 v[184:185], s[34:35], 0, v[132:133]
	ds_read_b128 v[172:175], v138 offset:16384
	ds_read_b128 v[176:179], v138 offset:17408
	ds_read_b128 v[188:191], v138 offset:18432
	ds_read_b128 v[192:195], v138 offset:19456
	ds_read_b128 v[196:199], v138 offset:20480
	ds_read_b128 v[200:203], v138 offset:21504
	ds_read_b128 v[204:207], v138 offset:22528
	ds_read_b128 v[208:211], v138 offset:23552
	global_load_lds_dwordx4 v132, s[34:35]
	v_lshl_add_u64 v[212:213], s[34:35], 0, v[136:137]
	s_mov_b32 m0, s80
	s_nop 0
	global_load_lds_dwordx4 v136, s[34:35]
	s_mov_b32 m0, s79
	v_lshl_add_u64 v[216:217], s[30:31], 0, v[134:135]
	global_load_lds_dwordx4 v132, s[44:45]
	s_nop 0
	s_mov_b32 m0, s78
	s_nop 0
	global_load_lds_dwordx4 v136, s[44:45]
	v_lshl_add_u64 v[214:215], s[30:31], 0, v[130:131]
	s_mov_b32 m0, s11
	s_nop 0
	global_load_lds_dwordx4 v130, s[30:31]
	s_mov_b32 m0, s64
	s_nop 0
	global_load_lds_dwordx4 v134, s[30:31]
	s_waitcnt vmcnt(8)
	s_waitcnt lgkmcnt(0)
	s_barrier
; #define PG8_STAGE(bufoff, gbase, voff) do { _Pragma("unroll") for (int _i = 0; _i < 2; ++_i) \
;         __builtin_amdgcn_global_load_lds((const unsigned*)((const char*)(gbase) + (voff)[_i]), (LAS unsigned*)(lds + (bufoff) + ldsw + _i * 8192), 16, 0, 0); } while (0)
; #define PG8_LDA(dst, b, h) do { _Pragma("unroll") for (int m = 0; m < 4; ++m) _Pragma("unroll") for (int k = 0; k < 2; ++k) dst[m][k] = *(const LAS bf16x8*)(lds + PG8_SA(b, h) + aoff + m * 2048 + k * 1024); } while (0)
; #define PG8_LDB(dst, b, h) do { _Pragma("unroll") for (int n = 0; n < 2; ++n) _Pragma("unroll") for (int k = 0; k < 2; ++k) dst[n][k] = *(const LAS bf16x8*)(lds + PG8_SB(b, h) + boff + n * 2048 + k * 1024); } while (0)
; #define PG8_MMA(ai, bj, At, Bt) do { __builtin_amdgcn_s_setprio(1); _Pragma("unroll") for (int m = 0; m < 4; ++m) _Pragma("unroll") for (int n = 0; n < 2; ++n) _Pragma("unroll") for (int k = 0; k < 2; ++k) \
;         acc[ai][bj][m][n] = __builtin_amdgcn_mfma_f32_16x16x32_bf16(Bt[n][k], At[m][k], acc[ai][bj][m][n], 0, 0, 0); __builtin_amdgcn_s_setprio(0); } while (0)
; #define PG8_WAIT_V(n) asm volatile("s_waitcnt vmcnt(" #n ")" ::: "memory")
; #define PG8_WAIT_L(n) asm volatile("s_waitcnt lgkmcnt(" #n ")" ::: "memory")
; #define PG8_BAR __builtin_amdgcn_s_barrier()
; #define PG8_SCHED __builtin_amdgcn_sched_barrier(0)
; template <class Epi>
; __device__ __forceinline__ void gemm_phase(LAS unsigned char* lds, const Gemm g, const StaticOrder& S, const Epi& E) {
;     ...
;             PG8_WAIT_V(8); PG8_WAIT_L(0); PG8_BAR; PG8_MMA(1, 0, At, B0); PG8_MMA(1, 1, At, B1); PG8_BAR; PG8_SCHED;
;             PG8_LDB(B0, 1, 0); PG8_LDB(B1, 1, 1); PG8_SCHED; PG8_LDA(At, 1, 0); PG8_STAGE(PG8_SA(0, 1), a2 + hstepA, voffA);
;             PG8_WAIT_V(8); PG8_WAIT_L(0); PG8_BAR; PG8_MMA(0, 0, At, B0); PG8_MMA(0, 1, At, B1); PG8_BAR; PG8_SCHED;
	s_setprio 1
	s_waitcnt lgkmcnt(0)
	v_mfma_f32_16x16x32_bf16 v[62:65], v[140:143], v[172:175], v[62:65]
	v_mfma_f32_16x16x32_bf16 v[58:61], v[148:151], v[172:175], v[58:61]
	v_mfma_f32_16x16x32_bf16 v[54:57], v[140:143], v[188:191], v[54:57]
	v_mfma_f32_16x16x32_bf16 v[50:53], v[148:151], v[188:191], v[50:53]
	v_mfma_f32_16x16x32_bf16 v[38:41], v[140:143], v[196:199], v[38:41]
	v_mfma_f32_16x16x32_bf16 v[34:37], v[148:151], v[196:199], v[34:37]
	v_mfma_f32_16x16x32_bf16 v[22:25], v[140:143], v[204:207], v[22:25]
	v_mfma_f32_16x16x32_bf16 v[18:21], v[148:151], v[204:207], v[18:21]
	v_mfma_f32_16x16x32_bf16 v[62:65], v[144:147], v[176:179], v[62:65]
	v_mfma_f32_16x16x32_bf16 v[58:61], v[152:155], v[176:179], v[58:61]
	v_mfma_f32_16x16x32_bf16 v[54:57], v[144:147], v[192:195], v[54:57]
	v_mfma_f32_16x16x32_bf16 v[50:53], v[152:155], v[192:195], v[50:53]
	v_mfma_f32_16x16x32_bf16 v[38:41], v[144:147], v[200:203], v[38:41]
	v_mfma_f32_16x16x32_bf16 v[34:37], v[152:155], v[200:203], v[34:37]
	v_mfma_f32_16x16x32_bf16 v[22:25], v[144:147], v[208:211], v[22:25]
	v_mfma_f32_16x16x32_bf16 v[18:21], v[152:155], v[208:211], v[18:21]
	s_setprio 0
	s_setprio 1
	v_mfma_f32_16x16x32_bf16 v[46:49], v[156:159], v[172:175], v[46:49]
	v_mfma_f32_16x16x32_bf16 v[42:45], v[164:167], v[172:175], v[42:45]
	v_mfma_f32_16x16x32_bf16 v[30:33], v[156:159], v[188:191], v[30:33]
	v_mfma_f32_16x16x32_bf16 v[26:29], v[164:167], v[188:191], v[26:29]
	v_mfma_f32_16x16x32_bf16 v[14:17], v[156:159], v[196:199], v[14:17]
	v_mfma_f32_16x16x32_bf16 v[10:13], v[164:167], v[196:199], v[10:13]
	v_mfma_f32_16x16x32_bf16 v[6:9], v[156:159], v[204:207], v[6:9]
	v_mfma_f32_16x16x32_bf16 v[2:5], v[164:167], v[204:207], v[2:5]
	v_mfma_f32_16x16x32_bf16 v[46:49], v[160:163], v[176:179], v[46:49]
	v_mfma_f32_16x16x32_bf16 v[42:45], v[168:171], v[176:179], v[42:45]
	v_mfma_f32_16x16x32_bf16 v[30:33], v[160:163], v[192:195], v[30:33]
	v_mfma_f32_16x16x32_bf16 v[26:29], v[168:171], v[192:195], v[26:29]
	v_mfma_f32_16x16x32_bf16 v[14:17], v[160:163], v[200:203], v[14:17]
	v_mfma_f32_16x16x32_bf16 v[10:13], v[168:171], v[200:203], v[10:13]
	v_mfma_f32_16x16x32_bf16 v[6:9], v[160:163], v[208:211], v[6:9]
	v_mfma_f32_16x16x32_bf16 v[2:5], v[168:171], v[208:211], v[2:5]
	s_setprio 0
	s_barrier
	v_add_u32_e32 v139, vcc_lo, v1
	ds_read_b128 v[140:143], v139
	ds_read_b128 v[144:147], v139 offset:1024
	ds_read_b128 v[148:151], v139 offset:2048
	ds_read_b128 v[152:155], v139 offset:3072
	v_add_u32_e32 v139, vcc_hi, v1
	ds_read_b128 v[156:159], v139
	ds_read_b128 v[160:163], v139 offset:1024
	ds_read_b128 v[164:167], v139 offset:2048
	ds_read_b128 v[168:171], v139 offset:3072
	s_mov_b32 m0, s65
	s_nop 0
	ds_read_b128 v[172:175], v138 offset:32768
	ds_read_b128 v[176:179], v138 offset:33792
	ds_read_b128 v[188:191], v138 offset:34816
	ds_read_b128 v[192:195], v138 offset:35840
	ds_read_b128 v[196:199], v138 offset:36864
	ds_read_b128 v[200:203], v138 offset:37888
	ds_read_b128 v[204:207], v138 offset:38912
	ds_read_b128 v[208:211], v138 offset:39936
	global_load_lds_dwordx4 v130, s[14:15]
	s_nop 0
	s_mov_b32 m0, s70
	s_nop 0
	global_load_lds_dwordx4 v134, s[14:15]
	s_waitcnt vmcnt(8)
	s_waitcnt lgkmcnt(0)
	s_barrier
	s_setprio 1
	s_waitcnt lgkmcnt(0)
	v_mfma_f32_16x16x32_bf16 v[126:129], v[140:143], v[172:175], v[126:129]
	v_mfma_f32_16x16x32_bf16 v[122:125], v[148:151], v[172:175], v[122:125]
	v_mfma_f32_16x16x32_bf16 v[118:121], v[140:143], v[188:191], v[118:121]
	v_mfma_f32_16x16x32_bf16 v[114:117], v[148:151], v[188:191], v[114:117]
	v_mfma_f32_16x16x32_bf16 v[102:105], v[140:143], v[196:199], v[102:105]
	v_mfma_f32_16x16x32_bf16 v[98:101], v[148:151], v[196:199], v[98:101]
	v_mfma_f32_16x16x32_bf16 v[86:89], v[140:143], v[204:207], v[86:89]
	v_mfma_f32_16x16x32_bf16 v[82:85], v[148:151], v[204:207], v[82:85]
	v_mfma_f32_16x16x32_bf16 v[126:129], v[144:147], v[176:179], v[126:129]
	v_mfma_f32_16x16x32_bf16 v[122:125], v[152:155], v[176:179], v[122:125]
	v_mfma_f32_16x16x32_bf16 v[118:121], v[144:147], v[192:195], v[118:121]
	v_mfma_f32_16x16x32_bf16 v[114:117], v[152:155], v[192:195], v[114:117]
	v_mfma_f32_16x16x32_bf16 v[102:105], v[144:147], v[200:203], v[102:105]
	v_mfma_f32_16x16x32_bf16 v[98:101], v[152:155], v[200:203], v[98:101]
	v_mfma_f32_16x16x32_bf16 v[86:89], v[144:147], v[208:211], v[86:89]
	v_mfma_f32_16x16x32_bf16 v[82:85], v[152:155], v[208:211], v[82:85]
	s_setprio 0
	s_setprio 1
	v_mfma_f32_16x16x32_bf16 v[110:113], v[156:159], v[172:175], v[110:113]
	v_mfma_f32_16x16x32_bf16 v[106:109], v[164:167], v[172:175], v[106:109]
	v_mfma_f32_16x16x32_bf16 v[94:97], v[156:159], v[188:191], v[94:97]
	v_mfma_f32_16x16x32_bf16 v[90:93], v[164:167], v[188:191], v[90:93]
	v_mfma_f32_16x16x32_bf16 v[78:81], v[156:159], v[196:199], v[78:81]
	v_mfma_f32_16x16x32_bf16 v[74:77], v[164:167], v[196:199], v[74:77]
	v_mfma_f32_16x16x32_bf16 v[70:73], v[156:159], v[204:207], v[70:73]
	v_mfma_f32_16x16x32_bf16 v[66:69], v[164:167], v[204:207], v[66:69]
	v_mfma_f32_16x16x32_bf16 v[110:113], v[160:163], v[176:179], v[110:113]
	v_mfma_f32_16x16x32_bf16 v[106:109], v[168:171], v[176:179], v[106:109]
	v_mfma_f32_16x16x32_bf16 v[94:97], v[160:163], v[192:195], v[94:97]
	v_mfma_f32_16x16x32_bf16 v[90:93], v[168:171], v[192:195], v[90:93]
	v_mfma_f32_16x16x32_bf16 v[78:81], v[160:163], v[200:203], v[78:81]
	v_mfma_f32_16x16x32_bf16 v[74:77], v[168:171], v[200:203], v[74:77]
	v_mfma_f32_16x16x32_bf16 v[70:73], v[160:163], v[208:211], v[70:73]
	v_mfma_f32_16x16x32_bf16 v[66:69], v[168:171], v[208:211], v[66:69]
	s_setprio 0
	s_barrier
; #define PG8_STAGE(bufoff, gbase, voff) do { _Pragma("unroll") for (int _i = 0; _i < 2; ++_i) \
;         __builtin_amdgcn_global_load_lds((const unsigned*)((const char*)(gbase) + (voff)[_i]), (LAS unsigned*)(lds + (bufoff) + ldsw + _i * 8192), 16, 0, 0); } while (0)
; #define PG8_LDA(dst, b, h) do { _Pragma("unroll") for (int m = 0; m < 4; ++m) _Pragma("unroll") for (int k = 0; k < 2; ++k) dst[m][k] = *(const LAS bf16x8*)(lds + PG8_SA(b, h) + aoff + m * 2048 + k * 1024); } while (0)
; #define PG8_MMA(ai, bj, At, Bt) do { __builtin_amdgcn_s_setprio(1); _Pragma("unroll") for (int m = 0; m < 4; ++m) _Pragma("unroll") for (int n = 0; n < 2; ++n) _Pragma("unroll") for (int k = 0; k < 2; ++k) \
;         acc[ai][bj][m][n] = __builtin_amdgcn_mfma_f32_16x16x32_bf16(Bt[n][k], At[m][k], acc[ai][bj][m][n], 0, 0, 0); __builtin_amdgcn_s_setprio(0); } while (0)
; #define PG8_WAIT_V(n) asm volatile("s_waitcnt vmcnt(" #n ")" ::: "memory")
; #define PG8_WAIT_L(n) asm volatile("s_waitcnt lgkmcnt(" #n ")" ::: "memory")
; #define PG8_BAR __builtin_amdgcn_s_barrier()
; #define PG8_SCHED __builtin_amdgcn_sched_barrier(0)
; template <class Epi>
; __device__ __forceinline__ void gemm_phase(LAS unsigned char* lds, const Gemm g, const StaticOrder& S, const Epi& E) {
;     ...
;             PG8_LDA(At, 1, 1); PG8_STAGE(PG8_SB(1, 0), b3, voffB); PG8_STAGE(PG8_SB(1, 1), b3 + hstepB, voffB); PG8_STAGE(PG8_SA(1, 0), a3, voffA);
;             PG8_WAIT_V(8); PG8_WAIT_L(0); PG8_BAR; PG8_MMA(1, 0, At, B0); PG8_MMA(1, 1, At, B1); PG8_BAR; PG8_SCHED;
;         }
;         if (wr == 0) PG8_BAR;
	s_mov_b32 m0, s41
	v_lshl_add_u64 v[184:185], v[184:185], 0, s[84:85]
	ds_read_b128 v[172:175], v138 offset:49152
	ds_read_b128 v[176:179], v138 offset:50176
	ds_read_b128 v[188:191], v138 offset:51200
	ds_read_b128 v[192:195], v138 offset:52224
	ds_read_b128 v[196:199], v138 offset:53248
	ds_read_b128 v[200:203], v138 offset:54272
	ds_read_b128 v[204:207], v138 offset:55296
	ds_read_b128 v[208:211], v138 offset:56320
	global_load_lds_dwordx4 v[184:185], off
	v_lshl_add_u64 v[184:185], v[212:213], 0, s[84:85]
	s_mov_b32 m0, s76
	s_nop 0
	global_load_lds_dwordx4 v[184:185], off
	s_nop 0
	s_mov_b32 m0, s81
	s_nop 0
	global_load_lds_dwordx4 v132, s[28:29]
	s_nop 0
	s_mov_b32 m0, s82
	s_nop 0
	global_load_lds_dwordx4 v136, s[28:29]
	v_lshl_add_u64 v[184:185], v[214:215], 0, s[84:85]
	s_mov_b32 m0, s86
	s_nop 0
	global_load_lds_dwordx4 v[184:185], off
	v_lshl_add_u64 v[184:185], v[216:217], 0, s[84:85]
	s_mov_b32 m0, s87
	s_nop 0
	global_load_lds_dwordx4 v[184:185], off
	s_waitcnt vmcnt(8)
	s_waitcnt lgkmcnt(0)
	s_barrier
	s_setprio 1
	s_waitcnt lgkmcnt(0)
	v_mfma_f32_16x16x32_bf16 v[62:65], v[140:143], v[172:175], v[62:65]
	v_mfma_f32_16x16x32_bf16 v[58:61], v[148:151], v[172:175], v[58:61]
	v_mfma_f32_16x16x32_bf16 v[54:57], v[140:143], v[188:191], v[54:57]
	v_mfma_f32_16x16x32_bf16 v[50:53], v[148:151], v[188:191], v[50:53]
	v_mfma_f32_16x16x32_bf16 v[38:41], v[140:143], v[196:199], v[38:41]
	v_mfma_f32_16x16x32_bf16 v[34:37], v[148:151], v[196:199], v[34:37]
	v_mfma_f32_16x16x32_bf16 v[22:25], v[140:143], v[204:207], v[22:25]
	v_mfma_f32_16x16x32_bf16 v[18:21], v[148:151], v[204:207], v[18:21]
	v_mfma_f32_16x16x32_bf16 v[62:65], v[144:147], v[176:179], v[62:65]
	v_mfma_f32_16x16x32_bf16 v[58:61], v[152:155], v[176:179], v[58:61]
	v_mfma_f32_16x16x32_bf16 v[54:57], v[144:147], v[192:195], v[54:57]
	v_mfma_f32_16x16x32_bf16 v[50:53], v[152:155], v[192:195], v[50:53]
	v_mfma_f32_16x16x32_bf16 v[38:41], v[144:147], v[200:203], v[38:41]
	v_mfma_f32_16x16x32_bf16 v[34:37], v[152:155], v[200:203], v[34:37]
	v_mfma_f32_16x16x32_bf16 v[22:25], v[144:147], v[208:211], v[22:25]
	v_mfma_f32_16x16x32_bf16 v[18:21], v[152:155], v[208:211], v[18:21]
	s_setprio 0
	s_setprio 1
	v_mfma_f32_16x16x32_bf16 v[46:49], v[156:159], v[172:175], v[46:49]
	v_mfma_f32_16x16x32_bf16 v[42:45], v[164:167], v[172:175], v[42:45]
	v_mfma_f32_16x16x32_bf16 v[30:33], v[156:159], v[188:191], v[30:33]
	v_mfma_f32_16x16x32_bf16 v[26:29], v[164:167], v[188:191], v[26:29]
	v_mfma_f32_16x16x32_bf16 v[14:17], v[156:159], v[196:199], v[14:17]
	v_mfma_f32_16x16x32_bf16 v[10:13], v[164:167], v[196:199], v[10:13]
	v_mfma_f32_16x16x32_bf16 v[6:9], v[156:159], v[204:207], v[6:9]
	v_mfma_f32_16x16x32_bf16 v[2:5], v[164:167], v[204:207], v[2:5]
	v_mfma_f32_16x16x32_bf16 v[46:49], v[160:163], v[176:179], v[46:49]
	v_mfma_f32_16x16x32_bf16 v[42:45], v[168:171], v[176:179], v[42:45]
	v_mfma_f32_16x16x32_bf16 v[30:33], v[160:163], v[192:195], v[30:33]
	v_mfma_f32_16x16x32_bf16 v[26:29], v[168:171], v[192:195], v[26:29]
	v_mfma_f32_16x16x32_bf16 v[14:17], v[160:163], v[200:203], v[14:17]
	v_mfma_f32_16x16x32_bf16 v[10:13], v[168:171], v[200:203], v[10:13]
	v_mfma_f32_16x16x32_bf16 v[6:9], v[160:163], v[208:211], v[6:9]
	v_mfma_f32_16x16x32_bf16 v[2:5], v[168:171], v[208:211], v[2:5]
	s_setprio 0
	s_barrier
	s_movk_i32 s14, 0x100
	s_andn2_b64 vcc, exec, s[26:27]
	s_mov_b64 s[28:29], -1
	s_mov_b64 s[26:27], 0
	s_cbranch_vccz .LBB0_1440
	v_readlane_b32 s28, v255, 28
	s_and_b64 vcc, exec, s[8:9]
	v_readlane_b32 s29, v255, 29
	s_cbranch_vccz .LBB0_1443
	s_barrier

; #define PG8_STAGE(bufoff, gbase, voff) do { _Pragma("unroll") for (int _i = 0; _i < 2; ++_i) \
;         __builtin_amdgcn_global_load_lds((const unsigned*)((const char*)(gbase) + (voff)[_i]), (LAS unsigned*)(lds + (bufoff) + ldsw + _i * 8192), 16, 0, 0); } while (0)
; #define PG8_LDA(dst, b, h) do { _Pragma("unroll") for (int m = 0; m < 4; ++m) _Pragma("unroll") for (int k = 0; k < 2; ++k) dst[m][k] = *(const LAS bf16x8*)(lds + PG8_SA(b, h) + aoff + m * 2048 + k * 1024); } while (0)
; #define PG8_LDB(dst, b, h) do { _Pragma("unroll") for (int n = 0; n < 2; ++n) _Pragma("unroll") for (int k = 0; k < 2; ++k) dst[n][k] = *(const LAS bf16x8*)(lds + PG8_SB(b, h) + boff + n * 2048 + k * 1024); } while (0)
; #define PG8_MMA(ai, bj, At, Bt) do { __builtin_amdgcn_s_setprio(1); _Pragma("unroll") for (int m = 0; m < 4; ++m) _Pragma("unroll") for (int n = 0; n < 2; ++n) _Pragma("unroll") for (int k = 0; k < 2; ++k) \
;         acc[ai][bj][m][n] = __builtin_amdgcn_mfma_f32_16x16x32_bf16(Bt[n][k], At[m][k], acc[ai][bj][m][n], 0, 0, 0); __builtin_amdgcn_s_setprio(0); } while (0)
; #define PG8_WAIT_V(n) asm volatile("s_waitcnt vmcnt(" #n ")" ::: "memory")
; #define PG8_WAIT_L(n) asm volatile("s_waitcnt lgkmcnt(" #n ")" ::: "memory")
; #define PG8_BAR __builtin_amdgcn_s_barrier()
; #define PG8_SCHED __builtin_amdgcn_sched_barrier(0)
; template <class Epi>
; __device__ __forceinline__ void gemm_phase(LAS unsigned char* lds, const Gemm g, const StaticOrder& S, const Epi& E) {
;     ...
;             const bool last = (t == nt - 2);
;             const char* a1 = cA + (size_t)(t + 1) * kstep;
;             const char* a2 = last ? nA : cA + (size_t)(t + 2) * kstep; const char* b2 = last ? nB : cB + (size_t)(t + 2) * kstep;
;             const char* a3 = a2 + kstep; const char* b3 = b2 + kstep;
;             PG8_LDB(B0, 0, 0); PG8_LDB(B1, 0, 1); PG8_SCHED; PG8_LDA(At, 0, 0); PG8_STAGE(PG8_SA(1, 1), a1 + hstepA, voffA);
;             PG8_WAIT_V(8); PG8_WAIT_L(0); PG8_BAR; PG8_MMA(0, 0, At, B0); PG8_MMA(0, 1, At, B1); PG8_BAR; PG8_SCHED;
;             PG8_LDA(At, 0, 1); PG8_STAGE(PG8_SB(0, 0), b2, voffB); PG8_STAGE(PG8_SB(0, 1), b2 + hstepB, voffB); PG8_STAGE(PG8_SA(0, 0), a2, voffA);
;             PG8_WAIT_V(8); PG8_WAIT_L(0); PG8_BAR; PG8_MMA(1, 0, At, B0); PG8_MMA(1, 1, At, B1); PG8_BAR; PG8_SCHED;
.LBB0_2035:
	s_add_u32 s14, s24, 0xfff80080
	s_addc_u32 s15, s25, -1
	s_add_i32 s41, 0, 0x10000
	s_cmp_eq_u32 s52, 28
	s_cselect_b32 s27, s1, s15
	s_cselect_b32 s26, s3, s14
	s_cselect_b32 s15, s7, s40
	s_cselect_b32 s14, s13, s17
	s_add_i32 s53, 0, 0x14000
	v_add_u32_e32 v142, s41, v1
	v_add_u32_e32 v158, s53, v1
	ds_read_b128 v[130:133], v142
	ds_read_b128 v[134:137], v142 offset:1024
	ds_read_b128 v[138:141], v142 offset:2048
	ds_read_b128 v[142:145], v142 offset:3072
	ds_read_b128 v[146:149], v158
	ds_read_b128 v[150:153], v158 offset:1024
	ds_read_b128 v[154:157], v158 offset:2048
	ds_read_b128 v[158:161], v158 offset:3072
	s_nop 0
	s_add_i32 m0, s23, 0xc000
	ds_read_b128 v[162:165], v181
	ds_read_b128 v[166:169], v181 offset:1024
	ds_read_b128 v[170:173], v181 offset:2048
	ds_read_b128 v[174:177], v181 offset:3072
	ds_read_b128 v[200:203], v181 offset:4096
	ds_read_b128 v[204:207], v181 offset:5120
	ds_read_b128 v[208:211], v181 offset:6144
	ds_read_b128 v[212:215], v181 offset:7168
	global_load_lds_dwordx4 v196, s[24:25]
	s_nop 0
	s_add_i32 m0, s23, 0xe000
	s_nop 0
	global_load_lds_dwordx4 v198, s[24:25]
	s_waitcnt vmcnt(8)
	s_waitcnt lgkmcnt(0)
	s_barrier
	s_setprio 1
	s_waitcnt lgkmcnt(0)
	v_mfma_f32_16x16x32_bf16 v[126:129], v[130:133], v[162:165], v[126:129]
	v_mfma_f32_16x16x32_bf16 v[122:125], v[138:141], v[162:165], v[122:125]
	v_mfma_f32_16x16x32_bf16 v[110:113], v[130:133], v[170:173], v[110:113]
	v_mfma_f32_16x16x32_bf16 v[106:109], v[138:141], v[170:173], v[106:109]
	v_mfma_f32_16x16x32_bf16 v[94:97], v[130:133], v[200:203], v[94:97]
	v_mfma_f32_16x16x32_bf16 v[90:93], v[138:141], v[200:203], v[90:93]
	v_mfma_f32_16x16x32_bf16 v[82:85], v[130:133], v[208:211], v[82:85]
	v_mfma_f32_16x16x32_bf16 v[74:77], v[138:141], v[208:211], v[74:77]
	v_mfma_f32_16x16x32_bf16 v[126:129], v[134:137], v[166:169], v[126:129]
	v_mfma_f32_16x16x32_bf16 v[122:125], v[142:145], v[166:169], v[122:125]
	v_mfma_f32_16x16x32_bf16 v[110:113], v[134:137], v[174:177], v[110:113]
	v_mfma_f32_16x16x32_bf16 v[106:109], v[142:145], v[174:177], v[106:109]
	v_mfma_f32_16x16x32_bf16 v[94:97], v[134:137], v[204:207], v[94:97]
	v_mfma_f32_16x16x32_bf16 v[90:93], v[142:145], v[204:207], v[90:93]
	v_mfma_f32_16x16x32_bf16 v[82:85], v[134:137], v[212:215], v[82:85]
	v_mfma_f32_16x16x32_bf16 v[74:77], v[142:145], v[212:215], v[74:77]
	s_setprio 0
	s_setprio 1
	v_mfma_f32_16x16x32_bf16 v[118:121], v[146:149], v[162:165], v[118:121]
	v_mfma_f32_16x16x32_bf16 v[114:117], v[154:157], v[162:165], v[114:117]
	v_mfma_f32_16x16x32_bf16 v[102:105], v[146:149], v[170:173], v[102:105]
	v_mfma_f32_16x16x32_bf16 v[98:101], v[154:157], v[170:173], v[98:101]
	v_mfma_f32_16x16x32_bf16 v[86:89], v[146:149], v[200:203], v[86:89]
	v_mfma_f32_16x16x32_bf16 v[78:81], v[154:157], v[200:203], v[78:81]
	v_mfma_f32_16x16x32_bf16 v[70:73], v[146:149], v[208:211], v[70:73]
	v_mfma_f32_16x16x32_bf16 v[66:69], v[154:157], v[208:211], v[66:69]
	v_mfma_f32_16x16x32_bf16 v[118:121], v[150:153], v[166:169], v[118:121]
	v_mfma_f32_16x16x32_bf16 v[114:117], v[158:161], v[166:169], v[114:117]
	v_mfma_f32_16x16x32_bf16 v[102:105], v[150:153], v[174:177], v[102:105]
	v_mfma_f32_16x16x32_bf16 v[98:101], v[158:161], v[174:177], v[98:101]
	v_mfma_f32_16x16x32_bf16 v[86:89], v[150:153], v[204:207], v[86:89]
	v_mfma_f32_16x16x32_bf16 v[78:81], v[158:161], v[204:207], v[78:81]
	v_mfma_f32_16x16x32_bf16 v[70:73], v[150:153], v[212:215], v[70:73]
	v_mfma_f32_16x16x32_bf16 v[66:69], v[158:161], v[212:215], v[66:69]
	s_setprio 0
	s_barrier
	s_add_i32 s41, s41, s30
	v_lshl_add_u64 v[178:179], s[14:15], 0, v[190:191]
	s_mov_b32 m0, s41
	ds_read_b128 v[162:165], v181 offset:16384
	ds_read_b128 v[166:169], v181 offset:17408
	ds_read_b128 v[170:173], v181 offset:18432
	ds_read_b128 v[174:177], v181 offset:19456
	ds_read_b128 v[200:203], v181 offset:20480
	ds_read_b128 v[204:207], v181 offset:21504
	ds_read_b128 v[208:211], v181 offset:22528
	ds_read_b128 v[212:215], v181 offset:23552
	global_load_lds_dwordx4 v190, s[14:15]
	s_add_i32 m0, s41, 0x2000
	s_add_u32 s62, s14, 0x80000
	v_lshl_add_u64 v[184:185], s[14:15], 0, v[194:195]
	s_addc_u32 s63, s15, 0
	s_add_i32 s41, s53, s30
	global_load_lds_dwordx4 v194, s[14:15]
	s_nop 0
	s_mov_b32 m0, s41
	v_lshl_add_u64 v[218:219], s[26:27], 0, v[192:193]
	global_load_lds_dwordx4 v190, s[62:63]
	s_nop 0
	s_add_i32 m0, s41, 0x2000
	s_nop 0
	global_load_lds_dwordx4 v194, s[62:63]
	v_lshl_add_u64 v[216:217], s[26:27], 0, v[188:189]
	s_mov_b32 m0, s23
	s_nop 0
	global_load_lds_dwordx4 v188, s[26:27]
	s_mov_b32 m0, s34
	s_nop 0
	global_load_lds_dwordx4 v192, s[26:27]
	s_waitcnt vmcnt(8)
	s_waitcnt lgkmcnt(0)
	s_barrier
; #define PG8_STAGE(bufoff, gbase, voff) do { _Pragma("unroll") for (int _i = 0; _i < 2; ++_i) \
;         __builtin_amdgcn_global_load_lds((const unsigned*)((const char*)(gbase) + (voff)[_i]), (LAS unsigned*)(lds + (bufoff) + ldsw + _i * 8192), 16, 0, 0); } while (0)
; #define PG8_LDA(dst, b, h) do { _Pragma("unroll") for (int m = 0; m < 4; ++m) _Pragma("unroll") for (int k = 0; k < 2; ++k) dst[m][k] = *(const LAS bf16x8*)(lds + PG8_SA(b, h) + aoff + m * 2048 + k * 1024); } while (0)
; #define PG8_LDB(dst, b, h) do { _Pragma("unroll") for (int n = 0; n < 2; ++n) _Pragma("unroll") for (int k = 0; k < 2; ++k) dst[n][k] = *(const LAS bf16x8*)(lds + PG8_SB(b, h) + boff + n * 2048 + k * 1024); } while (0)
; #define PG8_MMA(ai, bj, At, Bt) do { __builtin_amdgcn_s_setprio(1); _Pragma("unroll") for (int m = 0; m < 4; ++m) _Pragma("unroll") for (int n = 0; n < 2; ++n) _Pragma("unroll") for (int k = 0; k < 2; ++k) \
;         acc[ai][bj][m][n] = __builtin_amdgcn_mfma_f32_16x16x32_bf16(Bt[n][k], At[m][k], acc[ai][bj][m][n], 0, 0, 0); __builtin_amdgcn_s_setprio(0); } while (0)
; #define PG8_WAIT_V(n) asm volatile("s_waitcnt vmcnt(" #n ")" ::: "memory")
; #define PG8_WAIT_L(n) asm volatile("s_waitcnt lgkmcnt(" #n ")" ::: "memory")
; #define PG8_BAR __builtin_amdgcn_s_barrier()
; #define PG8_SCHED __builtin_amdgcn_sched_barrier(0)
; template <class Epi>
; __device__ __forceinline__ void gemm_phase(LAS unsigned char* lds, const Gemm g, const StaticOrder& S, const Epi& E) {
;     ...
;             PG8_WAIT_V(8); PG8_WAIT_L(0); PG8_BAR; PG8_MMA(1, 0, At, B0); PG8_MMA(1, 1, At, B1); PG8_BAR; PG8_SCHED;
;             PG8_LDB(B0, 1, 0); PG8_LDB(B1, 1, 1); PG8_SCHED; PG8_LDA(At, 1, 0); PG8_STAGE(PG8_SA(0, 1), a2 + hstepA, voffA);
;             PG8_WAIT_V(8); PG8_WAIT_L(0); PG8_BAR; PG8_MMA(0, 0, At, B0); PG8_MMA(0, 1, At, B1); PG8_BAR; PG8_SCHED;
	s_setprio 1
	s_waitcnt lgkmcnt(0)
	v_mfma_f32_16x16x32_bf16 v[62:65], v[130:133], v[162:165], v[62:65]
	v_mfma_f32_16x16x32_bf16 v[58:61], v[138:141], v[162:165], v[58:61]
	v_mfma_f32_16x16x32_bf16 v[50:53], v[130:133], v[170:173], v[50:53]
	v_mfma_f32_16x16x32_bf16 v[42:45], v[138:141], v[170:173], v[42:45]
	v_mfma_f32_16x16x32_bf16 v[30:33], v[130:133], v[200:203], v[30:33]
	v_mfma_f32_16x16x32_bf16 v[26:29], v[138:141], v[200:203], v[26:29]
	v_mfma_f32_16x16x32_bf16 v[18:21], v[130:133], v[208:211], v[18:21]
	v_mfma_f32_16x16x32_bf16 v[10:13], v[138:141], v[208:211], v[10:13]
	v_mfma_f32_16x16x32_bf16 v[62:65], v[134:137], v[166:169], v[62:65]
	v_mfma_f32_16x16x32_bf16 v[58:61], v[142:145], v[166:169], v[58:61]
	v_mfma_f32_16x16x32_bf16 v[50:53], v[134:137], v[174:177], v[50:53]
	v_mfma_f32_16x16x32_bf16 v[42:45], v[142:145], v[174:177], v[42:45]
	v_mfma_f32_16x16x32_bf16 v[30:33], v[134:137], v[204:207], v[30:33]
	v_mfma_f32_16x16x32_bf16 v[26:29], v[142:145], v[204:207], v[26:29]
	v_mfma_f32_16x16x32_bf16 v[18:21], v[134:137], v[212:215], v[18:21]
	v_mfma_f32_16x16x32_bf16 v[10:13], v[142:145], v[212:215], v[10:13]
	s_setprio 0
	s_setprio 1
	v_mfma_f32_16x16x32_bf16 v[54:57], v[146:149], v[162:165], v[54:57]
	v_mfma_f32_16x16x32_bf16 v[46:49], v[154:157], v[162:165], v[46:49]
	v_mfma_f32_16x16x32_bf16 v[38:41], v[146:149], v[170:173], v[38:41]
	v_mfma_f32_16x16x32_bf16 v[34:37], v[154:157], v[170:173], v[34:37]
	v_mfma_f32_16x16x32_bf16 v[22:25], v[146:149], v[200:203], v[22:25]
	v_mfma_f32_16x16x32_bf16 v[14:17], v[154:157], v[200:203], v[14:17]
	v_mfma_f32_16x16x32_bf16 v[6:9], v[146:149], v[208:211], v[6:9]
	v_mfma_f32_16x16x32_bf16 v[2:5], v[154:157], v[208:211], v[2:5]
	v_mfma_f32_16x16x32_bf16 v[54:57], v[150:153], v[166:169], v[54:57]
	v_mfma_f32_16x16x32_bf16 v[46:49], v[158:161], v[166:169], v[46:49]
	v_mfma_f32_16x16x32_bf16 v[38:41], v[150:153], v[174:177], v[38:41]
	v_mfma_f32_16x16x32_bf16 v[34:37], v[158:161], v[174:177], v[34:37]
	v_mfma_f32_16x16x32_bf16 v[22:25], v[150:153], v[204:207], v[22:25]
	v_mfma_f32_16x16x32_bf16 v[14:17], v[158:161], v[204:207], v[14:17]
	v_mfma_f32_16x16x32_bf16 v[6:9], v[150:153], v[212:215], v[6:9]
	v_mfma_f32_16x16x32_bf16 v[2:5], v[158:161], v[212:215], v[2:5]
	s_setprio 0
	s_barrier
	s_add_i32 s41, 0, 0x18000
	s_add_i32 s53, 0, 0x1c000
	v_add_u32_e32 v142, s41, v1
	v_add_u32_e32 v158, s53, v1
	ds_read_b128 v[130:133], v142
	ds_read_b128 v[134:137], v142 offset:1024
	ds_read_b128 v[138:141], v142 offset:2048
	ds_read_b128 v[142:145], v142 offset:3072
	ds_read_b128 v[146:149], v158
	ds_read_b128 v[150:153], v158 offset:1024
	ds_read_b128 v[154:157], v158 offset:2048
	ds_read_b128 v[158:161], v158 offset:3072
	s_add_u32 s26, s26, 0x80000
	s_addc_u32 s27, s27, 0
	s_mov_b32 m0, s35
	s_nop 0
	ds_read_b128 v[162:165], v181 offset:32768
	ds_read_b128 v[166:169], v181 offset:33792
	ds_read_b128 v[170:173], v181 offset:34816
	ds_read_b128 v[174:177], v181 offset:35840
	ds_read_b128 v[200:203], v181 offset:36864
	ds_read_b128 v[204:207], v181 offset:37888
	ds_read_b128 v[208:211], v181 offset:38912
	ds_read_b128 v[212:215], v181 offset:39936
	global_load_lds_dwordx4 v188, s[26:27]
	s_nop 0
	s_mov_b32 m0, s42
	s_nop 0
	global_load_lds_dwordx4 v192, s[26:27]
	s_waitcnt vmcnt(8)
	s_waitcnt lgkmcnt(0)
	s_barrier
	s_setprio 1
	s_waitcnt lgkmcnt(0)
	v_mfma_f32_16x16x32_bf16 v[126:129], v[130:133], v[162:165], v[126:129]
	v_mfma_f32_16x16x32_bf16 v[122:125], v[138:141], v[162:165], v[122:125]
	v_mfma_f32_16x16x32_bf16 v[110:113], v[130:133], v[170:173], v[110:113]
	v_mfma_f32_16x16x32_bf16 v[106:109], v[138:141], v[170:173], v[106:109]
	v_mfma_f32_16x16x32_bf16 v[94:97], v[130:133], v[200:203], v[94:97]
	v_mfma_f32_16x16x32_bf16 v[90:93], v[138:141], v[200:203], v[90:93]
	v_mfma_f32_16x16x32_bf16 v[82:85], v[130:133], v[208:211], v[82:85]
	v_mfma_f32_16x16x32_bf16 v[74:77], v[138:141], v[208:211], v[74:77]
	v_mfma_f32_16x16x32_bf16 v[126:129], v[134:137], v[166:169], v[126:129]
	v_mfma_f32_16x16x32_bf16 v[122:125], v[142:145], v[166:169], v[122:125]
	v_mfma_f32_16x16x32_bf16 v[110:113], v[134:137], v[174:177], v[110:113]
	v_mfma_f32_16x16x32_bf16 v[106:109], v[142:145], v[174:177], v[106:109]
	v_mfma_f32_16x16x32_bf16 v[94:97], v[134:137], v[204:207], v[94:97]
	v_mfma_f32_16x16x32_bf16 v[90:93], v[142:145], v[204:207], v[90:93]
	v_mfma_f32_16x16x32_bf16 v[82:85], v[134:137], v[212:215], v[82:85]
	v_mfma_f32_16x16x32_bf16 v[74:77], v[142:145], v[212:215], v[74:77]
	s_setprio 0
	s_setprio 1
	v_mfma_f32_16x16x32_bf16 v[118:121], v[146:149], v[162:165], v[118:121]
	v_mfma_f32_16x16x32_bf16 v[114:117], v[154:157], v[162:165], v[114:117]
	v_mfma_f32_16x16x32_bf16 v[102:105], v[146:149], v[170:173], v[102:105]
	v_mfma_f32_16x16x32_bf16 v[98:101], v[154:157], v[170:173], v[98:101]
	v_mfma_f32_16x16x32_bf16 v[86:89], v[146:149], v[200:203], v[86:89]
	v_mfma_f32_16x16x32_bf16 v[78:81], v[154:157], v[200:203], v[78:81]
	v_mfma_f32_16x16x32_bf16 v[70:73], v[146:149], v[208:211], v[70:73]
	v_mfma_f32_16x16x32_bf16 v[66:69], v[154:157], v[208:211], v[66:69]
	v_mfma_f32_16x16x32_bf16 v[118:121], v[150:153], v[166:169], v[118:121]
	v_mfma_f32_16x16x32_bf16 v[114:117], v[158:161], v[166:169], v[114:117]
	v_mfma_f32_16x16x32_bf16 v[102:105], v[150:153], v[174:177], v[102:105]
	v_mfma_f32_16x16x32_bf16 v[98:101], v[158:161], v[174:177], v[98:101]
	v_mfma_f32_16x16x32_bf16 v[86:89], v[150:153], v[204:207], v[86:89]
	v_mfma_f32_16x16x32_bf16 v[78:81], v[158:161], v[204:207], v[78:81]
	v_mfma_f32_16x16x32_bf16 v[70:73], v[150:153], v[212:215], v[70:73]
	v_mfma_f32_16x16x32_bf16 v[66:69], v[158:161], v[212:215], v[66:69]
	s_setprio 0
	s_barrier
; #define PG8_STAGE(bufoff, gbase, voff) do { _Pragma("unroll") for (int _i = 0; _i < 2; ++_i) \
;         __builtin_amdgcn_global_load_lds((const unsigned*)((const char*)(gbase) + (voff)[_i]), (LAS unsigned*)(lds + (bufoff) + ldsw + _i * 8192), 16, 0, 0); } while (0)
; #define PG8_LDA(dst, b, h) do { _Pragma("unroll") for (int m = 0; m < 4; ++m) _Pragma("unroll") for (int k = 0; k < 2; ++k) dst[m][k] = *(const LAS bf16x8*)(lds + PG8_SA(b, h) + aoff + m * 2048 + k * 1024); } while (0)
; #define PG8_MMA(ai, bj, At, Bt) do { __builtin_amdgcn_s_setprio(1); _Pragma("unroll") for (int m = 0; m < 4; ++m) _Pragma("unroll") for (int n = 0; n < 2; ++n) _Pragma("unroll") for (int k = 0; k < 2; ++k) \
;         acc[ai][bj][m][n] = __builtin_amdgcn_mfma_f32_16x16x32_bf16(Bt[n][k], At[m][k], acc[ai][bj][m][n], 0, 0, 0); __builtin_amdgcn_s_setprio(0); } while (0)
; #define PG8_WAIT_V(n) asm volatile("s_waitcnt vmcnt(" #n ")" ::: "memory")
; #define PG8_WAIT_L(n) asm volatile("s_waitcnt lgkmcnt(" #n ")" ::: "memory")
; #define PG8_BAR __builtin_amdgcn_s_barrier()
; #define PG8_SCHED __builtin_amdgcn_sched_barrier(0)
; template <class Epi>
; __device__ __forceinline__ void gemm_phase(LAS unsigned char* lds, const Gemm g, const StaticOrder& S, const Epi& E) {
;     ...
;             PG8_LDA(At, 1, 1); PG8_STAGE(PG8_SB(1, 0), b3, voffB); PG8_STAGE(PG8_SB(1, 1), b3 + hstepB, voffB); PG8_STAGE(PG8_SA(1, 0), a3, voffA);
;             PG8_WAIT_V(8); PG8_WAIT_L(0); PG8_BAR; PG8_MMA(1, 0, At, B0); PG8_MMA(1, 1, At, B1); PG8_BAR; PG8_SCHED;
;         }
;         if (wr == 0) PG8_BAR;
	s_add_i32 s26, s41, s30
	v_lshl_add_u64 v[178:179], v[178:179], 0, s[84:85]
	s_mov_b32 m0, s26
	ds_read_b128 v[162:165], v181 offset:49152
	ds_read_b128 v[166:169], v181 offset:50176
	ds_read_b128 v[170:173], v181 offset:51200
	ds_read_b128 v[174:177], v181 offset:52224
	ds_read_b128 v[200:203], v181 offset:53248
	ds_read_b128 v[204:207], v181 offset:54272
	ds_read_b128 v[208:211], v181 offset:55296
	ds_read_b128 v[212:215], v181 offset:56320
	global_load_lds_dwordx4 v[178:179], off
	s_add_i32 m0, s26, 0x2000
	s_add_u32 s14, s14, 0x80080
	v_lshl_add_u64 v[178:179], v[184:185], 0, s[84:85]
	s_addc_u32 s15, s15, 0
	s_add_i32 s26, s53, s30
	global_load_lds_dwordx4 v[178:179], off
	s_nop 0
	s_mov_b32 m0, s26
	s_nop 0
	global_load_lds_dwordx4 v190, s[14:15]
	s_nop 0
	s_add_i32 m0, s26, 0x2000
	s_nop 0
	global_load_lds_dwordx4 v194, s[14:15]
	v_lshl_add_u64 v[178:179], v[216:217], 0, s[84:85]
	s_mov_b32 m0, s68
	s_nop 0
	global_load_lds_dwordx4 v[178:179], off
	v_lshl_add_u64 v[178:179], v[218:219], 0, s[84:85]
	s_mov_b32 m0, s69
	s_nop 0
	global_load_lds_dwordx4 v[178:179], off
	s_waitcnt vmcnt(8)
	s_waitcnt lgkmcnt(0)
	s_barrier
	s_setprio 1
	s_waitcnt lgkmcnt(0)
	v_mfma_f32_16x16x32_bf16 v[62:65], v[130:133], v[162:165], v[62:65]
	v_mfma_f32_16x16x32_bf16 v[58:61], v[138:141], v[162:165], v[58:61]
	v_mfma_f32_16x16x32_bf16 v[50:53], v[130:133], v[170:173], v[50:53]
	v_mfma_f32_16x16x32_bf16 v[42:45], v[138:141], v[170:173], v[42:45]
	v_mfma_f32_16x16x32_bf16 v[30:33], v[130:133], v[200:203], v[30:33]
	v_mfma_f32_16x16x32_bf16 v[26:29], v[138:141], v[200:203], v[26:29]
	v_mfma_f32_16x16x32_bf16 v[18:21], v[130:133], v[208:211], v[18:21]
	v_mfma_f32_16x16x32_bf16 v[10:13], v[138:141], v[208:211], v[10:13]
	v_mfma_f32_16x16x32_bf16 v[62:65], v[134:137], v[166:169], v[62:65]
	v_mfma_f32_16x16x32_bf16 v[58:61], v[142:145], v[166:169], v[58:61]
	v_mfma_f32_16x16x32_bf16 v[50:53], v[134:137], v[174:177], v[50:53]
	v_mfma_f32_16x16x32_bf16 v[42:45], v[142:145], v[174:177], v[42:45]
	v_mfma_f32_16x16x32_bf16 v[30:33], v[134:137], v[204:207], v[30:33]
	v_mfma_f32_16x16x32_bf16 v[26:29], v[142:145], v[204:207], v[26:29]
	v_mfma_f32_16x16x32_bf16 v[18:21], v[134:137], v[212:215], v[18:21]
	v_mfma_f32_16x16x32_bf16 v[10:13], v[142:145], v[212:215], v[10:13]
	s_setprio 0
	s_setprio 1
	v_mfma_f32_16x16x32_bf16 v[54:57], v[146:149], v[162:165], v[54:57]
	v_mfma_f32_16x16x32_bf16 v[46:49], v[154:157], v[162:165], v[46:49]
	v_mfma_f32_16x16x32_bf16 v[38:41], v[146:149], v[170:173], v[38:41]
	v_mfma_f32_16x16x32_bf16 v[34:37], v[154:157], v[170:173], v[34:37]
	v_mfma_f32_16x16x32_bf16 v[22:25], v[146:149], v[200:203], v[22:25]
	v_mfma_f32_16x16x32_bf16 v[14:17], v[154:157], v[200:203], v[14:17]
	v_mfma_f32_16x16x32_bf16 v[6:9], v[146:149], v[208:211], v[6:9]
	v_mfma_f32_16x16x32_bf16 v[2:5], v[154:157], v[208:211], v[2:5]
	v_mfma_f32_16x16x32_bf16 v[54:57], v[150:153], v[166:169], v[54:57]
	v_mfma_f32_16x16x32_bf16 v[46:49], v[158:161], v[166:169], v[46:49]
	v_mfma_f32_16x16x32_bf16 v[38:41], v[150:153], v[174:177], v[38:41]
	v_mfma_f32_16x16x32_bf16 v[34:37], v[158:161], v[174:177], v[34:37]
	v_mfma_f32_16x16x32_bf16 v[22:25], v[150:153], v[204:207], v[22:25]
	v_mfma_f32_16x16x32_bf16 v[14:17], v[158:161], v[204:207], v[14:17]
	v_mfma_f32_16x16x32_bf16 v[6:9], v[150:153], v[212:215], v[6:9]
	v_mfma_f32_16x16x32_bf16 v[2:5], v[158:161], v[212:215], v[2:5]
	s_setprio 0
	s_barrier
	s_add_i32 s52, s52, 2
	s_add_u32 s24, s24, 0x100
	s_addc_u32 s25, s25, 0
	s_add_u32 s17, s17, 0x100
	s_addc_u32 s40, s40, 0
	s_cmp_gt_u32 s52, 29
	s_cbranch_scc0 .LBB0_2035
	s_and_b64 vcc, exec, s[10:11]
	s_cbranch_vccz .LBB0_2038
	s_barrier

; #define PG8_STAGE(bufoff, gbase, voff) do { _Pragma("unroll") for (int _i = 0; _i < 2; ++_i) \
;         __builtin_amdgcn_global_load_lds((const unsigned*)((const char*)(gbase) + (voff)[_i]), (LAS unsigned*)(lds + (bufoff) + ldsw + _i * 8192), 16, 0, 0); } while (0)
; #define PG8_LDA(dst, b, h) do { _Pragma("unroll") for (int m = 0; m < 4; ++m) _Pragma("unroll") for (int k = 0; k < 2; ++k) dst[m][k] = *(const LAS bf16x8*)(lds + PG8_SA(b, h) + aoff + m * 2048 + k * 1024); } while (0)
; #define PG8_LDB(dst, b, h) do { _Pragma("unroll") for (int n = 0; n < 2; ++n) _Pragma("unroll") for (int k = 0; k < 2; ++k) dst[n][k] = *(const LAS bf16x8*)(lds + PG8_SB(b, h) + boff + n * 2048 + k * 1024); } while (0)
; #define PG8_MMA(ai, bj, At, Bt) do { __builtin_amdgcn_s_setprio(1); _Pragma("unroll") for (int m = 0; m < 4; ++m) _Pragma("unroll") for (int n = 0; n < 2; ++n) _Pragma("unroll") for (int k = 0; k < 2; ++k) \
;         acc[ai][bj][m][n] = __builtin_amdgcn_mfma_f32_16x16x32_bf16(Bt[n][k], At[m][k], acc[ai][bj][m][n], 0, 0, 0); __builtin_amdgcn_s_setprio(0); } while (0)
; #define PG8_WAIT_V(n) asm volatile("s_waitcnt vmcnt(" #n ")" ::: "memory")
; #define PG8_WAIT_L(n) asm volatile("s_waitcnt lgkmcnt(" #n ")" ::: "memory")
; #define PG8_BAR __builtin_amdgcn_s_barrier()
; #define PG8_SCHED __builtin_amdgcn_sched_barrier(0)
; template <class Epi>
; __device__ __forceinline__ void gemm_phase(LAS unsigned char* lds, const Gemm g, const StaticOrder& S, const Epi& E) {
;     ...
;             const bool last = (t == nt - 2);
;             const char* a1 = cA + (size_t)(t + 1) * kstep;
;             const char* a2 = last ? nA : cA + (size_t)(t + 2) * kstep; const char* b2 = last ? nB : cB + (size_t)(t + 2) * kstep;
;             const char* a3 = a2 + kstep; const char* b3 = b2 + kstep;
;             PG8_LDB(B0, 0, 0); PG8_LDB(B1, 0, 1); PG8_SCHED; PG8_LDA(At, 0, 0); PG8_STAGE(PG8_SA(1, 1), a1 + hstepA, voffA);
;             PG8_WAIT_V(8); PG8_WAIT_L(0); PG8_BAR; PG8_MMA(0, 0, At, B0); PG8_MMA(0, 1, At, B1); PG8_BAR; PG8_SCHED;
;             PG8_LDA(At, 0, 1); PG8_STAGE(PG8_SB(0, 0), b2, voffB); PG8_STAGE(PG8_SB(0, 1), b2 + hstepB, voffB); PG8_STAGE(PG8_SA(0, 0), a2, voffA);
;             PG8_WAIT_V(8); PG8_WAIT_L(0); PG8_BAR; PG8_MMA(1, 0, At, B0); PG8_MMA(1, 1, At, B1); PG8_BAR; PG8_SCHED;
.LBB0_2130:
	s_add_u32 s14, s20, 0xfff80080
	s_addc_u32 s15, s21, -1
	s_add_i32 s62, 0, 0x10000
	s_cmp_eq_u32 s41, 28
	s_cselect_b32 s23, s3, s15
	s_cselect_b32 s22, s11, s14
	v_add_u32_e32 v142, s62, v1
	s_cselect_b32 s15, s9, s53
	s_cselect_b32 s14, s40, s52
	s_add_i32 s64, 0, 0x14000
	ds_read_b128 v[146:149], v142
	ds_read_b128 v[150:153], v142 offset:1024
	ds_read_b128 v[154:157], v142 offset:2048
	ds_read_b128 v[158:161], v142 offset:3072
	v_add_u32_e32 v142, s64, v1
	ds_read_b128 v[162:165], v142
	ds_read_b128 v[166:169], v142 offset:1024
	ds_read_b128 v[170:173], v142 offset:2048
	ds_read_b128 v[174:177], v142 offset:3072
	s_nop 0
	s_add_i32 m0, s19, 0xc000
	ds_read_b128 v[188:191], v144
	ds_read_b128 v[192:195], v144 offset:1024
	ds_read_b128 v[196:199], v144 offset:2048
	ds_read_b128 v[200:203], v144 offset:3072
	ds_read_b128 v[204:207], v144 offset:4096
	ds_read_b128 v[208:211], v144 offset:5120
	ds_read_b128 v[212:215], v144 offset:6144
	ds_read_b128 v[216:219], v144 offset:7168
	global_load_lds_dwordx4 v138, s[20:21]
	s_nop 0
	s_add_i32 m0, s19, 0xe000
	s_nop 0
	global_load_lds_dwordx4 v140, s[20:21]
	s_waitcnt vmcnt(8)
	s_waitcnt lgkmcnt(0)
	s_barrier
	s_setprio 1
	s_waitcnt lgkmcnt(0)
	v_mfma_f32_16x16x32_bf16 v[126:129], v[146:149], v[188:191], v[126:129]
	v_mfma_f32_16x16x32_bf16 v[122:125], v[154:157], v[188:191], v[122:125]
	v_mfma_f32_16x16x32_bf16 v[110:113], v[146:149], v[196:199], v[110:113]
	v_mfma_f32_16x16x32_bf16 v[106:109], v[154:157], v[196:199], v[106:109]
	v_mfma_f32_16x16x32_bf16 v[94:97], v[146:149], v[204:207], v[94:97]
	v_mfma_f32_16x16x32_bf16 v[90:93], v[154:157], v[204:207], v[90:93]
	v_mfma_f32_16x16x32_bf16 v[78:81], v[146:149], v[212:215], v[78:81]
	v_mfma_f32_16x16x32_bf16 v[74:77], v[154:157], v[212:215], v[74:77]
	v_mfma_f32_16x16x32_bf16 v[126:129], v[150:153], v[192:195], v[126:129]
	v_mfma_f32_16x16x32_bf16 v[122:125], v[158:161], v[192:195], v[122:125]
	v_mfma_f32_16x16x32_bf16 v[110:113], v[150:153], v[200:203], v[110:113]
	v_mfma_f32_16x16x32_bf16 v[106:109], v[158:161], v[200:203], v[106:109]
	v_mfma_f32_16x16x32_bf16 v[94:97], v[150:153], v[208:211], v[94:97]
	v_mfma_f32_16x16x32_bf16 v[90:93], v[158:161], v[208:211], v[90:93]
	v_mfma_f32_16x16x32_bf16 v[78:81], v[150:153], v[216:219], v[78:81]
	v_mfma_f32_16x16x32_bf16 v[74:77], v[158:161], v[216:219], v[74:77]
	s_setprio 0
	s_setprio 1
	v_mfma_f32_16x16x32_bf16 v[118:121], v[162:165], v[188:191], v[118:121]
	v_mfma_f32_16x16x32_bf16 v[114:117], v[170:173], v[188:191], v[114:117]
	v_mfma_f32_16x16x32_bf16 v[102:105], v[162:165], v[196:199], v[102:105]
	v_mfma_f32_16x16x32_bf16 v[98:101], v[170:173], v[196:199], v[98:101]
	v_mfma_f32_16x16x32_bf16 v[86:89], v[162:165], v[204:207], v[86:89]
	v_mfma_f32_16x16x32_bf16 v[82:85], v[170:173], v[204:207], v[82:85]
	v_mfma_f32_16x16x32_bf16 v[70:73], v[162:165], v[212:215], v[70:73]
	v_mfma_f32_16x16x32_bf16 v[66:69], v[170:173], v[212:215], v[66:69]
	v_mfma_f32_16x16x32_bf16 v[118:121], v[166:169], v[192:195], v[118:121]
	v_mfma_f32_16x16x32_bf16 v[114:117], v[174:177], v[192:195], v[114:117]
	v_mfma_f32_16x16x32_bf16 v[102:105], v[166:169], v[200:203], v[102:105]
	v_mfma_f32_16x16x32_bf16 v[98:101], v[174:177], v[200:203], v[98:101]
	v_mfma_f32_16x16x32_bf16 v[86:89], v[166:169], v[208:211], v[86:89]
	v_mfma_f32_16x16x32_bf16 v[82:85], v[174:177], v[208:211], v[82:85]
	v_mfma_f32_16x16x32_bf16 v[70:73], v[166:169], v[216:219], v[70:73]
	v_mfma_f32_16x16x32_bf16 v[66:69], v[174:177], v[216:219], v[66:69]
	s_setprio 0
	s_barrier
	s_add_i32 s62, s62, s27
	v_lshl_add_u64 v[142:143], s[14:15], 0, v[132:133]
	s_mov_b32 m0, s62
	ds_read_b128 v[188:191], v144 offset:16384
	ds_read_b128 v[192:195], v144 offset:17408
	ds_read_b128 v[196:199], v144 offset:18432
	ds_read_b128 v[200:203], v144 offset:19456
	ds_read_b128 v[204:207], v144 offset:20480
	ds_read_b128 v[208:211], v144 offset:21504
	ds_read_b128 v[212:215], v144 offset:22528
	ds_read_b128 v[216:219], v144 offset:23552
	global_load_lds_dwordx4 v132, s[14:15]
	s_add_i32 m0, s62, 0x2000
	s_add_u32 s62, s14, 0x80000
	v_lshl_add_u64 v[178:179], s[14:15], 0, v[136:137]
	s_addc_u32 s63, s15, 0
	s_add_i32 s64, s64, s27
	global_load_lds_dwordx4 v136, s[14:15]
	s_nop 0
	s_mov_b32 m0, s64
	v_lshl_add_u64 v[220:221], s[22:23], 0, v[134:135]
	global_load_lds_dwordx4 v132, s[62:63]
	s_nop 0
	s_add_i32 m0, s64, 0x2000
	s_nop 0
	global_load_lds_dwordx4 v136, s[62:63]
	v_lshl_add_u64 v[184:185], s[22:23], 0, v[130:131]
	s_mov_b32 m0, s19
	s_nop 0
	global_load_lds_dwordx4 v130, s[22:23]
	s_mov_b32 m0, s28
	s_nop 0
	global_load_lds_dwordx4 v134, s[22:23]
	s_waitcnt vmcnt(8)
	s_waitcnt lgkmcnt(0)
	s_barrier
; #define PG8_STAGE(bufoff, gbase, voff) do { _Pragma("unroll") for (int _i = 0; _i < 2; ++_i) \
;         __builtin_amdgcn_global_load_lds((const unsigned*)((const char*)(gbase) + (voff)[_i]), (LAS unsigned*)(lds + (bufoff) + ldsw + _i * 8192), 16, 0, 0); } while (0)
; #define PG8_LDA(dst, b, h) do { _Pragma("unroll") for (int m = 0; m < 4; ++m) _Pragma("unroll") for (int k = 0; k < 2; ++k) dst[m][k] = *(const LAS bf16x8*)(lds + PG8_SA(b, h) + aoff + m * 2048 + k * 1024); } while (0)
; #define PG8_LDB(dst, b, h) do { _Pragma("unroll") for (int n = 0; n < 2; ++n) _Pragma("unroll") for (int k = 0; k < 2; ++k) dst[n][k] = *(const LAS bf16x8*)(lds + PG8_SB(b, h) + boff + n * 2048 + k * 1024); } while (0)
; #define PG8_MMA(ai, bj, At, Bt) do { __builtin_amdgcn_s_setprio(1); _Pragma("unroll") for (int m = 0; m < 4; ++m) _Pragma("unroll") for (int n = 0; n < 2; ++n) _Pragma("unroll") for (int k = 0; k < 2; ++k) \
;         acc[ai][bj][m][n] = __builtin_amdgcn_mfma_f32_16x16x32_bf16(Bt[n][k], At[m][k], acc[ai][bj][m][n], 0, 0, 0); __builtin_amdgcn_s_setprio(0); } while (0)
; #define PG8_WAIT_V(n) asm volatile("s_waitcnt vmcnt(" #n ")" ::: "memory")
; #define PG8_WAIT_L(n) asm volatile("s_waitcnt lgkmcnt(" #n ")" ::: "memory")
; #define PG8_BAR __builtin_amdgcn_s_barrier()
; #define PG8_SCHED __builtin_amdgcn_sched_barrier(0)
; template <class Epi>
; __device__ __forceinline__ void gemm_phase(LAS unsigned char* lds, const Gemm g, const StaticOrder& S, const Epi& E) {
;     ...
;             PG8_WAIT_V(8); PG8_WAIT_L(0); PG8_BAR; PG8_MMA(1, 0, At, B0); PG8_MMA(1, 1, At, B1); PG8_BAR; PG8_SCHED;
;             PG8_LDB(B0, 1, 0); PG8_LDB(B1, 1, 1); PG8_SCHED; PG8_LDA(At, 1, 0); PG8_STAGE(PG8_SA(0, 1), a2 + hstepA, voffA);
;             PG8_WAIT_V(8); PG8_WAIT_L(0); PG8_BAR; PG8_MMA(0, 0, At, B0); PG8_MMA(0, 1, At, B1); PG8_BAR; PG8_SCHED;
	s_setprio 1
	s_waitcnt lgkmcnt(0)
	v_mfma_f32_16x16x32_bf16 v[62:65], v[146:149], v[188:191], v[62:65]
	v_mfma_f32_16x16x32_bf16 v[58:61], v[154:157], v[188:191], v[58:61]
	v_mfma_f32_16x16x32_bf16 v[46:49], v[146:149], v[196:199], v[46:49]
	v_mfma_f32_16x16x32_bf16 v[42:45], v[154:157], v[196:199], v[42:45]
	v_mfma_f32_16x16x32_bf16 v[30:33], v[146:149], v[204:207], v[30:33]
	v_mfma_f32_16x16x32_bf16 v[26:29], v[154:157], v[204:207], v[26:29]
	v_mfma_f32_16x16x32_bf16 v[14:17], v[146:149], v[212:215], v[14:17]
	v_mfma_f32_16x16x32_bf16 v[10:13], v[154:157], v[212:215], v[10:13]
	v_mfma_f32_16x16x32_bf16 v[62:65], v[150:153], v[192:195], v[62:65]
	v_mfma_f32_16x16x32_bf16 v[58:61], v[158:161], v[192:195], v[58:61]
	v_mfma_f32_16x16x32_bf16 v[46:49], v[150:153], v[200:203], v[46:49]
	v_mfma_f32_16x16x32_bf16 v[42:45], v[158:161], v[200:203], v[42:45]
	v_mfma_f32_16x16x32_bf16 v[30:33], v[150:153], v[208:211], v[30:33]
	v_mfma_f32_16x16x32_bf16 v[26:29], v[158:161], v[208:211], v[26:29]
	v_mfma_f32_16x16x32_bf16 v[14:17], v[150:153], v[216:219], v[14:17]
	v_mfma_f32_16x16x32_bf16 v[10:13], v[158:161], v[216:219], v[10:13]
	s_setprio 0
	s_setprio 1
	v_mfma_f32_16x16x32_bf16 v[54:57], v[162:165], v[188:191], v[54:57]
	v_mfma_f32_16x16x32_bf16 v[50:53], v[170:173], v[188:191], v[50:53]
	v_mfma_f32_16x16x32_bf16 v[38:41], v[162:165], v[196:199], v[38:41]
	v_mfma_f32_16x16x32_bf16 v[34:37], v[170:173], v[196:199], v[34:37]
	v_mfma_f32_16x16x32_bf16 v[22:25], v[162:165], v[204:207], v[22:25]
	v_mfma_f32_16x16x32_bf16 v[18:21], v[170:173], v[204:207], v[18:21]
	v_mfma_f32_16x16x32_bf16 v[6:9], v[162:165], v[212:215], v[6:9]
	v_mfma_f32_16x16x32_bf16 v[2:5], v[170:173], v[212:215], v[2:5]
	v_mfma_f32_16x16x32_bf16 v[54:57], v[166:169], v[192:195], v[54:57]
	v_mfma_f32_16x16x32_bf16 v[50:53], v[174:177], v[192:195], v[50:53]
	v_mfma_f32_16x16x32_bf16 v[38:41], v[166:169], v[200:203], v[38:41]
	v_mfma_f32_16x16x32_bf16 v[34:37], v[174:177], v[200:203], v[34:37]
	v_mfma_f32_16x16x32_bf16 v[22:25], v[166:169], v[208:211], v[22:25]
	v_mfma_f32_16x16x32_bf16 v[18:21], v[174:177], v[208:211], v[18:21]
	v_mfma_f32_16x16x32_bf16 v[6:9], v[166:169], v[216:219], v[6:9]
	v_mfma_f32_16x16x32_bf16 v[2:5], v[174:177], v[216:219], v[2:5]
	s_setprio 0
	s_barrier
	s_add_i32 s62, 0, 0x18000
	v_add_u32_e32 v145, s62, v1
	s_add_i32 s63, 0, 0x1c000
	ds_read_b128 v[146:149], v145
	ds_read_b128 v[150:153], v145 offset:1024
	ds_read_b128 v[154:157], v145 offset:2048
	ds_read_b128 v[158:161], v145 offset:3072
	v_add_u32_e32 v145, s63, v1
	ds_read_b128 v[162:165], v145
	ds_read_b128 v[166:169], v145 offset:1024
	ds_read_b128 v[170:173], v145 offset:2048
	ds_read_b128 v[174:177], v145 offset:3072
	s_add_u32 s22, s22, 0x80000
	s_addc_u32 s23, s23, 0
	s_mov_b32 m0, s29
	s_nop 0
	ds_read_b128 v[188:191], v144 offset:32768
	ds_read_b128 v[192:195], v144 offset:33792
	ds_read_b128 v[196:199], v144 offset:34816
	ds_read_b128 v[200:203], v144 offset:35840
	ds_read_b128 v[204:207], v144 offset:36864
	ds_read_b128 v[208:211], v144 offset:37888
	ds_read_b128 v[212:215], v144 offset:38912
	ds_read_b128 v[216:219], v144 offset:39936
	global_load_lds_dwordx4 v130, s[22:23]
	s_nop 0
	s_mov_b32 m0, s30
	s_nop 0
	global_load_lds_dwordx4 v134, s[22:23]
	s_waitcnt vmcnt(8)
	s_waitcnt lgkmcnt(0)
	s_barrier
	s_setprio 1
	s_waitcnt lgkmcnt(0)
	v_mfma_f32_16x16x32_bf16 v[126:129], v[146:149], v[188:191], v[126:129]
	v_mfma_f32_16x16x32_bf16 v[122:125], v[154:157], v[188:191], v[122:125]
	v_mfma_f32_16x16x32_bf16 v[110:113], v[146:149], v[196:199], v[110:113]
	v_mfma_f32_16x16x32_bf16 v[106:109], v[154:157], v[196:199], v[106:109]
	v_mfma_f32_16x16x32_bf16 v[94:97], v[146:149], v[204:207], v[94:97]
	v_mfma_f32_16x16x32_bf16 v[90:93], v[154:157], v[204:207], v[90:93]
	v_mfma_f32_16x16x32_bf16 v[78:81], v[146:149], v[212:215], v[78:81]
	v_mfma_f32_16x16x32_bf16 v[74:77], v[154:157], v[212:215], v[74:77]
	v_mfma_f32_16x16x32_bf16 v[126:129], v[150:153], v[192:195], v[126:129]
	v_mfma_f32_16x16x32_bf16 v[122:125], v[158:161], v[192:195], v[122:125]
	v_mfma_f32_16x16x32_bf16 v[110:113], v[150:153], v[200:203], v[110:113]
	v_mfma_f32_16x16x32_bf16 v[106:109], v[158:161], v[200:203], v[106:109]
	v_mfma_f32_16x16x32_bf16 v[94:97], v[150:153], v[208:211], v[94:97]
	v_mfma_f32_16x16x32_bf16 v[90:93], v[158:161], v[208:211], v[90:93]
	v_mfma_f32_16x16x32_bf16 v[78:81], v[150:153], v[216:219], v[78:81]
	v_mfma_f32_16x16x32_bf16 v[74:77], v[158:161], v[216:219], v[74:77]
	s_setprio 0
	s_setprio 1
	v_mfma_f32_16x16x32_bf16 v[118:121], v[162:165], v[188:191], v[118:121]
	v_mfma_f32_16x16x32_bf16 v[114:117], v[170:173], v[188:191], v[114:117]
	v_mfma_f32_16x16x32_bf16 v[102:105], v[162:165], v[196:199], v[102:105]
	v_mfma_f32_16x16x32_bf16 v[98:101], v[170:173], v[196:199], v[98:101]
	v_mfma_f32_16x16x32_bf16 v[86:89], v[162:165], v[204:207], v[86:89]
	v_mfma_f32_16x16x32_bf16 v[82:85], v[170:173], v[204:207], v[82:85]
	v_mfma_f32_16x16x32_bf16 v[70:73], v[162:165], v[212:215], v[70:73]
	v_mfma_f32_16x16x32_bf16 v[66:69], v[170:173], v[212:215], v[66:69]
	v_mfma_f32_16x16x32_bf16 v[118:121], v[166:169], v[192:195], v[118:121]
	v_mfma_f32_16x16x32_bf16 v[114:117], v[174:177], v[192:195], v[114:117]
	v_mfma_f32_16x16x32_bf16 v[102:105], v[166:169], v[200:203], v[102:105]
	v_mfma_f32_16x16x32_bf16 v[98:101], v[174:177], v[200:203], v[98:101]
	v_mfma_f32_16x16x32_bf16 v[86:89], v[166:169], v[208:211], v[86:89]
	v_mfma_f32_16x16x32_bf16 v[82:85], v[174:177], v[208:211], v[82:85]
	v_mfma_f32_16x16x32_bf16 v[70:73], v[166:169], v[216:219], v[70:73]
	v_mfma_f32_16x16x32_bf16 v[66:69], v[174:177], v[216:219], v[66:69]
	s_setprio 0
	s_barrier
; #define PG8_STAGE(bufoff, gbase, voff) do { _Pragma("unroll") for (int _i = 0; _i < 2; ++_i) \
;         __builtin_amdgcn_global_load_lds((const unsigned*)((const char*)(gbase) + (voff)[_i]), (LAS unsigned*)(lds + (bufoff) + ldsw + _i * 8192), 16, 0, 0); } while (0)
; #define PG8_LDA(dst, b, h) do { _Pragma("unroll") for (int m = 0; m < 4; ++m) _Pragma("unroll") for (int k = 0; k < 2; ++k) dst[m][k] = *(const LAS bf16x8*)(lds + PG8_SA(b, h) + aoff + m * 2048 + k * 1024); } while (0)
; #define PG8_MMA(ai, bj, At, Bt) do { __builtin_amdgcn_s_setprio(1); _Pragma("unroll") for (int m = 0; m < 4; ++m) _Pragma("unroll") for (int n = 0; n < 2; ++n) _Pragma("unroll") for (int k = 0; k < 2; ++k) \
;         acc[ai][bj][m][n] = __builtin_amdgcn_mfma_f32_16x16x32_bf16(Bt[n][k], At[m][k], acc[ai][bj][m][n], 0, 0, 0); __builtin_amdgcn_s_setprio(0); } while (0)
; #define PG8_WAIT_V(n) asm volatile("s_waitcnt vmcnt(" #n ")" ::: "memory")
; #define PG8_WAIT_L(n) asm volatile("s_waitcnt lgkmcnt(" #n ")" ::: "memory")
; #define PG8_BAR __builtin_amdgcn_s_barrier()
; #define PG8_SCHED __builtin_amdgcn_sched_barrier(0)
; template <class Epi>
; __device__ __forceinline__ void gemm_phase(LAS unsigned char* lds, const Gemm g, const StaticOrder& S, const Epi& E) {
;     ...
;             PG8_LDA(At, 1, 1); PG8_STAGE(PG8_SB(1, 0), b3, voffB); PG8_STAGE(PG8_SB(1, 1), b3 + hstepB, voffB); PG8_STAGE(PG8_SA(1, 0), a3, voffA);
;             PG8_WAIT_V(8); PG8_WAIT_L(0); PG8_BAR; PG8_MMA(1, 0, At, B0); PG8_MMA(1, 1, At, B1); PG8_BAR; PG8_SCHED;
;         }
;         if (wr == 0) PG8_BAR;
	s_add_i32 s22, s62, s27
	v_lshl_add_u64 v[142:143], v[142:143], 0, s[84:85]
	s_mov_b32 m0, s22
	ds_read_b128 v[188:191], v144 offset:49152
	ds_read_b128 v[192:195], v144 offset:50176
	ds_read_b128 v[196:199], v144 offset:51200
	ds_read_b128 v[200:203], v144 offset:52224
	ds_read_b128 v[204:207], v144 offset:53248
	ds_read_b128 v[208:211], v144 offset:54272
	ds_read_b128 v[212:215], v144 offset:55296
	ds_read_b128 v[216:219], v144 offset:56320
	global_load_lds_dwordx4 v[142:143], off
	s_add_i32 m0, s22, 0x2000
	s_add_u32 s14, s14, 0x80080
	v_lshl_add_u64 v[142:143], v[178:179], 0, s[84:85]
	s_addc_u32 s15, s15, 0
	s_add_i32 s22, s63, s27
	global_load_lds_dwordx4 v[142:143], off
	s_nop 0
	s_mov_b32 m0, s22
	s_nop 0
	global_load_lds_dwordx4 v132, s[14:15]
	s_nop 0
	s_add_i32 m0, s22, 0x2000
	s_nop 0
	global_load_lds_dwordx4 v136, s[14:15]
	v_lshl_add_u64 v[142:143], v[184:185], 0, s[84:85]
	s_mov_b32 m0, s34
	s_nop 0
	global_load_lds_dwordx4 v[142:143], off
	v_lshl_add_u64 v[142:143], v[220:221], 0, s[84:85]
	s_mov_b32 m0, s35
	s_nop 0
	global_load_lds_dwordx4 v[142:143], off
	s_waitcnt vmcnt(8)
	s_waitcnt lgkmcnt(0)
	s_barrier
	s_setprio 1
	s_waitcnt lgkmcnt(0)
	v_mfma_f32_16x16x32_bf16 v[62:65], v[146:149], v[188:191], v[62:65]
	v_mfma_f32_16x16x32_bf16 v[58:61], v[154:157], v[188:191], v[58:61]
	v_mfma_f32_16x16x32_bf16 v[46:49], v[146:149], v[196:199], v[46:49]
	v_mfma_f32_16x16x32_bf16 v[42:45], v[154:157], v[196:199], v[42:45]
	v_mfma_f32_16x16x32_bf16 v[30:33], v[146:149], v[204:207], v[30:33]
	v_mfma_f32_16x16x32_bf16 v[26:29], v[154:157], v[204:207], v[26:29]
	v_mfma_f32_16x16x32_bf16 v[14:17], v[146:149], v[212:215], v[14:17]
	v_mfma_f32_16x16x32_bf16 v[10:13], v[154:157], v[212:215], v[10:13]
	v_mfma_f32_16x16x32_bf16 v[62:65], v[150:153], v[192:195], v[62:65]
	v_mfma_f32_16x16x32_bf16 v[58:61], v[158:161], v[192:195], v[58:61]
	v_mfma_f32_16x16x32_bf16 v[46:49], v[150:153], v[200:203], v[46:49]
	v_mfma_f32_16x16x32_bf16 v[42:45], v[158:161], v[200:203], v[42:45]
	v_mfma_f32_16x16x32_bf16 v[30:33], v[150:153], v[208:211], v[30:33]
	v_mfma_f32_16x16x32_bf16 v[26:29], v[158:161], v[208:211], v[26:29]
	v_mfma_f32_16x16x32_bf16 v[14:17], v[150:153], v[216:219], v[14:17]
	v_mfma_f32_16x16x32_bf16 v[10:13], v[158:161], v[216:219], v[10:13]
	s_setprio 0
	s_setprio 1
	v_mfma_f32_16x16x32_bf16 v[54:57], v[162:165], v[188:191], v[54:57]
	v_mfma_f32_16x16x32_bf16 v[50:53], v[170:173], v[188:191], v[50:53]
	v_mfma_f32_16x16x32_bf16 v[38:41], v[162:165], v[196:199], v[38:41]
	v_mfma_f32_16x16x32_bf16 v[34:37], v[170:173], v[196:199], v[34:37]
	v_mfma_f32_16x16x32_bf16 v[22:25], v[162:165], v[204:207], v[22:25]
	v_mfma_f32_16x16x32_bf16 v[18:21], v[170:173], v[204:207], v[18:21]
	v_mfma_f32_16x16x32_bf16 v[6:9], v[162:165], v[212:215], v[6:9]
	v_mfma_f32_16x16x32_bf16 v[2:5], v[170:173], v[212:215], v[2:5]
	v_mfma_f32_16x16x32_bf16 v[54:57], v[166:169], v[192:195], v[54:57]
	v_mfma_f32_16x16x32_bf16 v[50:53], v[174:177], v[192:195], v[50:53]
	v_mfma_f32_16x16x32_bf16 v[38:41], v[166:169], v[200:203], v[38:41]
	v_mfma_f32_16x16x32_bf16 v[34:37], v[174:177], v[200:203], v[34:37]
	v_mfma_f32_16x16x32_bf16 v[22:25], v[166:169], v[208:211], v[22:25]
	v_mfma_f32_16x16x32_bf16 v[18:21], v[174:177], v[208:211], v[18:21]
	v_mfma_f32_16x16x32_bf16 v[6:9], v[166:169], v[216:219], v[6:9]
	v_mfma_f32_16x16x32_bf16 v[2:5], v[174:177], v[216:219], v[2:5]
	s_setprio 0
	s_barrier
	s_add_i32 s41, s41, 2
	s_add_u32 s20, s20, 0x100
	s_addc_u32 s21, s21, 0
	s_add_u32 s52, s52, 0x100
	s_addc_u32 s53, s53, 0
	s_cmp_gt_u32 s41, 29
	s_cbranch_scc0 .LBB0_2130
	s_and_b64 vcc, exec, s[6:7]
	s_cbranch_vccz .LBB0_2133
	s_barrier

; #define PG8_STAGE(bufoff, gbase, voff) do { _Pragma("unroll") for (int _i = 0; _i < 2; ++_i) \
;         __builtin_amdgcn_global_load_lds((const unsigned*)((const char*)(gbase) + (voff)[_i]), (LAS unsigned*)(lds + (bufoff) + ldsw + _i * 8192), 16, 0, 0); } while (0)
; #define PG8_LDA(dst, b, h) do { _Pragma("unroll") for (int m = 0; m < 4; ++m) _Pragma("unroll") for (int k = 0; k < 2; ++k) dst[m][k] = *(const LAS bf16x8*)(lds + PG8_SA(b, h) + aoff + m * 2048 + k * 1024); } while (0)
; #define PG8_LDB(dst, b, h) do { _Pragma("unroll") for (int n = 0; n < 2; ++n) _Pragma("unroll") for (int k = 0; k < 2; ++k) dst[n][k] = *(const LAS bf16x8*)(lds + PG8_SB(b, h) + boff + n * 2048 + k * 1024); } while (0)
; #define PG8_MMA(ai, bj, At, Bt) do { __builtin_amdgcn_s_setprio(1); _Pragma("unroll") for (int m = 0; m < 4; ++m) _Pragma("unroll") for (int n = 0; n < 2; ++n) _Pragma("unroll") for (int k = 0; k < 2; ++k) \
;         acc[ai][bj][m][n] = __builtin_amdgcn_mfma_f32_16x16x32_bf16(Bt[n][k], At[m][k], acc[ai][bj][m][n], 0, 0, 0); __builtin_amdgcn_s_setprio(0); } while (0)
; #define PG8_WAIT_V(n) asm volatile("s_waitcnt vmcnt(" #n ")" ::: "memory")
; #define PG8_BAR __builtin_amdgcn_s_barrier()
; template <class Epi>
; __device__ __forceinline__ void gemm_phase(LAS unsigned char* lds, const Gemm g, const StaticOrder& S, const Epi& E) {
;     ...
;         const bool has_next = S.next(ui + 1, nxt);
;         const char* nA = has_next ? PG8_UA(nxt) : cA; const char* nB = has_next ? PG8_UB(nxt) : cB;
;         for (int t = 0; t < nt; t += 2) {
;             const bool last = (t == nt - 2);
;             const char* a1 = cA + (size_t)(t + 1) * kstep;
;             const char* a2 = last ? nA : cA + (size_t)(t + 2) * kstep; const char* b2 = last ? nB : cB + (size_t)(t + 2) * kstep;
;             const char* a3 = a2 + kstep; const char* b3 = b2 + kstep;
;             PG8_LDB(B0, 0, 0); PG8_LDB(B1, 0, 1); PG8_SCHED; PG8_LDA(At, 0, 0); PG8_STAGE(PG8_SA(1, 1), a1 + hstepA, voffA);
;             PG8_WAIT_V(8); PG8_WAIT_L(0); PG8_BAR; PG8_MMA(0, 0, At, B0); PG8_MMA(0, 1, At, B1); PG8_BAR; PG8_SCHED;
;             PG8_LDA(At, 0, 1); PG8_STAGE(PG8_SB(0, 0), b2, voffB); PG8_STAGE(PG8_SB(0, 1), b2 + hstepB, voffB); PG8_STAGE(PG8_SA(0, 0), a2, voffA);
;             PG8_WAIT_V(8); PG8_WAIT_L(0); PG8_BAR; PG8_MMA(1, 0, At, B0); PG8_MMA(1, 1, At, B1); PG8_BAR; PG8_SCHED;
.LBB0_2155:
	s_add_u32 s41, s20, s14
	s_addc_u32 s44, s21, 0
	s_add_u32 s15, s41, 0x100
	s_addc_u32 s34, s44, 0
	s_and_b64 s[30:31], s[28:29], exec
	s_cselect_b32 s31, s19, s34
	s_cselect_b32 s30, s3, s15
	s_add_u32 s14, s12, s14
	s_addc_u32 s15, s13, 0
	s_add_u32 s34, s14, 0x100
	s_addc_u32 s35, s15, 0
	s_add_i32 s81, 0, 0x10000
	s_and_b64 s[14:15], s[28:29], exec
	s_cselect_b32 s35, s17, s35
	s_cselect_b32 s34, s40, s34
	s_add_i32 s29, 0, 0x14000
	s_add_u32 s68, s41, 0x10080
	s_addc_u32 s69, s44, 0
	s_add_i32 s80, s81, s63
	s_add_i32 m0, s11, 0xc000
	s_add_i32 s83, s11, 0xe000
	s_add_i32 s77, s80, 0x2000
	v_add_u32_e32 v139, s81, v1
	s_add_u32 s44, s34, 0x10000
	ds_read_b128 v[140:143], v139
	ds_read_b128 v[144:147], v139 offset:1024
	ds_read_b128 v[148:151], v139 offset:2048
	ds_read_b128 v[152:155], v139 offset:3072
	v_add_u32_e32 v139, s29, v1
	s_addc_u32 s45, s35, 0
	s_add_i32 s79, s29, s63
	ds_read_b128 v[156:159], v139
	ds_read_b128 v[160:163], v139 offset:1024
	ds_read_b128 v[164:167], v139 offset:2048
	ds_read_b128 v[168:171], v139 offset:3072
	s_add_i32 s78, s79, 0x2000
	s_add_i32 s76, 0, 0x18000
	s_add_i32 vcc_hi, 0, 0x1c000
	s_add_u32 s14, s30, 0x10000
	s_addc_u32 s15, s31, 0
	s_add_i32 vcc_lo, s76, s63
	s_add_i32 s41, vcc_lo, 0x2000
	s_add_u32 s28, s34, 0x10080
	s_addc_u32 s29, s35, 0
	s_add_i32 s82, vcc_hi, s63
	s_add_i32 s81, s82, 0x2000
	s_nop 0
	ds_read_b128 v[172:175], v138
	ds_read_b128 v[176:179], v138 offset:1024
	ds_read_b128 v[188:191], v138 offset:2048
	ds_read_b128 v[192:195], v138 offset:3072
	ds_read_b128 v[196:199], v138 offset:4096
	ds_read_b128 v[200:203], v138 offset:5120
	ds_read_b128 v[204:207], v138 offset:6144
	ds_read_b128 v[208:211], v138 offset:7168
	global_load_lds_dwordx4 v130, s[68:69]
	s_nop 0
	s_mov_b32 m0, s83
	s_nop 0
	global_load_lds_dwordx4 v134, s[68:69]
	s_waitcnt vmcnt(8)
	s_waitcnt lgkmcnt(0)
	s_barrier
	s_setprio 1
	s_waitcnt lgkmcnt(0)
	v_mfma_f32_16x16x32_bf16 v[126:129], v[140:143], v[172:175], v[126:129]
	v_mfma_f32_16x16x32_bf16 v[122:125], v[148:151], v[172:175], v[122:125]
	v_mfma_f32_16x16x32_bf16 v[118:121], v[140:143], v[188:191], v[118:121]
	v_mfma_f32_16x16x32_bf16 v[114:117], v[148:151], v[188:191], v[114:117]
	v_mfma_f32_16x16x32_bf16 v[102:105], v[140:143], v[196:199], v[102:105]
	v_mfma_f32_16x16x32_bf16 v[98:101], v[148:151], v[196:199], v[98:101]
	v_mfma_f32_16x16x32_bf16 v[86:89], v[140:143], v[204:207], v[86:89]
	v_mfma_f32_16x16x32_bf16 v[82:85], v[148:151], v[204:207], v[82:85]
	v_mfma_f32_16x16x32_bf16 v[126:129], v[144:147], v[176:179], v[126:129]
	v_mfma_f32_16x16x32_bf16 v[122:125], v[152:155], v[176:179], v[122:125]
	v_mfma_f32_16x16x32_bf16 v[118:121], v[144:147], v[192:195], v[118:121]
	v_mfma_f32_16x16x32_bf16 v[114:117], v[152:155], v[192:195], v[114:117]
	v_mfma_f32_16x16x32_bf16 v[102:105], v[144:147], v[200:203], v[102:105]
	v_mfma_f32_16x16x32_bf16 v[98:101], v[152:155], v[200:203], v[98:101]
	v_mfma_f32_16x16x32_bf16 v[86:89], v[144:147], v[208:211], v[86:89]
	v_mfma_f32_16x16x32_bf16 v[82:85], v[152:155], v[208:211], v[82:85]
	s_setprio 0
	s_setprio 1
	v_mfma_f32_16x16x32_bf16 v[110:113], v[156:159], v[172:175], v[110:113]
	v_mfma_f32_16x16x32_bf16 v[106:109], v[164:167], v[172:175], v[106:109]
	v_mfma_f32_16x16x32_bf16 v[94:97], v[156:159], v[188:191], v[94:97]
	v_mfma_f32_16x16x32_bf16 v[90:93], v[164:167], v[188:191], v[90:93]
	v_mfma_f32_16x16x32_bf16 v[78:81], v[156:159], v[196:199], v[78:81]
	v_mfma_f32_16x16x32_bf16 v[74:77], v[164:167], v[196:199], v[74:77]
	v_mfma_f32_16x16x32_bf16 v[70:73], v[156:159], v[204:207], v[70:73]
	v_mfma_f32_16x16x32_bf16 v[66:69], v[164:167], v[204:207], v[66:69]
	v_mfma_f32_16x16x32_bf16 v[110:113], v[160:163], v[176:179], v[110:113]
	v_mfma_f32_16x16x32_bf16 v[106:109], v[168:171], v[176:179], v[106:109]
	v_mfma_f32_16x16x32_bf16 v[94:97], v[160:163], v[192:195], v[94:97]
	v_mfma_f32_16x16x32_bf16 v[90:93], v[168:171], v[192:195], v[90:93]
	v_mfma_f32_16x16x32_bf16 v[78:81], v[160:163], v[200:203], v[78:81]
	v_mfma_f32_16x16x32_bf16 v[74:77], v[168:171], v[200:203], v[74:77]
	v_mfma_f32_16x16x32_bf16 v[70:73], v[160:163], v[208:211], v[70:73]
	v_mfma_f32_16x16x32_bf16 v[66:69], v[168:171], v[208:211], v[66:69]
	s_setprio 0
	s_barrier
	s_mov_b32 m0, s80
	v_lshl_add_u64 v[184:185], s[34:35], 0, v[132:133]
	ds_read_b128 v[172:175], v138 offset:16384
	ds_read_b128 v[176:179], v138 offset:17408
	ds_read_b128 v[188:191], v138 offset:18432
	ds_read_b128 v[192:195], v138 offset:19456
	ds_read_b128 v[196:199], v138 offset:20480
	ds_read_b128 v[200:203], v138 offset:21504
	ds_read_b128 v[204:207], v138 offset:22528
	ds_read_b128 v[208:211], v138 offset:23552
	global_load_lds_dwordx4 v132, s[34:35]
	v_lshl_add_u64 v[212:213], s[34:35], 0, v[136:137]
	s_mov_b32 m0, s77
	s_nop 0
	global_load_lds_dwordx4 v136, s[34:35]
	s_mov_b32 m0, s79
	v_lshl_add_u64 v[216:217], s[30:31], 0, v[134:135]
	global_load_lds_dwordx4 v132, s[44:45]
	s_nop 0
	s_mov_b32 m0, s78
	s_nop 0
	global_load_lds_dwordx4 v136, s[44:45]
	v_lshl_add_u64 v[214:215], s[30:31], 0, v[130:131]
	s_mov_b32 m0, s11
	s_nop 0
	global_load_lds_dwordx4 v130, s[30:31]
	s_mov_b32 m0, s64
	s_nop 0
	global_load_lds_dwordx4 v134, s[30:31]
	s_waitcnt vmcnt(8)
	s_waitcnt lgkmcnt(0)
	s_barrier
; #define PG8_STAGE(bufoff, gbase, voff) do { _Pragma("unroll") for (int _i = 0; _i < 2; ++_i) \
;         __builtin_amdgcn_global_load_lds((const unsigned*)((const char*)(gbase) + (voff)[_i]), (LAS unsigned*)(lds + (bufoff) + ldsw + _i * 8192), 16, 0, 0); } while (0)
; #define PG8_LDA(dst, b, h) do { _Pragma("unroll") for (int m = 0; m < 4; ++m) _Pragma("unroll") for (int k = 0; k < 2; ++k) dst[m][k] = *(const LAS bf16x8*)(lds + PG8_SA(b, h) + aoff + m * 2048 + k * 1024); } while (0)
; #define PG8_LDB(dst, b, h) do { _Pragma("unroll") for (int n = 0; n < 2; ++n) _Pragma("unroll") for (int k = 0; k < 2; ++k) dst[n][k] = *(const LAS bf16x8*)(lds + PG8_SB(b, h) + boff + n * 2048 + k * 1024); } while (0)
; #define PG8_MMA(ai, bj, At, Bt) do { __builtin_amdgcn_s_setprio(1); _Pragma("unroll") for (int m = 0; m < 4; ++m) _Pragma("unroll") for (int n = 0; n < 2; ++n) _Pragma("unroll") for (int k = 0; k < 2; ++k) \
;         acc[ai][bj][m][n] = __builtin_amdgcn_mfma_f32_16x16x32_bf16(Bt[n][k], At[m][k], acc[ai][bj][m][n], 0, 0, 0); __builtin_amdgcn_s_setprio(0); } while (0)
; #define PG8_WAIT_V(n) asm volatile("s_waitcnt vmcnt(" #n ")" ::: "memory")
; #define PG8_WAIT_L(n) asm volatile("s_waitcnt lgkmcnt(" #n ")" ::: "memory")
; #define PG8_BAR __builtin_amdgcn_s_barrier()
; #define PG8_SCHED __builtin_amdgcn_sched_barrier(0)
; template <class Epi>
; __device__ __forceinline__ void gemm_phase(LAS unsigned char* lds, const Gemm g, const StaticOrder& S, const Epi& E) {
;     ...
;             PG8_WAIT_V(8); PG8_WAIT_L(0); PG8_BAR; PG8_MMA(1, 0, At, B0); PG8_MMA(1, 1, At, B1); PG8_BAR; PG8_SCHED;
;             PG8_LDB(B0, 1, 0); PG8_LDB(B1, 1, 1); PG8_SCHED; PG8_LDA(At, 1, 0); PG8_STAGE(PG8_SA(0, 1), a2 + hstepA, voffA);
;             PG8_WAIT_V(8); PG8_WAIT_L(0); PG8_BAR; PG8_MMA(0, 0, At, B0); PG8_MMA(0, 1, At, B1); PG8_BAR; PG8_SCHED;
	s_setprio 1
	s_waitcnt lgkmcnt(0)
	v_mfma_f32_16x16x32_bf16 v[62:65], v[140:143], v[172:175], v[62:65]
	v_mfma_f32_16x16x32_bf16 v[58:61], v[148:151], v[172:175], v[58:61]
	v_mfma_f32_16x16x32_bf16 v[54:57], v[140:143], v[188:191], v[54:57]
	v_mfma_f32_16x16x32_bf16 v[50:53], v[148:151], v[188:191], v[50:53]
	v_mfma_f32_16x16x32_bf16 v[38:41], v[140:143], v[196:199], v[38:41]
	v_mfma_f32_16x16x32_bf16 v[34:37], v[148:151], v[196:199], v[34:37]
	v_mfma_f32_16x16x32_bf16 v[22:25], v[140:143], v[204:207], v[22:25]
	v_mfma_f32_16x16x32_bf16 v[18:21], v[148:151], v[204:207], v[18:21]
	v_mfma_f32_16x16x32_bf16 v[62:65], v[144:147], v[176:179], v[62:65]
	v_mfma_f32_16x16x32_bf16 v[58:61], v[152:155], v[176:179], v[58:61]
	v_mfma_f32_16x16x32_bf16 v[54:57], v[144:147], v[192:195], v[54:57]
	v_mfma_f32_16x16x32_bf16 v[50:53], v[152:155], v[192:195], v[50:53]
	v_mfma_f32_16x16x32_bf16 v[38:41], v[144:147], v[200:203], v[38:41]
	v_mfma_f32_16x16x32_bf16 v[34:37], v[152:155], v[200:203], v[34:37]
	v_mfma_f32_16x16x32_bf16 v[22:25], v[144:147], v[208:211], v[22:25]
	v_mfma_f32_16x16x32_bf16 v[18:21], v[152:155], v[208:211], v[18:21]
	s_setprio 0
	s_setprio 1
	v_mfma_f32_16x16x32_bf16 v[46:49], v[156:159], v[172:175], v[46:49]
	v_mfma_f32_16x16x32_bf16 v[42:45], v[164:167], v[172:175], v[42:45]
	v_mfma_f32_16x16x32_bf16 v[30:33], v[156:159], v[188:191], v[30:33]
	v_mfma_f32_16x16x32_bf16 v[26:29], v[164:167], v[188:191], v[26:29]
	v_mfma_f32_16x16x32_bf16 v[14:17], v[156:159], v[196:199], v[14:17]
	v_mfma_f32_16x16x32_bf16 v[10:13], v[164:167], v[196:199], v[10:13]
	v_mfma_f32_16x16x32_bf16 v[6:9], v[156:159], v[204:207], v[6:9]
	v_mfma_f32_16x16x32_bf16 v[2:5], v[164:167], v[204:207], v[2:5]
	v_mfma_f32_16x16x32_bf16 v[46:49], v[160:163], v[176:179], v[46:49]
	v_mfma_f32_16x16x32_bf16 v[42:45], v[168:171], v[176:179], v[42:45]
	v_mfma_f32_16x16x32_bf16 v[30:33], v[160:163], v[192:195], v[30:33]
	v_mfma_f32_16x16x32_bf16 v[26:29], v[168:171], v[192:195], v[26:29]
	v_mfma_f32_16x16x32_bf16 v[14:17], v[160:163], v[200:203], v[14:17]
	v_mfma_f32_16x16x32_bf16 v[10:13], v[168:171], v[200:203], v[10:13]
	v_mfma_f32_16x16x32_bf16 v[6:9], v[160:163], v[208:211], v[6:9]
	v_mfma_f32_16x16x32_bf16 v[2:5], v[168:171], v[208:211], v[2:5]
	s_setprio 0
	s_barrier
	v_add_u32_e32 v139, s76, v1
	ds_read_b128 v[140:143], v139
	ds_read_b128 v[144:147], v139 offset:1024
	ds_read_b128 v[148:151], v139 offset:2048
	ds_read_b128 v[152:155], v139 offset:3072
	v_add_u32_e32 v139, vcc_hi, v1
	ds_read_b128 v[156:159], v139
	ds_read_b128 v[160:163], v139 offset:1024
	ds_read_b128 v[164:167], v139 offset:2048
	ds_read_b128 v[168:171], v139 offset:3072
	s_mov_b32 m0, s65
	s_nop 0
	ds_read_b128 v[172:175], v138 offset:32768
	ds_read_b128 v[176:179], v138 offset:33792
	ds_read_b128 v[188:191], v138 offset:34816
	ds_read_b128 v[192:195], v138 offset:35840
	ds_read_b128 v[196:199], v138 offset:36864
	ds_read_b128 v[200:203], v138 offset:37888
	ds_read_b128 v[204:207], v138 offset:38912
	ds_read_b128 v[208:211], v138 offset:39936
	global_load_lds_dwordx4 v130, s[14:15]
	s_nop 0
	s_mov_b32 m0, s70
	s_nop 0
	global_load_lds_dwordx4 v134, s[14:15]
	s_waitcnt vmcnt(8)
	s_waitcnt lgkmcnt(0)
	s_barrier
	s_setprio 1
	s_waitcnt lgkmcnt(0)
	v_mfma_f32_16x16x32_bf16 v[126:129], v[140:143], v[172:175], v[126:129]
	v_mfma_f32_16x16x32_bf16 v[122:125], v[148:151], v[172:175], v[122:125]
	v_mfma_f32_16x16x32_bf16 v[118:121], v[140:143], v[188:191], v[118:121]
	v_mfma_f32_16x16x32_bf16 v[114:117], v[148:151], v[188:191], v[114:117]
	v_mfma_f32_16x16x32_bf16 v[102:105], v[140:143], v[196:199], v[102:105]
	v_mfma_f32_16x16x32_bf16 v[98:101], v[148:151], v[196:199], v[98:101]
	v_mfma_f32_16x16x32_bf16 v[86:89], v[140:143], v[204:207], v[86:89]
	v_mfma_f32_16x16x32_bf16 v[82:85], v[148:151], v[204:207], v[82:85]
	v_mfma_f32_16x16x32_bf16 v[126:129], v[144:147], v[176:179], v[126:129]
	v_mfma_f32_16x16x32_bf16 v[122:125], v[152:155], v[176:179], v[122:125]
	v_mfma_f32_16x16x32_bf16 v[118:121], v[144:147], v[192:195], v[118:121]
	v_mfma_f32_16x16x32_bf16 v[114:117], v[152:155], v[192:195], v[114:117]
	v_mfma_f32_16x16x32_bf16 v[102:105], v[144:147], v[200:203], v[102:105]
	v_mfma_f32_16x16x32_bf16 v[98:101], v[152:155], v[200:203], v[98:101]
	v_mfma_f32_16x16x32_bf16 v[86:89], v[144:147], v[208:211], v[86:89]
	v_mfma_f32_16x16x32_bf16 v[82:85], v[152:155], v[208:211], v[82:85]
	s_setprio 0
	s_setprio 1
	v_mfma_f32_16x16x32_bf16 v[110:113], v[156:159], v[172:175], v[110:113]
	v_mfma_f32_16x16x32_bf16 v[106:109], v[164:167], v[172:175], v[106:109]
	v_mfma_f32_16x16x32_bf16 v[94:97], v[156:159], v[188:191], v[94:97]
	v_mfma_f32_16x16x32_bf16 v[90:93], v[164:167], v[188:191], v[90:93]
	v_mfma_f32_16x16x32_bf16 v[78:81], v[156:159], v[196:199], v[78:81]
	v_mfma_f32_16x16x32_bf16 v[74:77], v[164:167], v[196:199], v[74:77]
	v_mfma_f32_16x16x32_bf16 v[70:73], v[156:159], v[204:207], v[70:73]
	v_mfma_f32_16x16x32_bf16 v[66:69], v[164:167], v[204:207], v[66:69]
	v_mfma_f32_16x16x32_bf16 v[110:113], v[160:163], v[176:179], v[110:113]
	v_mfma_f32_16x16x32_bf16 v[106:109], v[168:171], v[176:179], v[106:109]
	v_mfma_f32_16x16x32_bf16 v[94:97], v[160:163], v[192:195], v[94:97]
	v_mfma_f32_16x16x32_bf16 v[90:93], v[168:171], v[192:195], v[90:93]
	v_mfma_f32_16x16x32_bf16 v[78:81], v[160:163], v[200:203], v[78:81]
	v_mfma_f32_16x16x32_bf16 v[74:77], v[168:171], v[200:203], v[74:77]
	v_mfma_f32_16x16x32_bf16 v[70:73], v[160:163], v[208:211], v[70:73]
	v_mfma_f32_16x16x32_bf16 v[66:69], v[168:171], v[208:211], v[66:69]
	s_setprio 0
	s_barrier
; #define PG8_STAGE(bufoff, gbase, voff) do { _Pragma("unroll") for (int _i = 0; _i < 2; ++_i) \
;         __builtin_amdgcn_global_load_lds((const unsigned*)((const char*)(gbase) + (voff)[_i]), (LAS unsigned*)(lds + (bufoff) + ldsw + _i * 8192), 16, 0, 0); } while (0)
; #define PG8_LDA(dst, b, h) do { _Pragma("unroll") for (int m = 0; m < 4; ++m) _Pragma("unroll") for (int k = 0; k < 2; ++k) dst[m][k] = *(const LAS bf16x8*)(lds + PG8_SA(b, h) + aoff + m * 2048 + k * 1024); } while (0)
; #define PG8_MMA(ai, bj, At, Bt) do { __builtin_amdgcn_s_setprio(1); _Pragma("unroll") for (int m = 0; m < 4; ++m) _Pragma("unroll") for (int n = 0; n < 2; ++n) _Pragma("unroll") for (int k = 0; k < 2; ++k) \
;         acc[ai][bj][m][n] = __builtin_amdgcn_mfma_f32_16x16x32_bf16(Bt[n][k], At[m][k], acc[ai][bj][m][n], 0, 0, 0); __builtin_amdgcn_s_setprio(0); } while (0)
; #define PG8_WAIT_V(n) asm volatile("s_waitcnt vmcnt(" #n ")" ::: "memory")
; #define PG8_WAIT_L(n) asm volatile("s_waitcnt lgkmcnt(" #n ")" ::: "memory")
; #define PG8_BAR __builtin_amdgcn_s_barrier()
; #define PG8_SCHED __builtin_amdgcn_sched_barrier(0)
; template <class Epi>
; __device__ __forceinline__ void gemm_phase(LAS unsigned char* lds, const Gemm g, const StaticOrder& S, const Epi& E) {
;     ...
;             PG8_LDA(At, 1, 1); PG8_STAGE(PG8_SB(1, 0), b3, voffB); PG8_STAGE(PG8_SB(1, 1), b3 + hstepB, voffB); PG8_STAGE(PG8_SA(1, 0), a3, voffA);
;             PG8_WAIT_V(8); PG8_WAIT_L(0); PG8_BAR; PG8_MMA(1, 0, At, B0); PG8_MMA(1, 1, At, B1); PG8_BAR; PG8_SCHED;
;         }
;         if (wr == 0) PG8_BAR;
	s_mov_b32 m0, vcc_lo
	v_lshl_add_u64 v[184:185], v[184:185], 0, s[84:85]
	ds_read_b128 v[172:175], v138 offset:49152
	ds_read_b128 v[176:179], v138 offset:50176
	ds_read_b128 v[188:191], v138 offset:51200
	ds_read_b128 v[192:195], v138 offset:52224
	ds_read_b128 v[196:199], v138 offset:53248
	ds_read_b128 v[200:203], v138 offset:54272
	ds_read_b128 v[204:207], v138 offset:55296
	ds_read_b128 v[208:211], v138 offset:56320
	global_load_lds_dwordx4 v[184:185], off
	v_lshl_add_u64 v[184:185], v[212:213], 0, s[84:85]
	s_mov_b32 m0, s41
	s_nop 0
	global_load_lds_dwordx4 v[184:185], off
	s_nop 0
	s_mov_b32 m0, s82
	s_nop 0
	global_load_lds_dwordx4 v132, s[28:29]
	s_nop 0
	s_mov_b32 m0, s81
	s_nop 0
	global_load_lds_dwordx4 v136, s[28:29]
	v_lshl_add_u64 v[184:185], v[214:215], 0, s[84:85]
	s_mov_b32 m0, s86
	s_nop 0
	global_load_lds_dwordx4 v[184:185], off
	v_lshl_add_u64 v[184:185], v[216:217], 0, s[84:85]
	s_mov_b32 m0, s87
	s_nop 0
	global_load_lds_dwordx4 v[184:185], off
	s_waitcnt vmcnt(8)
	s_waitcnt lgkmcnt(0)
	s_barrier
	s_setprio 1
	s_waitcnt lgkmcnt(0)
	v_mfma_f32_16x16x32_bf16 v[62:65], v[140:143], v[172:175], v[62:65]
	v_mfma_f32_16x16x32_bf16 v[58:61], v[148:151], v[172:175], v[58:61]
	v_mfma_f32_16x16x32_bf16 v[54:57], v[140:143], v[188:191], v[54:57]
	v_mfma_f32_16x16x32_bf16 v[50:53], v[148:151], v[188:191], v[50:53]
	v_mfma_f32_16x16x32_bf16 v[38:41], v[140:143], v[196:199], v[38:41]
	v_mfma_f32_16x16x32_bf16 v[34:37], v[148:151], v[196:199], v[34:37]
	v_mfma_f32_16x16x32_bf16 v[22:25], v[140:143], v[204:207], v[22:25]
	v_mfma_f32_16x16x32_bf16 v[18:21], v[148:151], v[204:207], v[18:21]
	v_mfma_f32_16x16x32_bf16 v[62:65], v[144:147], v[176:179], v[62:65]
	v_mfma_f32_16x16x32_bf16 v[58:61], v[152:155], v[176:179], v[58:61]
	v_mfma_f32_16x16x32_bf16 v[54:57], v[144:147], v[192:195], v[54:57]
	v_mfma_f32_16x16x32_bf16 v[50:53], v[152:155], v[192:195], v[50:53]
	v_mfma_f32_16x16x32_bf16 v[38:41], v[144:147], v[200:203], v[38:41]
	v_mfma_f32_16x16x32_bf16 v[34:37], v[152:155], v[200:203], v[34:37]
	v_mfma_f32_16x16x32_bf16 v[22:25], v[144:147], v[208:211], v[22:25]
	v_mfma_f32_16x16x32_bf16 v[18:21], v[152:155], v[208:211], v[18:21]
	s_setprio 0
	s_setprio 1
	v_mfma_f32_16x16x32_bf16 v[46:49], v[156:159], v[172:175], v[46:49]
	v_mfma_f32_16x16x32_bf16 v[42:45], v[164:167], v[172:175], v[42:45]
	v_mfma_f32_16x16x32_bf16 v[30:33], v[156:159], v[188:191], v[30:33]
	v_mfma_f32_16x16x32_bf16 v[26:29], v[164:167], v[188:191], v[26:29]
	v_mfma_f32_16x16x32_bf16 v[14:17], v[156:159], v[196:199], v[14:17]
	v_mfma_f32_16x16x32_bf16 v[10:13], v[164:167], v[196:199], v[10:13]
	v_mfma_f32_16x16x32_bf16 v[6:9], v[156:159], v[204:207], v[6:9]
	v_mfma_f32_16x16x32_bf16 v[2:5], v[164:167], v[204:207], v[2:5]
	v_mfma_f32_16x16x32_bf16 v[46:49], v[160:163], v[176:179], v[46:49]
	v_mfma_f32_16x16x32_bf16 v[42:45], v[168:171], v[176:179], v[42:45]
	v_mfma_f32_16x16x32_bf16 v[30:33], v[160:163], v[192:195], v[30:33]
	v_mfma_f32_16x16x32_bf16 v[26:29], v[168:171], v[192:195], v[26:29]
	v_mfma_f32_16x16x32_bf16 v[14:17], v[160:163], v[200:203], v[14:17]
	v_mfma_f32_16x16x32_bf16 v[10:13], v[168:171], v[200:203], v[10:13]
	v_mfma_f32_16x16x32_bf16 v[6:9], v[160:163], v[208:211], v[6:9]
	v_mfma_f32_16x16x32_bf16 v[2:5], v[168:171], v[208:211], v[2:5]
	s_setprio 0
	s_barrier
	s_movk_i32 s14, 0x100
	s_andn2_b64 vcc, exec, s[26:27]
	s_mov_b64 s[28:29], -1
	s_mov_b64 s[26:27], 0
	s_cbranch_vccz .LBB0_2155
	v_readlane_b32 s28, v255, 28
	s_and_b64 vcc, exec, s[8:9]
	v_readlane_b32 s29, v255, 29
	s_cbranch_vccz .LBB0_2158
	s_barrier

; #define PG8_STAGE(bufoff, gbase, voff) do { _Pragma("unroll") for (int _i = 0; _i < 2; ++_i) \
;         __builtin_amdgcn_global_load_lds((const unsigned*)((const char*)(gbase) + (voff)[_i]), (LAS unsigned*)(lds + (bufoff) + ldsw + _i * 8192), 16, 0, 0); } while (0)
; #define PG8_LDA(dst, b, h) do { _Pragma("unroll") for (int m = 0; m < 4; ++m) _Pragma("unroll") for (int k = 0; k < 2; ++k) dst[m][k] = *(const LAS bf16x8*)(lds + PG8_SA(b, h) + aoff + m * 2048 + k * 1024); } while (0)
; #define PG8_LDB(dst, b, h) do { _Pragma("unroll") for (int n = 0; n < 2; ++n) _Pragma("unroll") for (int k = 0; k < 2; ++k) dst[n][k] = *(const LAS bf16x8*)(lds + PG8_SB(b, h) + boff + n * 2048 + k * 1024); } while (0)
; #define PG8_MMA(ai, bj, At, Bt) do { __builtin_amdgcn_s_setprio(1); _Pragma("unroll") for (int m = 0; m < 4; ++m) _Pragma("unroll") for (int n = 0; n < 2; ++n) _Pragma("unroll") for (int k = 0; k < 2; ++k) \
;         acc[ai][bj][m][n] = __builtin_amdgcn_mfma_f32_16x16x32_bf16(Bt[n][k], At[m][k], acc[ai][bj][m][n], 0, 0, 0); __builtin_amdgcn_s_setprio(0); } while (0)
; #define PG8_WAIT_V(n) asm volatile("s_waitcnt vmcnt(" #n ")" ::: "memory")
; #define PG8_WAIT_L(n) asm volatile("s_waitcnt lgkmcnt(" #n ")" ::: "memory")
; #define PG8_BAR __builtin_amdgcn_s_barrier()
; #define PG8_SCHED __builtin_amdgcn_sched_barrier(0)
; template <class Epi>
; __device__ __forceinline__ void gemm_phase(LAS unsigned char* lds, const Gemm g, const StaticOrder& S, const Epi& E) {
;     ...
;             const bool last = (t == nt - 2);
;             const char* a1 = cA + (size_t)(t + 1) * kstep;
;             const char* a2 = last ? nA : cA + (size_t)(t + 2) * kstep; const char* b2 = last ? nB : cB + (size_t)(t + 2) * kstep;
;             const char* a3 = a2 + kstep; const char* b3 = b2 + kstep;
;             PG8_LDB(B0, 0, 0); PG8_LDB(B1, 0, 1); PG8_SCHED; PG8_LDA(At, 0, 0); PG8_STAGE(PG8_SA(1, 1), a1 + hstepA, voffA);
;             PG8_WAIT_V(8); PG8_WAIT_L(0); PG8_BAR; PG8_MMA(0, 0, At, B0); PG8_MMA(0, 1, At, B1); PG8_BAR; PG8_SCHED;
;             PG8_LDA(At, 0, 1); PG8_STAGE(PG8_SB(0, 0), b2, voffB); PG8_STAGE(PG8_SB(0, 1), b2 + hstepB, voffB); PG8_STAGE(PG8_SA(0, 0), a2, voffA);
;             PG8_WAIT_V(8); PG8_WAIT_L(0); PG8_BAR; PG8_MMA(1, 0, At, B0); PG8_MMA(1, 1, At, B1); PG8_BAR; PG8_SCHED;
.LBB0_2233:
	s_add_u32 s14, s24, 0xffe00080
	s_addc_u32 s15, s25, -1
	s_add_i32 s52, 0, 0x10000
	s_cmpk_eq_i32 s41, 0x7c
	s_cselect_b32 s27, s1, s15
	s_cselect_b32 s26, s3, s14
	s_cselect_b32 s15, s9, s40
	s_cselect_b32 s14, s17, s19
	s_add_i32 s62, 0, 0x14000
	v_add_u32_e32 v142, s52, v1
	v_add_u32_e32 v167, s62, v1
	ds_read_b128 v[130:133], v142
	ds_read_b128 v[134:137], v142 offset:1024
	ds_read_b128 v[138:141], v142 offset:2048
	ds_read_b128 v[142:145], v142 offset:3072
	ds_read_b128 v[146:149], v167
	ds_read_b128 v[162:165], v167 offset:1024
	ds_read_b128 v[168:171], v167 offset:2048
	ds_read_b128 v[172:175], v167 offset:3072
	s_nop 0
	s_add_i32 m0, s31, 0xc000
	ds_read_b128 v[176:179], v166
	ds_read_b128 v[188:191], v166 offset:1024
	ds_read_b128 v[192:195], v166 offset:2048
	ds_read_b128 v[196:199], v166 offset:3072
	ds_read_b128 v[200:203], v166 offset:4096
	ds_read_b128 v[204:207], v166 offset:5120
	ds_read_b128 v[208:211], v166 offset:6144
	ds_read_b128 v[212:215], v166 offset:7168
	global_load_lds_dwordx4 v158, s[24:25]
	s_nop 0
	s_add_i32 m0, s31, 0xe000
	s_nop 0
	global_load_lds_dwordx4 v160, s[24:25]
	s_waitcnt vmcnt(8)
	s_waitcnt lgkmcnt(0)
	s_barrier
	s_setprio 1
	s_waitcnt lgkmcnt(0)
	v_mfma_f32_16x16x32_bf16 v[126:129], v[130:133], v[176:179], v[126:129]
	v_mfma_f32_16x16x32_bf16 v[122:125], v[138:141], v[176:179], v[122:125]
	v_mfma_f32_16x16x32_bf16 v[118:121], v[130:133], v[192:195], v[118:121]
	v_mfma_f32_16x16x32_bf16 v[114:117], v[138:141], v[192:195], v[114:117]
	v_mfma_f32_16x16x32_bf16 v[94:97], v[130:133], v[200:203], v[94:97]
	v_mfma_f32_16x16x32_bf16 v[90:93], v[138:141], v[200:203], v[90:93]
	v_mfma_f32_16x16x32_bf16 v[82:85], v[130:133], v[208:211], v[82:85]
	v_mfma_f32_16x16x32_bf16 v[74:77], v[138:141], v[208:211], v[74:77]
	v_mfma_f32_16x16x32_bf16 v[126:129], v[134:137], v[188:191], v[126:129]
	v_mfma_f32_16x16x32_bf16 v[122:125], v[142:145], v[188:191], v[122:125]
	v_mfma_f32_16x16x32_bf16 v[118:121], v[134:137], v[196:199], v[118:121]
	v_mfma_f32_16x16x32_bf16 v[114:117], v[142:145], v[196:199], v[114:117]
	v_mfma_f32_16x16x32_bf16 v[94:97], v[134:137], v[204:207], v[94:97]
	v_mfma_f32_16x16x32_bf16 v[90:93], v[142:145], v[204:207], v[90:93]
	v_mfma_f32_16x16x32_bf16 v[82:85], v[134:137], v[212:215], v[82:85]
	v_mfma_f32_16x16x32_bf16 v[74:77], v[142:145], v[212:215], v[74:77]
	s_setprio 0
	s_setprio 1
	v_mfma_f32_16x16x32_bf16 v[110:113], v[146:149], v[176:179], v[110:113]
	v_mfma_f32_16x16x32_bf16 v[106:109], v[168:171], v[176:179], v[106:109]
	v_mfma_f32_16x16x32_bf16 v[102:105], v[146:149], v[192:195], v[102:105]
	v_mfma_f32_16x16x32_bf16 v[98:101], v[168:171], v[192:195], v[98:101]
	v_mfma_f32_16x16x32_bf16 v[86:89], v[146:149], v[200:203], v[86:89]
	v_mfma_f32_16x16x32_bf16 v[78:81], v[168:171], v[200:203], v[78:81]
	v_mfma_f32_16x16x32_bf16 v[70:73], v[146:149], v[208:211], v[70:73]
	v_mfma_f32_16x16x32_bf16 v[66:69], v[168:171], v[208:211], v[66:69]
	v_mfma_f32_16x16x32_bf16 v[110:113], v[162:165], v[188:191], v[110:113]
	v_mfma_f32_16x16x32_bf16 v[106:109], v[172:175], v[188:191], v[106:109]
	v_mfma_f32_16x16x32_bf16 v[102:105], v[162:165], v[196:199], v[102:105]
	v_mfma_f32_16x16x32_bf16 v[98:101], v[172:175], v[196:199], v[98:101]
	v_mfma_f32_16x16x32_bf16 v[86:89], v[162:165], v[204:207], v[86:89]
	v_mfma_f32_16x16x32_bf16 v[78:81], v[172:175], v[204:207], v[78:81]
	v_mfma_f32_16x16x32_bf16 v[70:73], v[162:165], v[212:215], v[70:73]
	v_mfma_f32_16x16x32_bf16 v[66:69], v[172:175], v[212:215], v[66:69]
	s_setprio 0
	s_barrier
	s_add_i32 s52, s52, s30
	v_lshl_add_u64 v[184:185], s[14:15], 0, v[152:153]
	s_mov_b32 m0, s52
	ds_read_b128 v[176:179], v166 offset:16384
	ds_read_b128 v[188:191], v166 offset:17408
	ds_read_b128 v[192:195], v166 offset:18432
	ds_read_b128 v[196:199], v166 offset:19456
	ds_read_b128 v[200:203], v166 offset:20480
	ds_read_b128 v[204:207], v166 offset:21504
	ds_read_b128 v[208:211], v166 offset:22528
	ds_read_b128 v[212:215], v166 offset:23552
	global_load_lds_dwordx4 v152, s[14:15]
	s_add_i32 m0, s52, 0x2000
	s_add_u32 s52, s14, 0x200000
	v_lshl_add_u64 v[216:217], s[14:15], 0, v[156:157]
	s_addc_u32 s53, s15, 0
	s_add_i32 s62, s62, s30
	global_load_lds_dwordx4 v156, s[14:15]
	s_nop 0
	s_mov_b32 m0, s62
	v_lshl_add_u64 v[220:221], s[26:27], 0, v[154:155]
	global_load_lds_dwordx4 v152, s[52:53]
	s_nop 0
	s_add_i32 m0, s62, 0x2000
	s_nop 0
	global_load_lds_dwordx4 v156, s[52:53]
	v_lshl_add_u64 v[218:219], s[26:27], 0, v[150:151]
	s_mov_b32 m0, s31
	s_nop 0
	global_load_lds_dwordx4 v150, s[26:27]
	s_mov_b32 m0, s34
	s_nop 0
	global_load_lds_dwordx4 v154, s[26:27]
	s_waitcnt vmcnt(8)
	s_waitcnt lgkmcnt(0)
	s_barrier
; #define PG8_STAGE(bufoff, gbase, voff) do { _Pragma("unroll") for (int _i = 0; _i < 2; ++_i) \
;         __builtin_amdgcn_global_load_lds((const unsigned*)((const char*)(gbase) + (voff)[_i]), (LAS unsigned*)(lds + (bufoff) + ldsw + _i * 8192), 16, 0, 0); } while (0)
; #define PG8_LDA(dst, b, h) do { _Pragma("unroll") for (int m = 0; m < 4; ++m) _Pragma("unroll") for (int k = 0; k < 2; ++k) dst[m][k] = *(const LAS bf16x8*)(lds + PG8_SA(b, h) + aoff + m * 2048 + k * 1024); } while (0)
; #define PG8_LDB(dst, b, h) do { _Pragma("unroll") for (int n = 0; n < 2; ++n) _Pragma("unroll") for (int k = 0; k < 2; ++k) dst[n][k] = *(const LAS bf16x8*)(lds + PG8_SB(b, h) + boff + n * 2048 + k * 1024); } while (0)
; #define PG8_MMA(ai, bj, At, Bt) do { __builtin_amdgcn_s_setprio(1); _Pragma("unroll") for (int m = 0; m < 4; ++m) _Pragma("unroll") for (int n = 0; n < 2; ++n) _Pragma("unroll") for (int k = 0; k < 2; ++k) \
;         acc[ai][bj][m][n] = __builtin_amdgcn_mfma_f32_16x16x32_bf16(Bt[n][k], At[m][k], acc[ai][bj][m][n], 0, 0, 0); __builtin_amdgcn_s_setprio(0); } while (0)
; #define PG8_WAIT_V(n) asm volatile("s_waitcnt vmcnt(" #n ")" ::: "memory")
; #define PG8_WAIT_L(n) asm volatile("s_waitcnt lgkmcnt(" #n ")" ::: "memory")
; #define PG8_BAR __builtin_amdgcn_s_barrier()
; #define PG8_SCHED __builtin_amdgcn_sched_barrier(0)
; template <class Epi>
; __device__ __forceinline__ void gemm_phase(LAS unsigned char* lds, const Gemm g, const StaticOrder& S, const Epi& E) {
;     ...
;             PG8_WAIT_V(8); PG8_WAIT_L(0); PG8_BAR; PG8_MMA(1, 0, At, B0); PG8_MMA(1, 1, At, B1); PG8_BAR; PG8_SCHED;
;             PG8_LDB(B0, 1, 0); PG8_LDB(B1, 1, 1); PG8_SCHED; PG8_LDA(At, 1, 0); PG8_STAGE(PG8_SA(0, 1), a2 + hstepA, voffA);
;             PG8_WAIT_V(8); PG8_WAIT_L(0); PG8_BAR; PG8_MMA(0, 0, At, B0); PG8_MMA(0, 1, At, B1); PG8_BAR; PG8_SCHED;
	s_setprio 1
	s_waitcnt lgkmcnt(0)
	v_mfma_f32_16x16x32_bf16 v[62:65], v[130:133], v[176:179], v[62:65]
	v_mfma_f32_16x16x32_bf16 v[58:61], v[138:141], v[176:179], v[58:61]
	v_mfma_f32_16x16x32_bf16 v[50:53], v[130:133], v[192:195], v[50:53]
	v_mfma_f32_16x16x32_bf16 v[42:45], v[138:141], v[192:195], v[42:45]
	v_mfma_f32_16x16x32_bf16 v[30:33], v[130:133], v[200:203], v[30:33]
	v_mfma_f32_16x16x32_bf16 v[26:29], v[138:141], v[200:203], v[26:29]
	v_mfma_f32_16x16x32_bf16 v[18:21], v[130:133], v[208:211], v[18:21]
	v_mfma_f32_16x16x32_bf16 v[10:13], v[138:141], v[208:211], v[10:13]
	v_mfma_f32_16x16x32_bf16 v[62:65], v[134:137], v[188:191], v[62:65]
	v_mfma_f32_16x16x32_bf16 v[58:61], v[142:145], v[188:191], v[58:61]
	v_mfma_f32_16x16x32_bf16 v[50:53], v[134:137], v[196:199], v[50:53]
	v_mfma_f32_16x16x32_bf16 v[42:45], v[142:145], v[196:199], v[42:45]
	v_mfma_f32_16x16x32_bf16 v[30:33], v[134:137], v[204:207], v[30:33]
	v_mfma_f32_16x16x32_bf16 v[26:29], v[142:145], v[204:207], v[26:29]
	v_mfma_f32_16x16x32_bf16 v[18:21], v[134:137], v[212:215], v[18:21]
	v_mfma_f32_16x16x32_bf16 v[10:13], v[142:145], v[212:215], v[10:13]
	s_setprio 0
	s_setprio 1
	v_mfma_f32_16x16x32_bf16 v[54:57], v[146:149], v[176:179], v[54:57]
	v_mfma_f32_16x16x32_bf16 v[46:49], v[168:171], v[176:179], v[46:49]
	v_mfma_f32_16x16x32_bf16 v[38:41], v[146:149], v[192:195], v[38:41]
	v_mfma_f32_16x16x32_bf16 v[34:37], v[168:171], v[192:195], v[34:37]
	v_mfma_f32_16x16x32_bf16 v[22:25], v[146:149], v[200:203], v[22:25]
	v_mfma_f32_16x16x32_bf16 v[14:17], v[168:171], v[200:203], v[14:17]
	v_mfma_f32_16x16x32_bf16 v[6:9], v[146:149], v[208:211], v[6:9]
	v_mfma_f32_16x16x32_bf16 v[2:5], v[168:171], v[208:211], v[2:5]
	v_mfma_f32_16x16x32_bf16 v[54:57], v[162:165], v[188:191], v[54:57]
	v_mfma_f32_16x16x32_bf16 v[46:49], v[172:175], v[188:191], v[46:49]
	v_mfma_f32_16x16x32_bf16 v[38:41], v[162:165], v[196:199], v[38:41]
	v_mfma_f32_16x16x32_bf16 v[34:37], v[172:175], v[196:199], v[34:37]
	v_mfma_f32_16x16x32_bf16 v[22:25], v[162:165], v[204:207], v[22:25]
	v_mfma_f32_16x16x32_bf16 v[14:17], v[172:175], v[204:207], v[14:17]
	v_mfma_f32_16x16x32_bf16 v[6:9], v[162:165], v[212:215], v[6:9]
	v_mfma_f32_16x16x32_bf16 v[2:5], v[172:175], v[212:215], v[2:5]
	s_setprio 0
	s_barrier
	s_add_i32 s52, 0, 0x18000
	s_add_i32 s53, 0, 0x1c000
	v_add_u32_e32 v142, s52, v1
	v_add_u32_e32 v167, s53, v1
	ds_read_b128 v[130:133], v142
	ds_read_b128 v[134:137], v142 offset:1024
	ds_read_b128 v[138:141], v142 offset:2048
	ds_read_b128 v[142:145], v142 offset:3072
	ds_read_b128 v[146:149], v167
	ds_read_b128 v[162:165], v167 offset:1024
	ds_read_b128 v[168:171], v167 offset:2048
	ds_read_b128 v[172:175], v167 offset:3072
	s_add_u32 s26, s26, 0x200000
	s_addc_u32 s27, s27, 0
	s_mov_b32 m0, s35
	s_nop 0
	ds_read_b128 v[176:179], v166 offset:32768
	ds_read_b128 v[188:191], v166 offset:33792
	ds_read_b128 v[192:195], v166 offset:34816
	ds_read_b128 v[196:199], v166 offset:35840
	ds_read_b128 v[200:203], v166 offset:36864
	ds_read_b128 v[204:207], v166 offset:37888
	ds_read_b128 v[208:211], v166 offset:38912
	ds_read_b128 v[212:215], v166 offset:39936
	global_load_lds_dwordx4 v150, s[26:27]
	s_nop 0
	s_mov_b32 m0, s42
	s_nop 0
	global_load_lds_dwordx4 v154, s[26:27]
	s_waitcnt vmcnt(8)
	s_waitcnt lgkmcnt(0)
	s_barrier
	s_setprio 1
	s_waitcnt lgkmcnt(0)
	v_mfma_f32_16x16x32_bf16 v[126:129], v[130:133], v[176:179], v[126:129]
	v_mfma_f32_16x16x32_bf16 v[122:125], v[138:141], v[176:179], v[122:125]
	v_mfma_f32_16x16x32_bf16 v[118:121], v[130:133], v[192:195], v[118:121]
	v_mfma_f32_16x16x32_bf16 v[114:117], v[138:141], v[192:195], v[114:117]
	v_mfma_f32_16x16x32_bf16 v[94:97], v[130:133], v[200:203], v[94:97]
	v_mfma_f32_16x16x32_bf16 v[90:93], v[138:141], v[200:203], v[90:93]
	v_mfma_f32_16x16x32_bf16 v[82:85], v[130:133], v[208:211], v[82:85]
	v_mfma_f32_16x16x32_bf16 v[74:77], v[138:141], v[208:211], v[74:77]
	v_mfma_f32_16x16x32_bf16 v[126:129], v[134:137], v[188:191], v[126:129]
	v_mfma_f32_16x16x32_bf16 v[122:125], v[142:145], v[188:191], v[122:125]
	v_mfma_f32_16x16x32_bf16 v[118:121], v[134:137], v[196:199], v[118:121]
	v_mfma_f32_16x16x32_bf16 v[114:117], v[142:145], v[196:199], v[114:117]
	v_mfma_f32_16x16x32_bf16 v[94:97], v[134:137], v[204:207], v[94:97]
	v_mfma_f32_16x16x32_bf16 v[90:93], v[142:145], v[204:207], v[90:93]
	v_mfma_f32_16x16x32_bf16 v[82:85], v[134:137], v[212:215], v[82:85]
	v_mfma_f32_16x16x32_bf16 v[74:77], v[142:145], v[212:215], v[74:77]
	s_setprio 0
	s_setprio 1
	v_mfma_f32_16x16x32_bf16 v[110:113], v[146:149], v[176:179], v[110:113]
	v_mfma_f32_16x16x32_bf16 v[106:109], v[168:171], v[176:179], v[106:109]
	v_mfma_f32_16x16x32_bf16 v[102:105], v[146:149], v[192:195], v[102:105]
	v_mfma_f32_16x16x32_bf16 v[98:101], v[168:171], v[192:195], v[98:101]
	v_mfma_f32_16x16x32_bf16 v[86:89], v[146:149], v[200:203], v[86:89]
	v_mfma_f32_16x16x32_bf16 v[78:81], v[168:171], v[200:203], v[78:81]
	v_mfma_f32_16x16x32_bf16 v[70:73], v[146:149], v[208:211], v[70:73]
	v_mfma_f32_16x16x32_bf16 v[66:69], v[168:171], v[208:211], v[66:69]
	v_mfma_f32_16x16x32_bf16 v[110:113], v[162:165], v[188:191], v[110:113]
	v_mfma_f32_16x16x32_bf16 v[106:109], v[172:175], v[188:191], v[106:109]
	v_mfma_f32_16x16x32_bf16 v[102:105], v[162:165], v[196:199], v[102:105]
	v_mfma_f32_16x16x32_bf16 v[98:101], v[172:175], v[196:199], v[98:101]
	v_mfma_f32_16x16x32_bf16 v[86:89], v[162:165], v[204:207], v[86:89]
	v_mfma_f32_16x16x32_bf16 v[78:81], v[172:175], v[204:207], v[78:81]
	v_mfma_f32_16x16x32_bf16 v[70:73], v[162:165], v[212:215], v[70:73]
	v_mfma_f32_16x16x32_bf16 v[66:69], v[172:175], v[212:215], v[66:69]
	s_setprio 0
	s_barrier
; #define PG8_STAGE(bufoff, gbase, voff) do { _Pragma("unroll") for (int _i = 0; _i < 2; ++_i) \
;         __builtin_amdgcn_global_load_lds((const unsigned*)((const char*)(gbase) + (voff)[_i]), (LAS unsigned*)(lds + (bufoff) + ldsw + _i * 8192), 16, 0, 0); } while (0)
; #define PG8_LDA(dst, b, h) do { _Pragma("unroll") for (int m = 0; m < 4; ++m) _Pragma("unroll") for (int k = 0; k < 2; ++k) dst[m][k] = *(const LAS bf16x8*)(lds + PG8_SA(b, h) + aoff + m * 2048 + k * 1024); } while (0)
; #define PG8_MMA(ai, bj, At, Bt) do { __builtin_amdgcn_s_setprio(1); _Pragma("unroll") for (int m = 0; m < 4; ++m) _Pragma("unroll") for (int n = 0; n < 2; ++n) _Pragma("unroll") for (int k = 0; k < 2; ++k) \
;         acc[ai][bj][m][n] = __builtin_amdgcn_mfma_f32_16x16x32_bf16(Bt[n][k], At[m][k], acc[ai][bj][m][n], 0, 0, 0); __builtin_amdgcn_s_setprio(0); } while (0)
; #define PG8_WAIT_V(n) asm volatile("s_waitcnt vmcnt(" #n ")" ::: "memory")
; #define PG8_WAIT_L(n) asm volatile("s_waitcnt lgkmcnt(" #n ")" ::: "memory")
; #define PG8_BAR __builtin_amdgcn_s_barrier()
; #define PG8_SCHED __builtin_amdgcn_sched_barrier(0)
; template <class Epi>
; __device__ __forceinline__ void gemm_phase(LAS unsigned char* lds, const Gemm g, const StaticOrder& S, const Epi& E) {
;     ...
;             PG8_LDA(At, 1, 1); PG8_STAGE(PG8_SB(1, 0), b3, voffB); PG8_STAGE(PG8_SB(1, 1), b3 + hstepB, voffB); PG8_STAGE(PG8_SA(1, 0), a3, voffA);
;             PG8_WAIT_V(8); PG8_WAIT_L(0); PG8_BAR; PG8_MMA(1, 0, At, B0); PG8_MMA(1, 1, At, B1); PG8_BAR; PG8_SCHED;
;         }
;         if (wr == 0) PG8_BAR;
	s_add_i32 s26, s52, s30
	v_lshl_add_u64 v[184:185], v[184:185], 0, s[84:85]
	s_mov_b32 m0, s26
	ds_read_b128 v[176:179], v166 offset:49152
	ds_read_b128 v[188:191], v166 offset:50176
	ds_read_b128 v[192:195], v166 offset:51200
	ds_read_b128 v[196:199], v166 offset:52224
	ds_read_b128 v[200:203], v166 offset:53248
	ds_read_b128 v[204:207], v166 offset:54272
	ds_read_b128 v[208:211], v166 offset:55296
	ds_read_b128 v[212:215], v166 offset:56320
	global_load_lds_dwordx4 v[184:185], off
	s_add_i32 m0, s26, 0x2000
	s_add_u32 s14, s14, 0x200080
	v_lshl_add_u64 v[184:185], v[216:217], 0, s[84:85]
	s_addc_u32 s15, s15, 0
	s_add_i32 s26, s53, s30
	global_load_lds_dwordx4 v[184:185], off
	s_nop 0
	s_mov_b32 m0, s26
	s_nop 0
	global_load_lds_dwordx4 v152, s[14:15]
	s_nop 0
	s_add_i32 m0, s26, 0x2000
	s_nop 0
	global_load_lds_dwordx4 v156, s[14:15]
	v_lshl_add_u64 v[184:185], v[218:219], 0, s[84:85]
	s_mov_b32 m0, s68
	s_nop 0
	global_load_lds_dwordx4 v[184:185], off
	v_lshl_add_u64 v[184:185], v[220:221], 0, s[84:85]
	s_mov_b32 m0, s69
	s_nop 0
	global_load_lds_dwordx4 v[184:185], off
	s_waitcnt vmcnt(8)
	s_waitcnt lgkmcnt(0)
	s_barrier
	s_setprio 1
	s_waitcnt lgkmcnt(0)
	v_mfma_f32_16x16x32_bf16 v[62:65], v[130:133], v[176:179], v[62:65]
	v_mfma_f32_16x16x32_bf16 v[58:61], v[138:141], v[176:179], v[58:61]
	v_mfma_f32_16x16x32_bf16 v[50:53], v[130:133], v[192:195], v[50:53]
	v_mfma_f32_16x16x32_bf16 v[42:45], v[138:141], v[192:195], v[42:45]
	v_mfma_f32_16x16x32_bf16 v[30:33], v[130:133], v[200:203], v[30:33]
	v_mfma_f32_16x16x32_bf16 v[26:29], v[138:141], v[200:203], v[26:29]
	v_mfma_f32_16x16x32_bf16 v[18:21], v[130:133], v[208:211], v[18:21]
	v_mfma_f32_16x16x32_bf16 v[10:13], v[138:141], v[208:211], v[10:13]
	v_mfma_f32_16x16x32_bf16 v[62:65], v[134:137], v[188:191], v[62:65]
	v_mfma_f32_16x16x32_bf16 v[58:61], v[142:145], v[188:191], v[58:61]
	v_mfma_f32_16x16x32_bf16 v[50:53], v[134:137], v[196:199], v[50:53]
	v_mfma_f32_16x16x32_bf16 v[42:45], v[142:145], v[196:199], v[42:45]
	v_mfma_f32_16x16x32_bf16 v[30:33], v[134:137], v[204:207], v[30:33]
	v_mfma_f32_16x16x32_bf16 v[26:29], v[142:145], v[204:207], v[26:29]
	v_mfma_f32_16x16x32_bf16 v[18:21], v[134:137], v[212:215], v[18:21]
	v_mfma_f32_16x16x32_bf16 v[10:13], v[142:145], v[212:215], v[10:13]
	s_setprio 0
	s_setprio 1
	v_mfma_f32_16x16x32_bf16 v[54:57], v[146:149], v[176:179], v[54:57]
	v_mfma_f32_16x16x32_bf16 v[46:49], v[168:171], v[176:179], v[46:49]
	v_mfma_f32_16x16x32_bf16 v[38:41], v[146:149], v[192:195], v[38:41]
	v_mfma_f32_16x16x32_bf16 v[34:37], v[168:171], v[192:195], v[34:37]
	v_mfma_f32_16x16x32_bf16 v[22:25], v[146:149], v[200:203], v[22:25]
	v_mfma_f32_16x16x32_bf16 v[14:17], v[168:171], v[200:203], v[14:17]
	v_mfma_f32_16x16x32_bf16 v[6:9], v[146:149], v[208:211], v[6:9]
	v_mfma_f32_16x16x32_bf16 v[2:5], v[168:171], v[208:211], v[2:5]
	v_mfma_f32_16x16x32_bf16 v[54:57], v[162:165], v[188:191], v[54:57]
	v_mfma_f32_16x16x32_bf16 v[46:49], v[172:175], v[188:191], v[46:49]
	v_mfma_f32_16x16x32_bf16 v[38:41], v[162:165], v[196:199], v[38:41]
	v_mfma_f32_16x16x32_bf16 v[34:37], v[172:175], v[196:199], v[34:37]
	v_mfma_f32_16x16x32_bf16 v[22:25], v[162:165], v[204:207], v[22:25]
	v_mfma_f32_16x16x32_bf16 v[14:17], v[172:175], v[204:207], v[14:17]
	v_mfma_f32_16x16x32_bf16 v[6:9], v[162:165], v[212:215], v[6:9]
	v_mfma_f32_16x16x32_bf16 v[2:5], v[172:175], v[212:215], v[2:5]
	s_setprio 0
	s_barrier
	s_add_i32 s41, s41, 2
	s_add_u32 s24, s24, 0x100
	s_addc_u32 s25, s25, 0
	s_add_u32 s19, s19, 0x100
	s_addc_u32 s40, s40, 0
	s_cmpk_gt_u32 s41, 0x7d
	s_cbranch_scc0 .LBB0_2233
	s_and_b64 vcc, exec, s[12:13]
	s_cbranch_vccz .LBB0_2236
	s_barrier

; #define PG8_STAGE(bufoff, gbase, voff) do { _Pragma("unroll") for (int _i = 0; _i < 2; ++_i) \
;         __builtin_amdgcn_global_load_lds((const unsigned*)((const char*)(gbase) + (voff)[_i]), (LAS unsigned*)(lds + (bufoff) + ldsw + _i * 8192), 16, 0, 0); } while (0)
; #define PG8_LDA(dst, b, h) do { _Pragma("unroll") for (int m = 0; m < 4; ++m) _Pragma("unroll") for (int k = 0; k < 2; ++k) dst[m][k] = *(const LAS bf16x8*)(lds + PG8_SA(b, h) + aoff + m * 2048 + k * 1024); } while (0)
; #define PG8_LDB(dst, b, h) do { _Pragma("unroll") for (int n = 0; n < 2; ++n) _Pragma("unroll") for (int k = 0; k < 2; ++k) dst[n][k] = *(const LAS bf16x8*)(lds + PG8_SB(b, h) + boff + n * 2048 + k * 1024); } while (0)
; #define PG8_MMA(ai, bj, At, Bt) do { __builtin_amdgcn_s_setprio(1); _Pragma("unroll") for (int m = 0; m < 4; ++m) _Pragma("unroll") for (int n = 0; n < 2; ++n) _Pragma("unroll") for (int k = 0; k < 2; ++k) \
;         acc[ai][bj][m][n] = __builtin_amdgcn_mfma_f32_16x16x32_bf16(Bt[n][k], At[m][k], acc[ai][bj][m][n], 0, 0, 0); __builtin_amdgcn_s_setprio(0); } while (0)
; #define PG8_WAIT_V(n) asm volatile("s_waitcnt vmcnt(" #n ")" ::: "memory")
; #define PG8_WAIT_L(n) asm volatile("s_waitcnt lgkmcnt(" #n ")" ::: "memory")
; #define PG8_BAR __builtin_amdgcn_s_barrier()
; #define PG8_SCHED __builtin_amdgcn_sched_barrier(0)
; template <class Epi>
; __device__ __forceinline__ void gemm_phase(LAS unsigned char* lds, const Gemm g, const StaticOrder& S, const Epi& E) {
;     ...
;             const bool last = (t == nt - 2);
;             const char* a1 = cA + (size_t)(t + 1) * kstep;
;             const char* a2 = last ? nA : cA + (size_t)(t + 2) * kstep; const char* b2 = last ? nB : cB + (size_t)(t + 2) * kstep;
;             const char* a3 = a2 + kstep; const char* b3 = b2 + kstep;
;             PG8_LDB(B0, 0, 0); PG8_LDB(B1, 0, 1); PG8_SCHED; PG8_LDA(At, 0, 0); PG8_STAGE(PG8_SA(1, 1), a1 + hstepA, voffA);
;             PG8_WAIT_V(8); PG8_WAIT_L(0); PG8_BAR; PG8_MMA(0, 0, At, B0); PG8_MMA(0, 1, At, B1); PG8_BAR; PG8_SCHED;
;             PG8_LDA(At, 0, 1); PG8_STAGE(PG8_SB(0, 0), b2, voffB); PG8_STAGE(PG8_SB(0, 1), b2 + hstepB, voffB); PG8_STAGE(PG8_SA(0, 0), a2, voffA);
;             PG8_WAIT_V(8); PG8_WAIT_L(0); PG8_BAR; PG8_MMA(1, 0, At, B0); PG8_MMA(1, 1, At, B1); PG8_BAR; PG8_SCHED;
.LBB0_2332:
	s_add_u32 s14, s24, 0xfff80080
	s_addc_u32 s15, s25, -1
	s_add_i32 s41, 0, 0x10000
	s_cmp_eq_u32 s40, 28
	s_cselect_b32 s27, s1, s15
	s_cselect_b32 s26, s3, s14
	s_cselect_b32 s15, s9, s33
	s_cselect_b32 s14, s17, s19
	s_add_i32 s62, 0, 0x14000
	v_add_u32_e32 v142, s41, v1
	v_add_u32_e32 v170, s62, v1
	ds_read_b128 v[130:133], v142
	ds_read_b128 v[134:137], v142 offset:1024
	ds_read_b128 v[138:141], v142 offset:2048
	ds_read_b128 v[142:145], v142 offset:3072
	ds_read_b128 v[146:149], v170
	ds_read_b128 v[150:153], v170 offset:1024
	ds_read_b128 v[166:169], v170 offset:2048
	ds_read_b128 v[170:173], v170 offset:3072
	s_nop 0
	s_add_i32 m0, s35, 0xc000
	ds_read_b128 v[174:177], v181
	ds_read_b128 v[188:191], v181 offset:1024
	ds_read_b128 v[192:195], v181 offset:2048
	ds_read_b128 v[196:199], v181 offset:3072
	ds_read_b128 v[200:203], v181 offset:4096
	ds_read_b128 v[204:207], v181 offset:5120
	ds_read_b128 v[208:211], v181 offset:6144
	ds_read_b128 v[212:215], v181 offset:7168
	global_load_lds_dwordx4 v162, s[24:25]
	s_nop 0
	s_add_i32 m0, s35, 0xe000
	s_nop 0
	global_load_lds_dwordx4 v164, s[24:25]
	s_waitcnt vmcnt(8)
	s_waitcnt lgkmcnt(0)
	s_barrier
	s_setprio 1
	s_waitcnt lgkmcnt(0)
	v_mfma_f32_16x16x32_bf16 v[126:129], v[130:133], v[174:177], v[126:129]
	v_mfma_f32_16x16x32_bf16 v[122:125], v[138:141], v[174:177], v[122:125]
	v_mfma_f32_16x16x32_bf16 v[118:121], v[130:133], v[192:195], v[118:121]
	v_mfma_f32_16x16x32_bf16 v[114:117], v[138:141], v[192:195], v[114:117]
	v_mfma_f32_16x16x32_bf16 v[102:105], v[130:133], v[200:203], v[102:105]
	v_mfma_f32_16x16x32_bf16 v[98:101], v[138:141], v[200:203], v[98:101]
	v_mfma_f32_16x16x32_bf16 v[86:89], v[130:133], v[208:211], v[86:89]
	v_mfma_f32_16x16x32_bf16 v[82:85], v[138:141], v[208:211], v[82:85]
	v_mfma_f32_16x16x32_bf16 v[126:129], v[134:137], v[188:191], v[126:129]
	v_mfma_f32_16x16x32_bf16 v[122:125], v[142:145], v[188:191], v[122:125]
	v_mfma_f32_16x16x32_bf16 v[118:121], v[134:137], v[196:199], v[118:121]
	v_mfma_f32_16x16x32_bf16 v[114:117], v[142:145], v[196:199], v[114:117]
	v_mfma_f32_16x16x32_bf16 v[102:105], v[134:137], v[204:207], v[102:105]
	v_mfma_f32_16x16x32_bf16 v[98:101], v[142:145], v[204:207], v[98:101]
	v_mfma_f32_16x16x32_bf16 v[86:89], v[134:137], v[212:215], v[86:89]
	v_mfma_f32_16x16x32_bf16 v[82:85], v[142:145], v[212:215], v[82:85]
	s_setprio 0
	s_setprio 1
	v_mfma_f32_16x16x32_bf16 v[110:113], v[146:149], v[174:177], v[110:113]
	v_mfma_f32_16x16x32_bf16 v[106:109], v[166:169], v[174:177], v[106:109]
	v_mfma_f32_16x16x32_bf16 v[94:97], v[146:149], v[192:195], v[94:97]
	v_mfma_f32_16x16x32_bf16 v[90:93], v[166:169], v[192:195], v[90:93]
	v_mfma_f32_16x16x32_bf16 v[78:81], v[146:149], v[200:203], v[78:81]
	v_mfma_f32_16x16x32_bf16 v[74:77], v[166:169], v[200:203], v[74:77]
	v_mfma_f32_16x16x32_bf16 v[70:73], v[146:149], v[208:211], v[70:73]
	v_mfma_f32_16x16x32_bf16 v[66:69], v[166:169], v[208:211], v[66:69]
	v_mfma_f32_16x16x32_bf16 v[110:113], v[150:153], v[188:191], v[110:113]
	v_mfma_f32_16x16x32_bf16 v[106:109], v[170:173], v[188:191], v[106:109]
	v_mfma_f32_16x16x32_bf16 v[94:97], v[150:153], v[196:199], v[94:97]
	v_mfma_f32_16x16x32_bf16 v[90:93], v[170:173], v[196:199], v[90:93]
	v_mfma_f32_16x16x32_bf16 v[78:81], v[150:153], v[204:207], v[78:81]
	v_mfma_f32_16x16x32_bf16 v[74:77], v[170:173], v[204:207], v[74:77]
	v_mfma_f32_16x16x32_bf16 v[70:73], v[150:153], v[212:215], v[70:73]
	v_mfma_f32_16x16x32_bf16 v[66:69], v[170:173], v[212:215], v[66:69]
	s_setprio 0
	s_barrier
	s_add_i32 s41, s41, s34
	v_lshl_add_u64 v[178:179], s[14:15], 0, v[156:157]
	s_mov_b32 m0, s41
	ds_read_b128 v[174:177], v181 offset:16384
	ds_read_b128 v[188:191], v181 offset:17408
	ds_read_b128 v[192:195], v181 offset:18432
	ds_read_b128 v[196:199], v181 offset:19456
	ds_read_b128 v[200:203], v181 offset:20480
	ds_read_b128 v[204:207], v181 offset:21504
	ds_read_b128 v[208:211], v181 offset:22528
	ds_read_b128 v[212:215], v181 offset:23552
	global_load_lds_dwordx4 v156, s[14:15]
	s_add_i32 m0, s41, 0x2000
	s_add_u32 s52, s14, 0x80000
	v_lshl_add_u64 v[184:185], s[14:15], 0, v[160:161]
	s_addc_u32 s53, s15, 0
	s_add_i32 s41, s62, s34
	global_load_lds_dwordx4 v160, s[14:15]
	s_nop 0
	s_mov_b32 m0, s41
	v_lshl_add_u64 v[218:219], s[26:27], 0, v[158:159]
	global_load_lds_dwordx4 v156, s[52:53]
	s_nop 0
	s_add_i32 m0, s41, 0x2000
	s_nop 0
	global_load_lds_dwordx4 v160, s[52:53]
	v_lshl_add_u64 v[216:217], s[26:27], 0, v[154:155]
	s_mov_b32 m0, s35
	s_nop 0
	global_load_lds_dwordx4 v154, s[26:27]
	s_mov_b32 m0, s42
	s_nop 0
	global_load_lds_dwordx4 v158, s[26:27]
	s_waitcnt vmcnt(8)
	s_waitcnt lgkmcnt(0)
	s_barrier
; #define PG8_STAGE(bufoff, gbase, voff) do { _Pragma("unroll") for (int _i = 0; _i < 2; ++_i) \
;         __builtin_amdgcn_global_load_lds((const unsigned*)((const char*)(gbase) + (voff)[_i]), (LAS unsigned*)(lds + (bufoff) + ldsw + _i * 8192), 16, 0, 0); } while (0)
; #define PG8_LDA(dst, b, h) do { _Pragma("unroll") for (int m = 0; m < 4; ++m) _Pragma("unroll") for (int k = 0; k < 2; ++k) dst[m][k] = *(const LAS bf16x8*)(lds + PG8_SA(b, h) + aoff + m * 2048 + k * 1024); } while (0)
; #define PG8_LDB(dst, b, h) do { _Pragma("unroll") for (int n = 0; n < 2; ++n) _Pragma("unroll") for (int k = 0; k < 2; ++k) dst[n][k] = *(const LAS bf16x8*)(lds + PG8_SB(b, h) + boff + n * 2048 + k * 1024); } while (0)
; #define PG8_MMA(ai, bj, At, Bt) do { __builtin_amdgcn_s_setprio(1); _Pragma("unroll") for (int m = 0; m < 4; ++m) _Pragma("unroll") for (int n = 0; n < 2; ++n) _Pragma("unroll") for (int k = 0; k < 2; ++k) \
;         acc[ai][bj][m][n] = __builtin_amdgcn_mfma_f32_16x16x32_bf16(Bt[n][k], At[m][k], acc[ai][bj][m][n], 0, 0, 0); __builtin_amdgcn_s_setprio(0); } while (0)
; #define PG8_WAIT_V(n) asm volatile("s_waitcnt vmcnt(" #n ")" ::: "memory")
; #define PG8_WAIT_L(n) asm volatile("s_waitcnt lgkmcnt(" #n ")" ::: "memory")
; #define PG8_BAR __builtin_amdgcn_s_barrier()
; #define PG8_SCHED __builtin_amdgcn_sched_barrier(0)
; template <class Epi>
; __device__ __forceinline__ void gemm_phase(LAS unsigned char* lds, const Gemm g, const StaticOrder& S, const Epi& E) {
;     ...
;             PG8_WAIT_V(8); PG8_WAIT_L(0); PG8_BAR; PG8_MMA(1, 0, At, B0); PG8_MMA(1, 1, At, B1); PG8_BAR; PG8_SCHED;
;             PG8_LDB(B0, 1, 0); PG8_LDB(B1, 1, 1); PG8_SCHED; PG8_LDA(At, 1, 0); PG8_STAGE(PG8_SA(0, 1), a2 + hstepA, voffA);
;             PG8_WAIT_V(8); PG8_WAIT_L(0); PG8_BAR; PG8_MMA(0, 0, At, B0); PG8_MMA(0, 1, At, B1); PG8_BAR; PG8_SCHED;
	s_setprio 1
	s_waitcnt lgkmcnt(0)
	v_mfma_f32_16x16x32_bf16 v[62:65], v[130:133], v[174:177], v[62:65]
	v_mfma_f32_16x16x32_bf16 v[58:61], v[138:141], v[174:177], v[58:61]
	v_mfma_f32_16x16x32_bf16 v[54:57], v[130:133], v[192:195], v[54:57]
	v_mfma_f32_16x16x32_bf16 v[50:53], v[138:141], v[192:195], v[50:53]
	v_mfma_f32_16x16x32_bf16 v[46:49], v[130:133], v[200:203], v[46:49]
	v_mfma_f32_16x16x32_bf16 v[38:41], v[138:141], v[200:203], v[38:41]
	v_mfma_f32_16x16x32_bf16 v[30:33], v[130:133], v[208:211], v[30:33]
	v_mfma_f32_16x16x32_bf16 v[22:25], v[138:141], v[208:211], v[22:25]
	v_mfma_f32_16x16x32_bf16 v[62:65], v[134:137], v[188:191], v[62:65]
	v_mfma_f32_16x16x32_bf16 v[58:61], v[142:145], v[188:191], v[58:61]
	v_mfma_f32_16x16x32_bf16 v[54:57], v[134:137], v[196:199], v[54:57]
	v_mfma_f32_16x16x32_bf16 v[50:53], v[142:145], v[196:199], v[50:53]
	v_mfma_f32_16x16x32_bf16 v[46:49], v[134:137], v[204:207], v[46:49]
	v_mfma_f32_16x16x32_bf16 v[38:41], v[142:145], v[204:207], v[38:41]
	v_mfma_f32_16x16x32_bf16 v[30:33], v[134:137], v[212:215], v[30:33]
	v_mfma_f32_16x16x32_bf16 v[22:25], v[142:145], v[212:215], v[22:25]
	s_setprio 0
	s_setprio 1
	v_mfma_f32_16x16x32_bf16 v[42:45], v[146:149], v[174:177], v[42:45]
	v_mfma_f32_16x16x32_bf16 v[34:37], v[166:169], v[174:177], v[34:37]
	v_mfma_f32_16x16x32_bf16 v[26:29], v[146:149], v[192:195], v[26:29]
	v_mfma_f32_16x16x32_bf16 v[18:21], v[166:169], v[192:195], v[18:21]
	v_mfma_f32_16x16x32_bf16 v[14:17], v[146:149], v[200:203], v[14:17]
	v_mfma_f32_16x16x32_bf16 v[10:13], v[166:169], v[200:203], v[10:13]
	v_mfma_f32_16x16x32_bf16 v[6:9], v[146:149], v[208:211], v[6:9]
	v_mfma_f32_16x16x32_bf16 v[2:5], v[166:169], v[208:211], v[2:5]
	v_mfma_f32_16x16x32_bf16 v[42:45], v[150:153], v[188:191], v[42:45]
	v_mfma_f32_16x16x32_bf16 v[34:37], v[170:173], v[188:191], v[34:37]
	v_mfma_f32_16x16x32_bf16 v[26:29], v[150:153], v[196:199], v[26:29]
	v_mfma_f32_16x16x32_bf16 v[18:21], v[170:173], v[196:199], v[18:21]
	v_mfma_f32_16x16x32_bf16 v[14:17], v[150:153], v[204:207], v[14:17]
	v_mfma_f32_16x16x32_bf16 v[10:13], v[170:173], v[204:207], v[10:13]
	v_mfma_f32_16x16x32_bf16 v[6:9], v[150:153], v[212:215], v[6:9]
	v_mfma_f32_16x16x32_bf16 v[2:5], v[170:173], v[212:215], v[2:5]
	s_setprio 0
	s_barrier
	s_add_i32 s41, 0, 0x18000
	s_add_i32 s52, 0, 0x1c000
	v_add_u32_e32 v142, s41, v1
	v_add_u32_e32 v170, s52, v1
	ds_read_b128 v[130:133], v142
	ds_read_b128 v[134:137], v142 offset:1024
	ds_read_b128 v[138:141], v142 offset:2048
	ds_read_b128 v[142:145], v142 offset:3072
	ds_read_b128 v[146:149], v170
	ds_read_b128 v[150:153], v170 offset:1024
	ds_read_b128 v[166:169], v170 offset:2048
	ds_read_b128 v[170:173], v170 offset:3072
	s_add_u32 s26, s26, 0x80000
	s_addc_u32 s27, s27, 0
	s_mov_b32 m0, s44
	s_nop 0
	ds_read_b128 v[174:177], v181 offset:32768
	ds_read_b128 v[188:191], v181 offset:33792
	ds_read_b128 v[192:195], v181 offset:34816
	ds_read_b128 v[196:199], v181 offset:35840
	ds_read_b128 v[200:203], v181 offset:36864
	ds_read_b128 v[204:207], v181 offset:37888
	ds_read_b128 v[208:211], v181 offset:38912
	ds_read_b128 v[212:215], v181 offset:39936
	global_load_lds_dwordx4 v154, s[26:27]
	s_nop 0
	s_mov_b32 m0, s45
	s_nop 0
	global_load_lds_dwordx4 v158, s[26:27]
	s_waitcnt vmcnt(8)
	s_waitcnt lgkmcnt(0)
	s_barrier
	s_setprio 1
	s_waitcnt lgkmcnt(0)
	v_mfma_f32_16x16x32_bf16 v[126:129], v[130:133], v[174:177], v[126:129]
	v_mfma_f32_16x16x32_bf16 v[122:125], v[138:141], v[174:177], v[122:125]
	v_mfma_f32_16x16x32_bf16 v[118:121], v[130:133], v[192:195], v[118:121]
	v_mfma_f32_16x16x32_bf16 v[114:117], v[138:141], v[192:195], v[114:117]
	v_mfma_f32_16x16x32_bf16 v[102:105], v[130:133], v[200:203], v[102:105]
	v_mfma_f32_16x16x32_bf16 v[98:101], v[138:141], v[200:203], v[98:101]
	v_mfma_f32_16x16x32_bf16 v[86:89], v[130:133], v[208:211], v[86:89]
	v_mfma_f32_16x16x32_bf16 v[82:85], v[138:141], v[208:211], v[82:85]
	v_mfma_f32_16x16x32_bf16 v[126:129], v[134:137], v[188:191], v[126:129]
	v_mfma_f32_16x16x32_bf16 v[122:125], v[142:145], v[188:191], v[122:125]
	v_mfma_f32_16x16x32_bf16 v[118:121], v[134:137], v[196:199], v[118:121]
	v_mfma_f32_16x16x32_bf16 v[114:117], v[142:145], v[196:199], v[114:117]
	v_mfma_f32_16x16x32_bf16 v[102:105], v[134:137], v[204:207], v[102:105]
	v_mfma_f32_16x16x32_bf16 v[98:101], v[142:145], v[204:207], v[98:101]
	v_mfma_f32_16x16x32_bf16 v[86:89], v[134:137], v[212:215], v[86:89]
	v_mfma_f32_16x16x32_bf16 v[82:85], v[142:145], v[212:215], v[82:85]
	s_setprio 0
	s_setprio 1
	v_mfma_f32_16x16x32_bf16 v[110:113], v[146:149], v[174:177], v[110:113]
	v_mfma_f32_16x16x32_bf16 v[106:109], v[166:169], v[174:177], v[106:109]
	v_mfma_f32_16x16x32_bf16 v[94:97], v[146:149], v[192:195], v[94:97]
	v_mfma_f32_16x16x32_bf16 v[90:93], v[166:169], v[192:195], v[90:93]
	v_mfma_f32_16x16x32_bf16 v[78:81], v[146:149], v[200:203], v[78:81]
	v_mfma_f32_16x16x32_bf16 v[74:77], v[166:169], v[200:203], v[74:77]
	v_mfma_f32_16x16x32_bf16 v[70:73], v[146:149], v[208:211], v[70:73]
	v_mfma_f32_16x16x32_bf16 v[66:69], v[166:169], v[208:211], v[66:69]
	v_mfma_f32_16x16x32_bf16 v[110:113], v[150:153], v[188:191], v[110:113]
	v_mfma_f32_16x16x32_bf16 v[106:109], v[170:173], v[188:191], v[106:109]
	v_mfma_f32_16x16x32_bf16 v[94:97], v[150:153], v[196:199], v[94:97]
	v_mfma_f32_16x16x32_bf16 v[90:93], v[170:173], v[196:199], v[90:93]
	v_mfma_f32_16x16x32_bf16 v[78:81], v[150:153], v[204:207], v[78:81]
	v_mfma_f32_16x16x32_bf16 v[74:77], v[170:173], v[204:207], v[74:77]
	v_mfma_f32_16x16x32_bf16 v[70:73], v[150:153], v[212:215], v[70:73]
	v_mfma_f32_16x16x32_bf16 v[66:69], v[170:173], v[212:215], v[66:69]
	s_setprio 0
	s_barrier
; #define PG8_STAGE(bufoff, gbase, voff) do { _Pragma("unroll") for (int _i = 0; _i < 2; ++_i) \
;         __builtin_amdgcn_global_load_lds((const unsigned*)((const char*)(gbase) + (voff)[_i]), (LAS unsigned*)(lds + (bufoff) + ldsw + _i * 8192), 16, 0, 0); } while (0)
; #define PG8_LDA(dst, b, h) do { _Pragma("unroll") for (int m = 0; m < 4; ++m) _Pragma("unroll") for (int k = 0; k < 2; ++k) dst[m][k] = *(const LAS bf16x8*)(lds + PG8_SA(b, h) + aoff + m * 2048 + k * 1024); } while (0)
; #define PG8_MMA(ai, bj, At, Bt) do { __builtin_amdgcn_s_setprio(1); _Pragma("unroll") for (int m = 0; m < 4; ++m) _Pragma("unroll") for (int n = 0; n < 2; ++n) _Pragma("unroll") for (int k = 0; k < 2; ++k) \
;         acc[ai][bj][m][n] = __builtin_amdgcn_mfma_f32_16x16x32_bf16(Bt[n][k], At[m][k], acc[ai][bj][m][n], 0, 0, 0); __builtin_amdgcn_s_setprio(0); } while (0)
; #define PG8_WAIT_V(n) asm volatile("s_waitcnt vmcnt(" #n ")" ::: "memory")
; #define PG8_WAIT_L(n) asm volatile("s_waitcnt lgkmcnt(" #n ")" ::: "memory")
; #define PG8_BAR __builtin_amdgcn_s_barrier()
; #define PG8_SCHED __builtin_amdgcn_sched_barrier(0)
; template <class Epi>
; __device__ __forceinline__ void gemm_phase(LAS unsigned char* lds, const Gemm g, const StaticOrder& S, const Epi& E) {
;     ...
;             PG8_LDA(At, 1, 1); PG8_STAGE(PG8_SB(1, 0), b3, voffB); PG8_STAGE(PG8_SB(1, 1), b3 + hstepB, voffB); PG8_STAGE(PG8_SA(1, 0), a3, voffA);
;             PG8_WAIT_V(8); PG8_WAIT_L(0); PG8_BAR; PG8_MMA(1, 0, At, B0); PG8_MMA(1, 1, At, B1); PG8_BAR; PG8_SCHED;
;         }
;         if (wr == 0) PG8_BAR;
	s_add_i32 s26, s41, s34
	v_lshl_add_u64 v[178:179], v[178:179], 0, s[84:85]
	s_mov_b32 m0, s26
	ds_read_b128 v[174:177], v181 offset:49152
	ds_read_b128 v[188:191], v181 offset:50176
	ds_read_b128 v[192:195], v181 offset:51200
	ds_read_b128 v[196:199], v181 offset:52224
	ds_read_b128 v[200:203], v181 offset:53248
	ds_read_b128 v[204:207], v181 offset:54272
	ds_read_b128 v[208:211], v181 offset:55296
	ds_read_b128 v[212:215], v181 offset:56320
	global_load_lds_dwordx4 v[178:179], off
	s_add_i32 m0, s26, 0x2000
	s_add_u32 s14, s14, 0x80080
	v_lshl_add_u64 v[178:179], v[184:185], 0, s[84:85]
	s_addc_u32 s15, s15, 0
	s_add_i32 s26, s52, s34
	global_load_lds_dwordx4 v[178:179], off
	s_nop 0
	s_mov_b32 m0, s26
	s_nop 0
	global_load_lds_dwordx4 v156, s[14:15]
	s_nop 0
	s_add_i32 m0, s26, 0x2000
	s_nop 0
	global_load_lds_dwordx4 v160, s[14:15]
	v_lshl_add_u64 v[178:179], v[216:217], 0, s[84:85]
	s_mov_b32 m0, s86
	s_nop 0
	global_load_lds_dwordx4 v[178:179], off
	v_lshl_add_u64 v[178:179], v[218:219], 0, s[84:85]
	s_mov_b32 m0, s87
	s_nop 0
	global_load_lds_dwordx4 v[178:179], off
	s_waitcnt vmcnt(8)
	s_waitcnt lgkmcnt(0)
	s_barrier
	s_setprio 1
	s_waitcnt lgkmcnt(0)
	v_mfma_f32_16x16x32_bf16 v[62:65], v[130:133], v[174:177], v[62:65]
	v_mfma_f32_16x16x32_bf16 v[58:61], v[138:141], v[174:177], v[58:61]
	v_mfma_f32_16x16x32_bf16 v[54:57], v[130:133], v[192:195], v[54:57]
	v_mfma_f32_16x16x32_bf16 v[50:53], v[138:141], v[192:195], v[50:53]
	v_mfma_f32_16x16x32_bf16 v[46:49], v[130:133], v[200:203], v[46:49]
	v_mfma_f32_16x16x32_bf16 v[38:41], v[138:141], v[200:203], v[38:41]
	v_mfma_f32_16x16x32_bf16 v[30:33], v[130:133], v[208:211], v[30:33]
	v_mfma_f32_16x16x32_bf16 v[22:25], v[138:141], v[208:211], v[22:25]
	v_mfma_f32_16x16x32_bf16 v[62:65], v[134:137], v[188:191], v[62:65]
	v_mfma_f32_16x16x32_bf16 v[58:61], v[142:145], v[188:191], v[58:61]
	v_mfma_f32_16x16x32_bf16 v[54:57], v[134:137], v[196:199], v[54:57]
	v_mfma_f32_16x16x32_bf16 v[50:53], v[142:145], v[196:199], v[50:53]
	v_mfma_f32_16x16x32_bf16 v[46:49], v[134:137], v[204:207], v[46:49]
	v_mfma_f32_16x16x32_bf16 v[38:41], v[142:145], v[204:207], v[38:41]
	v_mfma_f32_16x16x32_bf16 v[30:33], v[134:137], v[212:215], v[30:33]
	v_mfma_f32_16x16x32_bf16 v[22:25], v[142:145], v[212:215], v[22:25]
	s_setprio 0
	s_setprio 1
	v_mfma_f32_16x16x32_bf16 v[42:45], v[146:149], v[174:177], v[42:45]
	v_mfma_f32_16x16x32_bf16 v[34:37], v[166:169], v[174:177], v[34:37]
	v_mfma_f32_16x16x32_bf16 v[26:29], v[146:149], v[192:195], v[26:29]
	v_mfma_f32_16x16x32_bf16 v[18:21], v[166:169], v[192:195], v[18:21]
	v_mfma_f32_16x16x32_bf16 v[14:17], v[146:149], v[200:203], v[14:17]
	v_mfma_f32_16x16x32_bf16 v[10:13], v[166:169], v[200:203], v[10:13]
	v_mfma_f32_16x16x32_bf16 v[6:9], v[146:149], v[208:211], v[6:9]
	v_mfma_f32_16x16x32_bf16 v[2:5], v[166:169], v[208:211], v[2:5]
	v_mfma_f32_16x16x32_bf16 v[42:45], v[150:153], v[188:191], v[42:45]
	v_mfma_f32_16x16x32_bf16 v[34:37], v[170:173], v[188:191], v[34:37]
	v_mfma_f32_16x16x32_bf16 v[26:29], v[150:153], v[196:199], v[26:29]
	v_mfma_f32_16x16x32_bf16 v[18:21], v[170:173], v[196:199], v[18:21]
	v_mfma_f32_16x16x32_bf16 v[14:17], v[150:153], v[204:207], v[14:17]
	v_mfma_f32_16x16x32_bf16 v[10:13], v[170:173], v[204:207], v[10:13]
	v_mfma_f32_16x16x32_bf16 v[6:9], v[150:153], v[212:215], v[6:9]
	v_mfma_f32_16x16x32_bf16 v[2:5], v[170:173], v[212:215], v[2:5]
	s_setprio 0
	s_barrier
	s_add_i32 s40, s40, 2
	s_add_u32 s24, s24, 0x100
	s_addc_u32 s25, s25, 0
	s_add_u32 s19, s19, 0x100
	s_addc_u32 s33, s33, 0
	s_cmp_gt_u32 s40, 29
	s_cbranch_scc0 .LBB0_2332
	s_and_b64 vcc, exec, s[12:13]
	s_cbranch_vccz .LBB0_2335
	s_barrier

; #define PG8_STAGE(bufoff, gbase, voff) do { _Pragma("unroll") for (int _i = 0; _i < 2; ++_i) \
;         __builtin_amdgcn_global_load_lds((const unsigned*)((const char*)(gbase) + (voff)[_i]), (LAS unsigned*)(lds + (bufoff) + ldsw + _i * 8192), 16, 0, 0); } while (0)
; #define PG8_LDA(dst, b, h) do { _Pragma("unroll") for (int m = 0; m < 4; ++m) _Pragma("unroll") for (int k = 0; k < 2; ++k) dst[m][k] = *(const LAS bf16x8*)(lds + PG8_SA(b, h) + aoff + m * 2048 + k * 1024); } while (0)
; #define PG8_LDB(dst, b, h) do { _Pragma("unroll") for (int n = 0; n < 2; ++n) _Pragma("unroll") for (int k = 0; k < 2; ++k) dst[n][k] = *(const LAS bf16x8*)(lds + PG8_SB(b, h) + boff + n * 2048 + k * 1024); } while (0)
; #define PG8_MMA(ai, bj, At, Bt) do { __builtin_amdgcn_s_setprio(1); _Pragma("unroll") for (int m = 0; m < 4; ++m) _Pragma("unroll") for (int n = 0; n < 2; ++n) _Pragma("unroll") for (int k = 0; k < 2; ++k) \
;         acc[ai][bj][m][n] = __builtin_amdgcn_mfma_f32_16x16x32_bf16(Bt[n][k], At[m][k], acc[ai][bj][m][n], 0, 0, 0); __builtin_amdgcn_s_setprio(0); } while (0)
; #define PG8_WAIT_V(n) asm volatile("s_waitcnt vmcnt(" #n ")" ::: "memory")
; #define PG8_WAIT_L(n) asm volatile("s_waitcnt lgkmcnt(" #n ")" ::: "memory")
; #define PG8_BAR __builtin_amdgcn_s_barrier()
; #define PG8_SCHED __builtin_amdgcn_sched_barrier(0)
; template <class Epi>
; __device__ __forceinline__ void gemm_phase(LAS unsigned char* lds, const Gemm g, const StaticOrder& S, const Epi& E) {
;     ...
;             const bool last = (t == nt - 2);
;             const char* a1 = cA + (size_t)(t + 1) * kstep;
;             const char* a2 = last ? nA : cA + (size_t)(t + 2) * kstep; const char* b2 = last ? nB : cB + (size_t)(t + 2) * kstep;
;             const char* a3 = a2 + kstep; const char* b3 = b2 + kstep;
;             PG8_LDB(B0, 0, 0); PG8_LDB(B1, 0, 1); PG8_SCHED; PG8_LDA(At, 0, 0); PG8_STAGE(PG8_SA(1, 1), a1 + hstepA, voffA);
;             PG8_WAIT_V(8); PG8_WAIT_L(0); PG8_BAR; PG8_MMA(0, 0, At, B0); PG8_MMA(0, 1, At, B1); PG8_BAR; PG8_SCHED;
;             PG8_LDA(At, 0, 1); PG8_STAGE(PG8_SB(0, 0), b2, voffB); PG8_STAGE(PG8_SB(0, 1), b2 + hstepB, voffB); PG8_STAGE(PG8_SA(0, 0), a2, voffA);
;             PG8_WAIT_V(8); PG8_WAIT_L(0); PG8_BAR; PG8_MMA(1, 0, At, B0); PG8_MMA(1, 1, At, B1); PG8_BAR; PG8_SCHED;
.LBB0_2376:
	s_add_u32 s14, s22, 0xfff80080
	s_addc_u32 s15, s23, -1
	s_add_i32 s53, 0, 0x10000
	s_cmp_eq_u32 s41, 28
	s_cselect_b32 s25, s3, s15
	s_cselect_b32 s24, s9, s14
	s_cselect_b32 s15, s13, s52
	s_cselect_b32 s14, s17, s40
	s_add_i32 s64, 0, 0x14000
	v_add_u32_e32 v142, s53, v1
	v_add_u32_e32 v170, s64, v1
	ds_read_b128 v[130:133], v142
	ds_read_b128 v[134:137], v142 offset:1024
	ds_read_b128 v[138:141], v142 offset:2048
	ds_read_b128 v[142:145], v142 offset:3072
	ds_read_b128 v[146:149], v170
	ds_read_b128 v[150:153], v170 offset:1024
	ds_read_b128 v[166:169], v170 offset:2048
	ds_read_b128 v[170:173], v170 offset:3072
	s_nop 0
	s_add_i32 m0, s30, 0xc000
	ds_read_b128 v[174:177], v181
	ds_read_b128 v[188:191], v181 offset:1024
	ds_read_b128 v[192:195], v181 offset:2048
	ds_read_b128 v[196:199], v181 offset:3072
	ds_read_b128 v[200:203], v181 offset:4096
	ds_read_b128 v[204:207], v181 offset:5120
	ds_read_b128 v[208:211], v181 offset:6144
	ds_read_b128 v[212:215], v181 offset:7168
	global_load_lds_dwordx4 v162, s[22:23]
	s_nop 0
	s_add_i32 m0, s30, 0xe000
	s_nop 0
	global_load_lds_dwordx4 v164, s[22:23]
	s_waitcnt vmcnt(8)
	s_waitcnt lgkmcnt(0)
	s_barrier
	s_setprio 1
	s_waitcnt lgkmcnt(0)
	v_mfma_f32_16x16x32_bf16 v[126:129], v[130:133], v[174:177], v[126:129]
	v_mfma_f32_16x16x32_bf16 v[122:125], v[138:141], v[174:177], v[122:125]
	v_mfma_f32_16x16x32_bf16 v[118:121], v[130:133], v[192:195], v[118:121]
	v_mfma_f32_16x16x32_bf16 v[114:117], v[138:141], v[192:195], v[114:117]
	v_mfma_f32_16x16x32_bf16 v[102:105], v[130:133], v[200:203], v[102:105]
	v_mfma_f32_16x16x32_bf16 v[98:101], v[138:141], v[200:203], v[98:101]
	v_mfma_f32_16x16x32_bf16 v[86:89], v[130:133], v[208:211], v[86:89]
	v_mfma_f32_16x16x32_bf16 v[82:85], v[138:141], v[208:211], v[82:85]
	v_mfma_f32_16x16x32_bf16 v[126:129], v[134:137], v[188:191], v[126:129]
	v_mfma_f32_16x16x32_bf16 v[122:125], v[142:145], v[188:191], v[122:125]
	v_mfma_f32_16x16x32_bf16 v[118:121], v[134:137], v[196:199], v[118:121]
	v_mfma_f32_16x16x32_bf16 v[114:117], v[142:145], v[196:199], v[114:117]
	v_mfma_f32_16x16x32_bf16 v[102:105], v[134:137], v[204:207], v[102:105]
	v_mfma_f32_16x16x32_bf16 v[98:101], v[142:145], v[204:207], v[98:101]
	v_mfma_f32_16x16x32_bf16 v[86:89], v[134:137], v[212:215], v[86:89]
	v_mfma_f32_16x16x32_bf16 v[82:85], v[142:145], v[212:215], v[82:85]
	s_setprio 0
	s_setprio 1
	v_mfma_f32_16x16x32_bf16 v[110:113], v[146:149], v[174:177], v[110:113]
	v_mfma_f32_16x16x32_bf16 v[106:109], v[166:169], v[174:177], v[106:109]
	v_mfma_f32_16x16x32_bf16 v[94:97], v[146:149], v[192:195], v[94:97]
	v_mfma_f32_16x16x32_bf16 v[90:93], v[166:169], v[192:195], v[90:93]
	v_mfma_f32_16x16x32_bf16 v[78:81], v[146:149], v[200:203], v[78:81]
	v_mfma_f32_16x16x32_bf16 v[74:77], v[166:169], v[200:203], v[74:77]
	v_mfma_f32_16x16x32_bf16 v[70:73], v[146:149], v[208:211], v[70:73]
	v_mfma_f32_16x16x32_bf16 v[66:69], v[166:169], v[208:211], v[66:69]
	v_mfma_f32_16x16x32_bf16 v[110:113], v[150:153], v[188:191], v[110:113]
	v_mfma_f32_16x16x32_bf16 v[106:109], v[170:173], v[188:191], v[106:109]
	v_mfma_f32_16x16x32_bf16 v[94:97], v[150:153], v[196:199], v[94:97]
	v_mfma_f32_16x16x32_bf16 v[90:93], v[170:173], v[196:199], v[90:93]
	v_mfma_f32_16x16x32_bf16 v[78:81], v[150:153], v[204:207], v[78:81]
	v_mfma_f32_16x16x32_bf16 v[74:77], v[170:173], v[204:207], v[74:77]
	v_mfma_f32_16x16x32_bf16 v[70:73], v[150:153], v[212:215], v[70:73]
	v_mfma_f32_16x16x32_bf16 v[66:69], v[170:173], v[212:215], v[66:69]
	s_setprio 0
	s_barrier
	s_add_i32 s53, s53, s27
	v_lshl_add_u64 v[178:179], s[14:15], 0, v[156:157]
	s_mov_b32 m0, s53
	ds_read_b128 v[174:177], v181 offset:16384
	ds_read_b128 v[188:191], v181 offset:17408
	ds_read_b128 v[192:195], v181 offset:18432
	ds_read_b128 v[196:199], v181 offset:19456
	ds_read_b128 v[200:203], v181 offset:20480
	ds_read_b128 v[204:207], v181 offset:21504
	ds_read_b128 v[208:211], v181 offset:22528
	ds_read_b128 v[212:215], v181 offset:23552
	global_load_lds_dwordx4 v156, s[14:15]
	s_add_i32 m0, s53, 0x2000
	s_add_u32 s62, s14, 0x80000
	v_lshl_add_u64 v[184:185], s[14:15], 0, v[160:161]
	s_addc_u32 s63, s15, 0
	s_add_i32 s53, s64, s27
	global_load_lds_dwordx4 v160, s[14:15]
	s_nop 0
	s_mov_b32 m0, s53
	v_lshl_add_u64 v[216:217], s[24:25], 0, v[158:159]
	global_load_lds_dwordx4 v156, s[62:63]
	s_nop 0
	s_add_i32 m0, s53, 0x2000
	s_nop 0
	global_load_lds_dwordx4 v160, s[62:63]
	v_lshl_add_u64 v[186:187], s[24:25], 0, v[154:155]
	s_mov_b32 m0, s30
	s_nop 0
	global_load_lds_dwordx4 v154, s[24:25]
	s_mov_b32 m0, s31
	s_nop 0
	global_load_lds_dwordx4 v158, s[24:25]
	s_waitcnt vmcnt(8)
	s_waitcnt lgkmcnt(0)
	s_barrier
; #define PG8_STAGE(bufoff, gbase, voff) do { _Pragma("unroll") for (int _i = 0; _i < 2; ++_i) \
;         __builtin_amdgcn_global_load_lds((const unsigned*)((const char*)(gbase) + (voff)[_i]), (LAS unsigned*)(lds + (bufoff) + ldsw + _i * 8192), 16, 0, 0); } while (0)
; #define PG8_LDA(dst, b, h) do { _Pragma("unroll") for (int m = 0; m < 4; ++m) _Pragma("unroll") for (int k = 0; k < 2; ++k) dst[m][k] = *(const LAS bf16x8*)(lds + PG8_SA(b, h) + aoff + m * 2048 + k * 1024); } while (0)
; #define PG8_LDB(dst, b, h) do { _Pragma("unroll") for (int n = 0; n < 2; ++n) _Pragma("unroll") for (int k = 0; k < 2; ++k) dst[n][k] = *(const LAS bf16x8*)(lds + PG8_SB(b, h) + boff + n * 2048 + k * 1024); } while (0)
; #define PG8_MMA(ai, bj, At, Bt) do { __builtin_amdgcn_s_setprio(1); _Pragma("unroll") for (int m = 0; m < 4; ++m) _Pragma("unroll") for (int n = 0; n < 2; ++n) _Pragma("unroll") for (int k = 0; k < 2; ++k) \
;         acc[ai][bj][m][n] = __builtin_amdgcn_mfma_f32_16x16x32_bf16(Bt[n][k], At[m][k], acc[ai][bj][m][n], 0, 0, 0); __builtin_amdgcn_s_setprio(0); } while (0)
; #define PG8_WAIT_V(n) asm volatile("s_waitcnt vmcnt(" #n ")" ::: "memory")
; #define PG8_WAIT_L(n) asm volatile("s_waitcnt lgkmcnt(" #n ")" ::: "memory")
; #define PG8_BAR __builtin_amdgcn_s_barrier()
; #define PG8_SCHED __builtin_amdgcn_sched_barrier(0)
; template <class Epi>
; __device__ __forceinline__ void gemm_phase(LAS unsigned char* lds, const Gemm g, const StaticOrder& S, const Epi& E) {
;     ...
;             PG8_WAIT_V(8); PG8_WAIT_L(0); PG8_BAR; PG8_MMA(1, 0, At, B0); PG8_MMA(1, 1, At, B1); PG8_BAR; PG8_SCHED;
;             PG8_LDB(B0, 1, 0); PG8_LDB(B1, 1, 1); PG8_SCHED; PG8_LDA(At, 1, 0); PG8_STAGE(PG8_SA(0, 1), a2 + hstepA, voffA);
;             PG8_WAIT_V(8); PG8_WAIT_L(0); PG8_BAR; PG8_MMA(0, 0, At, B0); PG8_MMA(0, 1, At, B1); PG8_BAR; PG8_SCHED;
	s_setprio 1
	s_waitcnt lgkmcnt(0)
	v_mfma_f32_16x16x32_bf16 v[62:65], v[130:133], v[174:177], v[62:65]
	v_mfma_f32_16x16x32_bf16 v[58:61], v[138:141], v[174:177], v[58:61]
	v_mfma_f32_16x16x32_bf16 v[54:57], v[130:133], v[192:195], v[54:57]
	v_mfma_f32_16x16x32_bf16 v[50:53], v[138:141], v[192:195], v[50:53]
	v_mfma_f32_16x16x32_bf16 v[46:49], v[130:133], v[200:203], v[46:49]
	v_mfma_f32_16x16x32_bf16 v[38:41], v[138:141], v[200:203], v[38:41]
	v_mfma_f32_16x16x32_bf16 v[30:33], v[130:133], v[208:211], v[30:33]
	v_mfma_f32_16x16x32_bf16 v[22:25], v[138:141], v[208:211], v[22:25]
	v_mfma_f32_16x16x32_bf16 v[62:65], v[134:137], v[188:191], v[62:65]
	v_mfma_f32_16x16x32_bf16 v[58:61], v[142:145], v[188:191], v[58:61]
	v_mfma_f32_16x16x32_bf16 v[54:57], v[134:137], v[196:199], v[54:57]
	v_mfma_f32_16x16x32_bf16 v[50:53], v[142:145], v[196:199], v[50:53]
	v_mfma_f32_16x16x32_bf16 v[46:49], v[134:137], v[204:207], v[46:49]
	v_mfma_f32_16x16x32_bf16 v[38:41], v[142:145], v[204:207], v[38:41]
	v_mfma_f32_16x16x32_bf16 v[30:33], v[134:137], v[212:215], v[30:33]
	v_mfma_f32_16x16x32_bf16 v[22:25], v[142:145], v[212:215], v[22:25]
	s_setprio 0
	s_setprio 1
	v_mfma_f32_16x16x32_bf16 v[42:45], v[146:149], v[174:177], v[42:45]
	v_mfma_f32_16x16x32_bf16 v[34:37], v[166:169], v[174:177], v[34:37]
	v_mfma_f32_16x16x32_bf16 v[26:29], v[146:149], v[192:195], v[26:29]
	v_mfma_f32_16x16x32_bf16 v[18:21], v[166:169], v[192:195], v[18:21]
	v_mfma_f32_16x16x32_bf16 v[14:17], v[146:149], v[200:203], v[14:17]
	v_mfma_f32_16x16x32_bf16 v[10:13], v[166:169], v[200:203], v[10:13]
	v_mfma_f32_16x16x32_bf16 v[6:9], v[146:149], v[208:211], v[6:9]
	v_mfma_f32_16x16x32_bf16 v[2:5], v[166:169], v[208:211], v[2:5]
	v_mfma_f32_16x16x32_bf16 v[42:45], v[150:153], v[188:191], v[42:45]
	v_mfma_f32_16x16x32_bf16 v[34:37], v[170:173], v[188:191], v[34:37]
	v_mfma_f32_16x16x32_bf16 v[26:29], v[150:153], v[196:199], v[26:29]
	v_mfma_f32_16x16x32_bf16 v[18:21], v[170:173], v[196:199], v[18:21]
	v_mfma_f32_16x16x32_bf16 v[14:17], v[150:153], v[204:207], v[14:17]
	v_mfma_f32_16x16x32_bf16 v[10:13], v[170:173], v[204:207], v[10:13]
	v_mfma_f32_16x16x32_bf16 v[6:9], v[150:153], v[212:215], v[6:9]
	v_mfma_f32_16x16x32_bf16 v[2:5], v[170:173], v[212:215], v[2:5]
	s_setprio 0
	s_barrier
	s_add_i32 s53, 0, 0x18000
	s_add_i32 s62, 0, 0x1c000
	v_add_u32_e32 v142, s53, v1
	v_add_u32_e32 v170, s62, v1
	ds_read_b128 v[130:133], v142
	ds_read_b128 v[134:137], v142 offset:1024
	ds_read_b128 v[138:141], v142 offset:2048
	ds_read_b128 v[142:145], v142 offset:3072
	ds_read_b128 v[146:149], v170
	ds_read_b128 v[150:153], v170 offset:1024
	ds_read_b128 v[166:169], v170 offset:2048
	ds_read_b128 v[170:173], v170 offset:3072
	s_add_u32 s24, s24, 0x80000
	s_addc_u32 s25, s25, 0
	s_mov_b32 m0, s34
	s_nop 0
	ds_read_b128 v[174:177], v181 offset:32768
	ds_read_b128 v[188:191], v181 offset:33792
	ds_read_b128 v[192:195], v181 offset:34816
	ds_read_b128 v[196:199], v181 offset:35840
	ds_read_b128 v[200:203], v181 offset:36864
	ds_read_b128 v[204:207], v181 offset:37888
	ds_read_b128 v[208:211], v181 offset:38912
	ds_read_b128 v[212:215], v181 offset:39936
	global_load_lds_dwordx4 v154, s[24:25]
	s_nop 0
	s_mov_b32 m0, s35
	s_nop 0
	global_load_lds_dwordx4 v158, s[24:25]
	s_waitcnt vmcnt(8)
	s_waitcnt lgkmcnt(0)
	s_barrier
	s_setprio 1
	s_waitcnt lgkmcnt(0)
	v_mfma_f32_16x16x32_bf16 v[126:129], v[130:133], v[174:177], v[126:129]
	v_mfma_f32_16x16x32_bf16 v[122:125], v[138:141], v[174:177], v[122:125]
	v_mfma_f32_16x16x32_bf16 v[118:121], v[130:133], v[192:195], v[118:121]
	v_mfma_f32_16x16x32_bf16 v[114:117], v[138:141], v[192:195], v[114:117]
	v_mfma_f32_16x16x32_bf16 v[102:105], v[130:133], v[200:203], v[102:105]
	v_mfma_f32_16x16x32_bf16 v[98:101], v[138:141], v[200:203], v[98:101]
	v_mfma_f32_16x16x32_bf16 v[86:89], v[130:133], v[208:211], v[86:89]
	v_mfma_f32_16x16x32_bf16 v[82:85], v[138:141], v[208:211], v[82:85]
	v_mfma_f32_16x16x32_bf16 v[126:129], v[134:137], v[188:191], v[126:129]
	v_mfma_f32_16x16x32_bf16 v[122:125], v[142:145], v[188:191], v[122:125]
	v_mfma_f32_16x16x32_bf16 v[118:121], v[134:137], v[196:199], v[118:121]
	v_mfma_f32_16x16x32_bf16 v[114:117], v[142:145], v[196:199], v[114:117]
	v_mfma_f32_16x16x32_bf16 v[102:105], v[134:137], v[204:207], v[102:105]
	v_mfma_f32_16x16x32_bf16 v[98:101], v[142:145], v[204:207], v[98:101]
	v_mfma_f32_16x16x32_bf16 v[86:89], v[134:137], v[212:215], v[86:89]
	v_mfma_f32_16x16x32_bf16 v[82:85], v[142:145], v[212:215], v[82:85]
	s_setprio 0
	s_setprio 1
	v_mfma_f32_16x16x32_bf16 v[110:113], v[146:149], v[174:177], v[110:113]
	v_mfma_f32_16x16x32_bf16 v[106:109], v[166:169], v[174:177], v[106:109]
	v_mfma_f32_16x16x32_bf16 v[94:97], v[146:149], v[192:195], v[94:97]
	v_mfma_f32_16x16x32_bf16 v[90:93], v[166:169], v[192:195], v[90:93]
	v_mfma_f32_16x16x32_bf16 v[78:81], v[146:149], v[200:203], v[78:81]
	v_mfma_f32_16x16x32_bf16 v[74:77], v[166:169], v[200:203], v[74:77]
	v_mfma_f32_16x16x32_bf16 v[70:73], v[146:149], v[208:211], v[70:73]
	v_mfma_f32_16x16x32_bf16 v[66:69], v[166:169], v[208:211], v[66:69]
	v_mfma_f32_16x16x32_bf16 v[110:113], v[150:153], v[188:191], v[110:113]
	v_mfma_f32_16x16x32_bf16 v[106:109], v[170:173], v[188:191], v[106:109]
	v_mfma_f32_16x16x32_bf16 v[94:97], v[150:153], v[196:199], v[94:97]
	v_mfma_f32_16x16x32_bf16 v[90:93], v[170:173], v[196:199], v[90:93]
	v_mfma_f32_16x16x32_bf16 v[78:81], v[150:153], v[204:207], v[78:81]
	v_mfma_f32_16x16x32_bf16 v[74:77], v[170:173], v[204:207], v[74:77]
	v_mfma_f32_16x16x32_bf16 v[70:73], v[150:153], v[212:215], v[70:73]
	v_mfma_f32_16x16x32_bf16 v[66:69], v[170:173], v[212:215], v[66:69]
	s_setprio 0
	s_barrier
; #define PG8_STAGE(bufoff, gbase, voff) do { _Pragma("unroll") for (int _i = 0; _i < 2; ++_i) \
;         __builtin_amdgcn_global_load_lds((const unsigned*)((const char*)(gbase) + (voff)[_i]), (LAS unsigned*)(lds + (bufoff) + ldsw + _i * 8192), 16, 0, 0); } while (0)
; #define PG8_LDA(dst, b, h) do { _Pragma("unroll") for (int m = 0; m < 4; ++m) _Pragma("unroll") for (int k = 0; k < 2; ++k) dst[m][k] = *(const LAS bf16x8*)(lds + PG8_SA(b, h) + aoff + m * 2048 + k * 1024); } while (0)
; #define PG8_MMA(ai, bj, At, Bt) do { __builtin_amdgcn_s_setprio(1); _Pragma("unroll") for (int m = 0; m < 4; ++m) _Pragma("unroll") for (int n = 0; n < 2; ++n) _Pragma("unroll") for (int k = 0; k < 2; ++k) \
;         acc[ai][bj][m][n] = __builtin_amdgcn_mfma_f32_16x16x32_bf16(Bt[n][k], At[m][k], acc[ai][bj][m][n], 0, 0, 0); __builtin_amdgcn_s_setprio(0); } while (0)
; #define PG8_WAIT_V(n) asm volatile("s_waitcnt vmcnt(" #n ")" ::: "memory")
; #define PG8_WAIT_L(n) asm volatile("s_waitcnt lgkmcnt(" #n ")" ::: "memory")
; #define PG8_BAR __builtin_amdgcn_s_barrier()
; #define PG8_SCHED __builtin_amdgcn_sched_barrier(0)
; template <class Epi>
; __device__ __forceinline__ void gemm_phase(LAS unsigned char* lds, const Gemm g, const StaticOrder& S, const Epi& E) {
;     ...
;             PG8_LDA(At, 1, 1); PG8_STAGE(PG8_SB(1, 0), b3, voffB); PG8_STAGE(PG8_SB(1, 1), b3 + hstepB, voffB); PG8_STAGE(PG8_SA(1, 0), a3, voffA);
;             PG8_WAIT_V(8); PG8_WAIT_L(0); PG8_BAR; PG8_MMA(1, 0, At, B0); PG8_MMA(1, 1, At, B1); PG8_BAR; PG8_SCHED;
;         }
;         if (wr == 0) PG8_BAR;
	s_add_i32 s24, s53, s27
	v_lshl_add_u64 v[178:179], v[178:179], 0, s[84:85]
	s_mov_b32 m0, s24
	ds_read_b128 v[174:177], v181 offset:49152
	ds_read_b128 v[188:191], v181 offset:50176
	ds_read_b128 v[192:195], v181 offset:51200
	ds_read_b128 v[196:199], v181 offset:52224
	ds_read_b128 v[200:203], v181 offset:53248
	ds_read_b128 v[204:207], v181 offset:54272
	ds_read_b128 v[208:211], v181 offset:55296
	ds_read_b128 v[212:215], v181 offset:56320
	global_load_lds_dwordx4 v[178:179], off
	s_add_i32 m0, s24, 0x2000
	s_add_u32 s14, s14, 0x80080
	v_lshl_add_u64 v[178:179], v[184:185], 0, s[84:85]
	s_addc_u32 s15, s15, 0
	s_add_i32 s24, s62, s27
	global_load_lds_dwordx4 v[178:179], off
	s_nop 0
	s_mov_b32 m0, s24
	s_nop 0
	global_load_lds_dwordx4 v156, s[14:15]
	s_nop 0
	s_add_i32 m0, s24, 0x2000
	s_nop 0
	global_load_lds_dwordx4 v160, s[14:15]
	v_lshl_add_u64 v[178:179], v[186:187], 0, s[84:85]
	s_mov_b32 m0, s45
	s_nop 0
	global_load_lds_dwordx4 v[178:179], off
	v_lshl_add_u64 v[178:179], v[216:217], 0, s[84:85]
	s_mov_b32 m0, s68
	s_nop 0
	global_load_lds_dwordx4 v[178:179], off
	s_waitcnt vmcnt(8)
	s_waitcnt lgkmcnt(0)
	s_barrier
	s_setprio 1
	s_waitcnt lgkmcnt(0)
	v_mfma_f32_16x16x32_bf16 v[62:65], v[130:133], v[174:177], v[62:65]
	v_mfma_f32_16x16x32_bf16 v[58:61], v[138:141], v[174:177], v[58:61]
	v_mfma_f32_16x16x32_bf16 v[54:57], v[130:133], v[192:195], v[54:57]
	v_mfma_f32_16x16x32_bf16 v[50:53], v[138:141], v[192:195], v[50:53]
	v_mfma_f32_16x16x32_bf16 v[46:49], v[130:133], v[200:203], v[46:49]
	v_mfma_f32_16x16x32_bf16 v[38:41], v[138:141], v[200:203], v[38:41]
	v_mfma_f32_16x16x32_bf16 v[30:33], v[130:133], v[208:211], v[30:33]
	v_mfma_f32_16x16x32_bf16 v[22:25], v[138:141], v[208:211], v[22:25]
	v_mfma_f32_16x16x32_bf16 v[62:65], v[134:137], v[188:191], v[62:65]
	v_mfma_f32_16x16x32_bf16 v[58:61], v[142:145], v[188:191], v[58:61]
	v_mfma_f32_16x16x32_bf16 v[54:57], v[134:137], v[196:199], v[54:57]
	v_mfma_f32_16x16x32_bf16 v[50:53], v[142:145], v[196:199], v[50:53]
	v_mfma_f32_16x16x32_bf16 v[46:49], v[134:137], v[204:207], v[46:49]
	v_mfma_f32_16x16x32_bf16 v[38:41], v[142:145], v[204:207], v[38:41]
	v_mfma_f32_16x16x32_bf16 v[30:33], v[134:137], v[212:215], v[30:33]
	v_mfma_f32_16x16x32_bf16 v[22:25], v[142:145], v[212:215], v[22:25]
	s_setprio 0
	s_setprio 1
	v_mfma_f32_16x16x32_bf16 v[42:45], v[146:149], v[174:177], v[42:45]
	v_mfma_f32_16x16x32_bf16 v[34:37], v[166:169], v[174:177], v[34:37]
	v_mfma_f32_16x16x32_bf16 v[26:29], v[146:149], v[192:195], v[26:29]
	v_mfma_f32_16x16x32_bf16 v[18:21], v[166:169], v[192:195], v[18:21]
	v_mfma_f32_16x16x32_bf16 v[14:17], v[146:149], v[200:203], v[14:17]
	v_mfma_f32_16x16x32_bf16 v[10:13], v[166:169], v[200:203], v[10:13]
	v_mfma_f32_16x16x32_bf16 v[6:9], v[146:149], v[208:211], v[6:9]
	v_mfma_f32_16x16x32_bf16 v[2:5], v[166:169], v[208:211], v[2:5]
	v_mfma_f32_16x16x32_bf16 v[42:45], v[150:153], v[188:191], v[42:45]
	v_mfma_f32_16x16x32_bf16 v[34:37], v[170:173], v[188:191], v[34:37]
	v_mfma_f32_16x16x32_bf16 v[26:29], v[150:153], v[196:199], v[26:29]
	v_mfma_f32_16x16x32_bf16 v[18:21], v[170:173], v[196:199], v[18:21]
	v_mfma_f32_16x16x32_bf16 v[14:17], v[150:153], v[204:207], v[14:17]
	v_mfma_f32_16x16x32_bf16 v[10:13], v[170:173], v[204:207], v[10:13]
	v_mfma_f32_16x16x32_bf16 v[6:9], v[150:153], v[212:215], v[6:9]
	v_mfma_f32_16x16x32_bf16 v[2:5], v[170:173], v[212:215], v[2:5]
	s_setprio 0
	s_barrier
	s_add_i32 s41, s41, 2
	s_add_u32 s22, s22, 0x100
	s_addc_u32 s23, s23, 0
	s_add_u32 s40, s40, 0x100
	s_addc_u32 s52, s52, 0
	s_cmp_gt_u32 s41, 29
	s_cbranch_scc0 .LBB0_2376
	v_mov_b64_e32 v[250:251], 0xff
	v_mov_b64_e32 v[252:253], 0x100
	v_mov_b32_e32 v183, 0x7f800000
	s_and_b64 vcc, exec, s[10:11]
	s_cbranch_vccz .LBB0_2379
	s_barrier
